# scan packed f32 + gemm256 k-loop reschedule (B-first reads, LDS stores inside MFMA burst) + MLA attention LDS fragment prefetch + static priority for second resident block
# speedup vs baseline: 1.1203x; 1.0368x over previous
; DI void cfence() { asm volatile("" ::: "memory"); }
; DI int swz4(int row) { const int g = (row >> 2) & 3; return ((g << 1) ^ ((g >> 1) * 3)) & 3; }
; #define LSTORE2(RA, RB, P)                                       \
;   {                                                              \
;     char* dA_ = smem + (P) * 24576 + wofs;                       \
;     _Pragma("unroll") for (int j = 0; j < 4; ++j) *(u32x4*)(dA_ + j * 4096) = RA[j]; \
;     _Pragma("unroll") for (int j = 0; j < 2; ++j) *(u32x4*)(dA_ + 16384 + j * 4096) = RB[j]; \
;   }
; DI void gemm256_kloop(f32x4 (&acc)[8][4], const bf16_t* __restrict__ A, int lda, const bf16_t* __restrict__ Bt, int ldb,
;                       int K, int b, int s0, int col0, char* smem) {
;     ...
;   GLOAD2(xa, xb, 0);
;   GLOAD2(ya, yb, 1);
;   cfence();
;   LSTORE2(xa, xb, 0);
;   __syncthreads();
;   const int co = ((fq ^ swz4(fr)) << 4);
;   const int aofs = (wr * 128 + fr) * 64 + co, bofs = (wc * 64 + fr) * 64 + co;
;   for (int kt = 0; kt < nk; kt += 2) {
;     GLOAD2(xa, xb, kt + 2);
;     cfence();
;     COMPUTE2(0);
;     LSTORE2(ya, yb, 1);
;     __syncthreads();
;     if (kt + 1 < nk) {
;       GLOAD2(ya, yb, kt + 3);
;       cfence();
;       COMPUTE2(1);
;       LSTORE2(xa, xb, 0);
;       __syncthreads();
.LBB0_37:
	s_add_i32 s12, s11, 2
	s_cmpk_lt_u32 s11, 0xae
	s_cselect_b64 s[18:19], -1, 0
	s_and_b64 vcc, s[18:19], exec
	s_cselect_b32 s13, s10, 0x2bc0
	buffer_load_dwordx4 v[162:165], v0, s[20:23], s13 offen
	buffer_load_dwordx4 v[166:169], v154, s[20:23], s13 offen
	buffer_load_dwordx4 v[170:173], v155, s[20:23], s13 offen
	buffer_load_dwordx4 v[174:177], v156, s[20:23], s13 offen
	buffer_load_dwordx4 v[178:181], v157, s[4:7], s13 offen
	buffer_load_dwordx4 v[182:185], v158, s[4:7], s13 offen
	ds_read_b128 v[236:239], v160 offset:16384
	ds_read_b128 v[240:243], v160 offset:17408
	ds_read_b128 v[244:247], v160 offset:18432
	ds_read_b128 v[248:251], v160 offset:19456
	ds_read_b128 v[186:189], v161
	ds_read_b128 v[190:193], v161 offset:1024
	ds_read_b128 v[212:215], v161 offset:2048
	ds_read_b128 v[216:219], v161 offset:3072
	ds_read_b128 v[220:223], v161 offset:4096
	ds_read_b128 v[224:227], v161 offset:5120
	ds_read_b128 v[228:231], v161 offset:6144
	ds_read_b128 v[232:235], v161 offset:7168
	s_setprio 1
	s_waitcnt lgkmcnt(7)
	v_mfma_f32_16x16x32_bf16 v[126:129], v[186:189], v[236:239], v[126:129]
	v_mfma_f32_16x16x32_bf16 v[122:125], v[186:189], v[240:243], v[122:125]
	v_mfma_f32_16x16x32_bf16 v[118:121], v[186:189], v[244:247], v[118:121]
	v_mfma_f32_16x16x32_bf16 v[114:117], v[186:189], v[248:251], v[114:117]
	s_waitcnt lgkmcnt(6)
	v_mfma_f32_16x16x32_bf16 v[110:113], v[190:193], v[236:239], v[110:113]
	v_mfma_f32_16x16x32_bf16 v[106:109], v[190:193], v[240:243], v[106:109]
	v_mfma_f32_16x16x32_bf16 v[102:105], v[190:193], v[244:247], v[102:105]
	v_mfma_f32_16x16x32_bf16 v[98:101], v[190:193], v[248:251], v[98:101]
	s_waitcnt lgkmcnt(5)
	v_mfma_f32_16x16x32_bf16 v[94:97], v[212:215], v[236:239], v[94:97]
	v_mfma_f32_16x16x32_bf16 v[90:93], v[212:215], v[240:243], v[90:93]
	v_mfma_f32_16x16x32_bf16 v[86:89], v[212:215], v[244:247], v[86:89]
	v_mfma_f32_16x16x32_bf16 v[82:85], v[212:215], v[248:251], v[82:85]
	s_waitcnt lgkmcnt(4)
	v_mfma_f32_16x16x32_bf16 v[78:81], v[216:219], v[236:239], v[78:81]
	v_mfma_f32_16x16x32_bf16 v[74:77], v[216:219], v[240:243], v[74:77]
	v_mfma_f32_16x16x32_bf16 v[70:73], v[216:219], v[244:247], v[70:73]
	v_mfma_f32_16x16x32_bf16 v[66:69], v[216:219], v[248:251], v[66:69]
	s_waitcnt lgkmcnt(3)
	v_mfma_f32_16x16x32_bf16 v[62:65], v[220:223], v[236:239], v[62:65]
	v_mfma_f32_16x16x32_bf16 v[58:61], v[220:223], v[240:243], v[58:61]
	s_waitcnt vmcnt(10)
	ds_write_b128 v159, v[134:137] offset:24576
	v_mfma_f32_16x16x32_bf16 v[54:57], v[220:223], v[244:247], v[54:57]
	v_mfma_f32_16x16x32_bf16 v[50:53], v[220:223], v[248:251], v[50:53]
	s_waitcnt vmcnt(8)
	ds_write_b128 v159, v[142:145] offset:28672
	s_waitcnt lgkmcnt(4)
	v_mfma_f32_16x16x32_bf16 v[46:49], v[224:227], v[236:239], v[46:49]
	v_mfma_f32_16x16x32_bf16 v[42:45], v[224:227], v[240:243], v[42:45]
	s_waitcnt vmcnt(7)
	ds_write_b128 v159, v[146:149] offset:32768
	v_mfma_f32_16x16x32_bf16 v[38:41], v[224:227], v[244:247], v[38:41]
	v_mfma_f32_16x16x32_bf16 v[34:37], v[224:227], v[248:251], v[34:37]
	s_waitcnt vmcnt(6)
	ds_write_b128 v159, v[150:153] offset:36864
	s_waitcnt lgkmcnt(5)
	v_mfma_f32_16x16x32_bf16 v[30:33], v[228:231], v[236:239], v[30:33]
	v_mfma_f32_16x16x32_bf16 v[26:29], v[228:231], v[240:243], v[26:29]
	ds_write_b128 v159, v[130:133] offset:40960
	v_mfma_f32_16x16x32_bf16 v[22:25], v[228:231], v[244:247], v[22:25]
	v_mfma_f32_16x16x32_bf16 v[18:21], v[228:231], v[248:251], v[18:21]
	ds_write_b128 v159, v[138:141] offset:45056
	s_waitcnt lgkmcnt(6)
	v_mfma_f32_16x16x32_bf16 v[14:17], v[232:235], v[236:239], v[14:17]
	v_mfma_f32_16x16x32_bf16 v[10:13], v[232:235], v[240:243], v[10:13]
	v_mfma_f32_16x16x32_bf16 v[6:9], v[232:235], v[244:247], v[6:9]
	v_mfma_f32_16x16x32_bf16 v[2:5], v[232:235], v[248:251], v[2:5]
	s_setprio 0
	s_min_u32 s11, s11, 0xac
	s_lshl_b32 s11, s11, 6
	s_addk_i32 s11, 0xc0
	s_waitcnt lgkmcnt(0)
	s_barrier
; DI void cfence() { asm volatile("" ::: "memory"); }
; DI int swz4(int row) { const int g = (row >> 2) & 3; return ((g << 1) ^ ((g >> 1) * 3)) & 3; }
; #define LSTORE2(RA, RB, P)                                       \
;   {                                                              \
;     char* dA_ = smem + (P) * 24576 + wofs;                       \
;     _Pragma("unroll") for (int j = 0; j < 4; ++j) *(u32x4*)(dA_ + j * 4096) = RA[j]; \
;     _Pragma("unroll") for (int j = 0; j < 2; ++j) *(u32x4*)(dA_ + 16384 + j * 4096) = RB[j]; \
;   }
; DI void gemm256_kloop(f32x4 (&acc)[8][4], const bf16_t* __restrict__ A, int lda, const bf16_t* __restrict__ Bt, int ldb,
;                       int K, int b, int s0, int col0, char* smem) {
;     ...
;   GLOAD2(xa, xb, 0);
;   GLOAD2(ya, yb, 1);
;   cfence();
;   LSTORE2(xa, xb, 0);
;   __syncthreads();
;   const int co = ((fq ^ swz4(fr)) << 4);
;   const int aofs = (wr * 128 + fr) * 64 + co, bofs = (wc * 64 + fr) * 64 + co;
;   for (int kt = 0; kt < nk; kt += 2) {
;     GLOAD2(xa, xb, kt + 2);
;     cfence();
;     COMPUTE2(0);
;     LSTORE2(ya, yb, 1);
;     __syncthreads();
;     if (kt + 1 < nk) {
;       GLOAD2(ya, yb, kt + 3);
;       cfence();
;       COMPUTE2(1);
;       LSTORE2(xa, xb, 0);
;       __syncthreads();
	buffer_load_dwordx4 v[134:137], v0, s[20:23], s11 offen
	buffer_load_dwordx4 v[142:145], v154, s[20:23], s11 offen
	buffer_load_dwordx4 v[146:149], v155, s[20:23], s11 offen
	buffer_load_dwordx4 v[150:153], v156, s[20:23], s11 offen
	buffer_load_dwordx4 v[130:133], v157, s[4:7], s11 offen
	buffer_load_dwordx4 v[138:141], v158, s[4:7], s11 offen
	ds_read_b128 v[236:239], v160 offset:40960
	ds_read_b128 v[240:243], v160 offset:41984
	ds_read_b128 v[244:247], v160 offset:43008
	ds_read_b128 v[248:251], v160 offset:44032
	ds_read_b128 v[186:189], v161 offset:24576
	ds_read_b128 v[190:193], v161 offset:25600
	ds_read_b128 v[212:215], v161 offset:26624
	ds_read_b128 v[216:219], v161 offset:27648
	ds_read_b128 v[220:223], v161 offset:28672
	ds_read_b128 v[224:227], v161 offset:29696
	ds_read_b128 v[228:231], v161 offset:30720
	ds_read_b128 v[232:235], v161 offset:31744
	s_setprio 1
	s_waitcnt lgkmcnt(7)
	v_mfma_f32_16x16x32_bf16 v[126:129], v[186:189], v[236:239], v[126:129]
	v_mfma_f32_16x16x32_bf16 v[122:125], v[186:189], v[240:243], v[122:125]
	v_mfma_f32_16x16x32_bf16 v[118:121], v[186:189], v[244:247], v[118:121]
	v_mfma_f32_16x16x32_bf16 v[114:117], v[186:189], v[248:251], v[114:117]
	s_waitcnt lgkmcnt(6)
	v_mfma_f32_16x16x32_bf16 v[110:113], v[190:193], v[236:239], v[110:113]
	v_mfma_f32_16x16x32_bf16 v[106:109], v[190:193], v[240:243], v[106:109]
	v_mfma_f32_16x16x32_bf16 v[102:105], v[190:193], v[244:247], v[102:105]
	v_mfma_f32_16x16x32_bf16 v[98:101], v[190:193], v[248:251], v[98:101]
	s_waitcnt lgkmcnt(5)
	v_mfma_f32_16x16x32_bf16 v[94:97], v[212:215], v[236:239], v[94:97]
	v_mfma_f32_16x16x32_bf16 v[90:93], v[212:215], v[240:243], v[90:93]
	v_mfma_f32_16x16x32_bf16 v[86:89], v[212:215], v[244:247], v[86:89]
	v_mfma_f32_16x16x32_bf16 v[82:85], v[212:215], v[248:251], v[82:85]
	s_waitcnt lgkmcnt(4)
	v_mfma_f32_16x16x32_bf16 v[78:81], v[216:219], v[236:239], v[78:81]
	v_mfma_f32_16x16x32_bf16 v[74:77], v[216:219], v[240:243], v[74:77]
	v_mfma_f32_16x16x32_bf16 v[70:73], v[216:219], v[244:247], v[70:73]
	v_mfma_f32_16x16x32_bf16 v[66:69], v[216:219], v[248:251], v[66:69]
	s_waitcnt lgkmcnt(3)
	v_mfma_f32_16x16x32_bf16 v[62:65], v[220:223], v[236:239], v[62:65]
	v_mfma_f32_16x16x32_bf16 v[58:61], v[220:223], v[240:243], v[58:61]
	s_waitcnt vmcnt(11)
	ds_write_b128 v159, v[162:165]
	v_mfma_f32_16x16x32_bf16 v[54:57], v[220:223], v[244:247], v[54:57]
	v_mfma_f32_16x16x32_bf16 v[50:53], v[220:223], v[248:251], v[50:53]
	s_waitcnt vmcnt(10)
	ds_write_b128 v159, v[166:169] offset:4096
	s_waitcnt lgkmcnt(4)
	v_mfma_f32_16x16x32_bf16 v[46:49], v[224:227], v[236:239], v[46:49]
	v_mfma_f32_16x16x32_bf16 v[42:45], v[224:227], v[240:243], v[42:45]
	s_waitcnt vmcnt(9)
	ds_write_b128 v159, v[170:173] offset:8192
	v_mfma_f32_16x16x32_bf16 v[38:41], v[224:227], v[244:247], v[38:41]
	v_mfma_f32_16x16x32_bf16 v[34:37], v[224:227], v[248:251], v[34:37]
	s_waitcnt vmcnt(8)
	ds_write_b128 v159, v[174:177] offset:12288
	s_waitcnt lgkmcnt(5)
	v_mfma_f32_16x16x32_bf16 v[30:33], v[228:231], v[236:239], v[30:33]
	v_mfma_f32_16x16x32_bf16 v[26:29], v[228:231], v[240:243], v[26:29]
	s_waitcnt vmcnt(7)
	ds_write_b128 v159, v[178:181] offset:16384
	v_mfma_f32_16x16x32_bf16 v[22:25], v[228:231], v[244:247], v[22:25]
	v_mfma_f32_16x16x32_bf16 v[18:21], v[228:231], v[248:251], v[18:21]
	s_waitcnt vmcnt(6)
	ds_write_b128 v159, v[182:185] offset:20480
	s_waitcnt lgkmcnt(6)
	v_mfma_f32_16x16x32_bf16 v[14:17], v[232:235], v[236:239], v[14:17]
	v_mfma_f32_16x16x32_bf16 v[10:13], v[232:235], v[240:243], v[10:13]
	v_mfma_f32_16x16x32_bf16 v[6:9], v[232:235], v[244:247], v[6:9]
	v_mfma_f32_16x16x32_bf16 v[2:5], v[232:235], v[248:251], v[2:5]
	s_setprio 0
	s_addk_i32 s10, 0x80
	s_mov_b32 s11, s12
	s_waitcnt lgkmcnt(0)
	s_barrier
	s_cbranch_vccnz .LBB0_37
	s_lshl_b32 s17, s8, 8
	s_sub_i32 s18, s17, s9
	s_mov_b32 s10, 0
	s_mov_b64 s[6:7], -1
	s_branch .LBB0_40

; DI void cfence() { asm volatile("" ::: "memory"); }
; DI int swz4(int row) { const int g = (row >> 2) & 3; return ((g << 1) ^ ((g >> 1) * 3)) & 3; }
; #define LSTORE2(RA, RB, P)                                       \
;   {                                                              \
;     char* dA_ = smem + (P) * 24576 + wofs;                       \
;     _Pragma("unroll") for (int j = 0; j < 4; ++j) *(u32x4*)(dA_ + j * 4096) = RA[j]; \
;     _Pragma("unroll") for (int j = 0; j < 2; ++j) *(u32x4*)(dA_ + 16384 + j * 4096) = RB[j]; \
;   }
; DI void gemm256_kloop(f32x4 (&acc)[8][4], const bf16_t* __restrict__ A, int lda, const bf16_t* __restrict__ Bt, int ldb,
;                       int K, int b, int s0, int col0, char* smem) {
;     ...
;   GLOAD2(xa, xb, 0);
;   GLOAD2(ya, yb, 1);
;   cfence();
;   LSTORE2(xa, xb, 0);
;   __syncthreads();
;   const int co = ((fq ^ swz4(fr)) << 4);
;   const int aofs = (wr * 128 + fr) * 64 + co, bofs = (wc * 64 + fr) * 64 + co;
;   for (int kt = 0; kt < nk; kt += 2) {
;     GLOAD2(xa, xb, kt + 2);
;     cfence();
;     COMPUTE2(0);
;     LSTORE2(ya, yb, 1);
;     __syncthreads();
;     if (kt + 1 < nk) {
;       GLOAD2(ya, yb, kt + 3);
;       cfence();
;       COMPUTE2(1);
;       LSTORE2(xa, xb, 0);
;       __syncthreads();
.LBB0_59:
	s_add_i32 s12, s11, 2
	s_cmpk_lt_u32 s11, 0xae
	s_cselect_b64 s[16:17], -1, 0
	s_and_b64 vcc, s[16:17], exec
	s_cselect_b32 s13, s10, 0x2bc0
	buffer_load_dwordx4 v[162:165], v0, s[20:23], s13 offen
	buffer_load_dwordx4 v[166:169], v154, s[20:23], s13 offen
	buffer_load_dwordx4 v[170:173], v155, s[20:23], s13 offen
	buffer_load_dwordx4 v[174:177], v156, s[20:23], s13 offen
	buffer_load_dwordx4 v[178:181], v157, s[4:7], s13 offen
	buffer_load_dwordx4 v[182:185], v158, s[4:7], s13 offen
	ds_read_b128 v[236:239], v160 offset:16384
	ds_read_b128 v[240:243], v160 offset:17408
	ds_read_b128 v[244:247], v160 offset:18432
	ds_read_b128 v[248:251], v160 offset:19456
	ds_read_b128 v[186:189], v161
	ds_read_b128 v[190:193], v161 offset:1024
	ds_read_b128 v[212:215], v161 offset:2048
	ds_read_b128 v[216:219], v161 offset:3072
	ds_read_b128 v[220:223], v161 offset:4096
	ds_read_b128 v[224:227], v161 offset:5120
	ds_read_b128 v[228:231], v161 offset:6144
	ds_read_b128 v[232:235], v161 offset:7168
	s_setprio 1
	s_waitcnt lgkmcnt(7)
	v_mfma_f32_16x16x32_bf16 v[126:129], v[186:189], v[236:239], v[126:129]
	v_mfma_f32_16x16x32_bf16 v[122:125], v[186:189], v[240:243], v[122:125]
	v_mfma_f32_16x16x32_bf16 v[118:121], v[186:189], v[244:247], v[118:121]
	v_mfma_f32_16x16x32_bf16 v[114:117], v[186:189], v[248:251], v[114:117]
	s_waitcnt lgkmcnt(6)
	v_mfma_f32_16x16x32_bf16 v[110:113], v[190:193], v[236:239], v[110:113]
	v_mfma_f32_16x16x32_bf16 v[106:109], v[190:193], v[240:243], v[106:109]
	v_mfma_f32_16x16x32_bf16 v[102:105], v[190:193], v[244:247], v[102:105]
	v_mfma_f32_16x16x32_bf16 v[98:101], v[190:193], v[248:251], v[98:101]
	s_waitcnt lgkmcnt(5)
	v_mfma_f32_16x16x32_bf16 v[94:97], v[212:215], v[236:239], v[94:97]
	v_mfma_f32_16x16x32_bf16 v[90:93], v[212:215], v[240:243], v[90:93]
	v_mfma_f32_16x16x32_bf16 v[86:89], v[212:215], v[244:247], v[86:89]
	v_mfma_f32_16x16x32_bf16 v[82:85], v[212:215], v[248:251], v[82:85]
	s_waitcnt lgkmcnt(4)
	v_mfma_f32_16x16x32_bf16 v[78:81], v[216:219], v[236:239], v[78:81]
	v_mfma_f32_16x16x32_bf16 v[74:77], v[216:219], v[240:243], v[74:77]
	v_mfma_f32_16x16x32_bf16 v[70:73], v[216:219], v[244:247], v[70:73]
	v_mfma_f32_16x16x32_bf16 v[66:69], v[216:219], v[248:251], v[66:69]
	s_waitcnt lgkmcnt(3)
	v_mfma_f32_16x16x32_bf16 v[62:65], v[220:223], v[236:239], v[62:65]
	v_mfma_f32_16x16x32_bf16 v[58:61], v[220:223], v[240:243], v[58:61]
	s_waitcnt vmcnt(10)
	ds_write_b128 v159, v[134:137] offset:24576
	v_mfma_f32_16x16x32_bf16 v[54:57], v[220:223], v[244:247], v[54:57]
	v_mfma_f32_16x16x32_bf16 v[50:53], v[220:223], v[248:251], v[50:53]
	s_waitcnt vmcnt(8)
	ds_write_b128 v159, v[142:145] offset:28672
	s_waitcnt lgkmcnt(4)
	v_mfma_f32_16x16x32_bf16 v[46:49], v[224:227], v[236:239], v[46:49]
	v_mfma_f32_16x16x32_bf16 v[42:45], v[224:227], v[240:243], v[42:45]
	s_waitcnt vmcnt(7)
	ds_write_b128 v159, v[146:149] offset:32768
	v_mfma_f32_16x16x32_bf16 v[38:41], v[224:227], v[244:247], v[38:41]
	v_mfma_f32_16x16x32_bf16 v[34:37], v[224:227], v[248:251], v[34:37]
	s_waitcnt vmcnt(6)
	ds_write_b128 v159, v[150:153] offset:36864
	s_waitcnt lgkmcnt(5)
	v_mfma_f32_16x16x32_bf16 v[30:33], v[228:231], v[236:239], v[30:33]
	v_mfma_f32_16x16x32_bf16 v[26:29], v[228:231], v[240:243], v[26:29]
	ds_write_b128 v159, v[130:133] offset:40960
	v_mfma_f32_16x16x32_bf16 v[22:25], v[228:231], v[244:247], v[22:25]
	v_mfma_f32_16x16x32_bf16 v[18:21], v[228:231], v[248:251], v[18:21]
	ds_write_b128 v159, v[138:141] offset:45056
	s_waitcnt lgkmcnt(6)
	v_mfma_f32_16x16x32_bf16 v[14:17], v[232:235], v[236:239], v[14:17]
	v_mfma_f32_16x16x32_bf16 v[10:13], v[232:235], v[240:243], v[10:13]
	v_mfma_f32_16x16x32_bf16 v[6:9], v[232:235], v[244:247], v[6:9]
	v_mfma_f32_16x16x32_bf16 v[2:5], v[232:235], v[248:251], v[2:5]
	s_setprio 0
	s_min_u32 s11, s11, 0xac
	s_lshl_b32 s11, s11, 6
	s_addk_i32 s11, 0xc0
	s_waitcnt lgkmcnt(0)
	s_barrier
; DI void cfence() { asm volatile("" ::: "memory"); }
; DI int swz4(int row) { const int g = (row >> 2) & 3; return ((g << 1) ^ ((g >> 1) * 3)) & 3; }
; #define LSTORE2(RA, RB, P)                                       \
;   {                                                              \
;     char* dA_ = smem + (P) * 24576 + wofs;                       \
;     _Pragma("unroll") for (int j = 0; j < 4; ++j) *(u32x4*)(dA_ + j * 4096) = RA[j]; \
;     _Pragma("unroll") for (int j = 0; j < 2; ++j) *(u32x4*)(dA_ + 16384 + j * 4096) = RB[j]; \
;   }
; DI void gemm256_kloop(f32x4 (&acc)[8][4], const bf16_t* __restrict__ A, int lda, const bf16_t* __restrict__ Bt, int ldb,
;                       int K, int b, int s0, int col0, char* smem) {
;     ...
;   GLOAD2(xa, xb, 0);
;   GLOAD2(ya, yb, 1);
;   cfence();
;   LSTORE2(xa, xb, 0);
;   __syncthreads();
;   const int co = ((fq ^ swz4(fr)) << 4);
;   const int aofs = (wr * 128 + fr) * 64 + co, bofs = (wc * 64 + fr) * 64 + co;
;   for (int kt = 0; kt < nk; kt += 2) {
;     GLOAD2(xa, xb, kt + 2);
;     cfence();
;     COMPUTE2(0);
;     LSTORE2(ya, yb, 1);
;     __syncthreads();
;     if (kt + 1 < nk) {
;       GLOAD2(ya, yb, kt + 3);
;       cfence();
;       COMPUTE2(1);
;       LSTORE2(xa, xb, 0);
;       __syncthreads();
	buffer_load_dwordx4 v[134:137], v0, s[20:23], s11 offen
	buffer_load_dwordx4 v[142:145], v154, s[20:23], s11 offen
	buffer_load_dwordx4 v[146:149], v155, s[20:23], s11 offen
	buffer_load_dwordx4 v[150:153], v156, s[20:23], s11 offen
	buffer_load_dwordx4 v[130:133], v157, s[4:7], s11 offen
	buffer_load_dwordx4 v[138:141], v158, s[4:7], s11 offen
	ds_read_b128 v[236:239], v160 offset:40960
	ds_read_b128 v[240:243], v160 offset:41984
	ds_read_b128 v[244:247], v160 offset:43008
	ds_read_b128 v[248:251], v160 offset:44032
	ds_read_b128 v[186:189], v161 offset:24576
	ds_read_b128 v[190:193], v161 offset:25600
	ds_read_b128 v[212:215], v161 offset:26624
	ds_read_b128 v[216:219], v161 offset:27648
	ds_read_b128 v[220:223], v161 offset:28672
	ds_read_b128 v[224:227], v161 offset:29696
	ds_read_b128 v[228:231], v161 offset:30720
	ds_read_b128 v[232:235], v161 offset:31744
	s_setprio 1
	s_waitcnt lgkmcnt(7)
	v_mfma_f32_16x16x32_bf16 v[126:129], v[186:189], v[236:239], v[126:129]
	v_mfma_f32_16x16x32_bf16 v[122:125], v[186:189], v[240:243], v[122:125]
	v_mfma_f32_16x16x32_bf16 v[118:121], v[186:189], v[244:247], v[118:121]
	v_mfma_f32_16x16x32_bf16 v[114:117], v[186:189], v[248:251], v[114:117]
	s_waitcnt lgkmcnt(6)
	v_mfma_f32_16x16x32_bf16 v[110:113], v[190:193], v[236:239], v[110:113]
	v_mfma_f32_16x16x32_bf16 v[106:109], v[190:193], v[240:243], v[106:109]
	v_mfma_f32_16x16x32_bf16 v[102:105], v[190:193], v[244:247], v[102:105]
	v_mfma_f32_16x16x32_bf16 v[98:101], v[190:193], v[248:251], v[98:101]
	s_waitcnt lgkmcnt(5)
	v_mfma_f32_16x16x32_bf16 v[94:97], v[212:215], v[236:239], v[94:97]
	v_mfma_f32_16x16x32_bf16 v[90:93], v[212:215], v[240:243], v[90:93]
	v_mfma_f32_16x16x32_bf16 v[86:89], v[212:215], v[244:247], v[86:89]
	v_mfma_f32_16x16x32_bf16 v[82:85], v[212:215], v[248:251], v[82:85]
	s_waitcnt lgkmcnt(4)
	v_mfma_f32_16x16x32_bf16 v[78:81], v[216:219], v[236:239], v[78:81]
	v_mfma_f32_16x16x32_bf16 v[74:77], v[216:219], v[240:243], v[74:77]
	v_mfma_f32_16x16x32_bf16 v[70:73], v[216:219], v[244:247], v[70:73]
	v_mfma_f32_16x16x32_bf16 v[66:69], v[216:219], v[248:251], v[66:69]
	s_waitcnt lgkmcnt(3)
	v_mfma_f32_16x16x32_bf16 v[62:65], v[220:223], v[236:239], v[62:65]
	v_mfma_f32_16x16x32_bf16 v[58:61], v[220:223], v[240:243], v[58:61]
	s_waitcnt vmcnt(11)
	ds_write_b128 v159, v[162:165]
	v_mfma_f32_16x16x32_bf16 v[54:57], v[220:223], v[244:247], v[54:57]
	v_mfma_f32_16x16x32_bf16 v[50:53], v[220:223], v[248:251], v[50:53]
	s_waitcnt vmcnt(10)
	ds_write_b128 v159, v[166:169] offset:4096
	s_waitcnt lgkmcnt(4)
	v_mfma_f32_16x16x32_bf16 v[46:49], v[224:227], v[236:239], v[46:49]
	v_mfma_f32_16x16x32_bf16 v[42:45], v[224:227], v[240:243], v[42:45]
	s_waitcnt vmcnt(9)
	ds_write_b128 v159, v[170:173] offset:8192
	v_mfma_f32_16x16x32_bf16 v[38:41], v[224:227], v[244:247], v[38:41]
	v_mfma_f32_16x16x32_bf16 v[34:37], v[224:227], v[248:251], v[34:37]
	s_waitcnt vmcnt(8)
	ds_write_b128 v159, v[174:177] offset:12288
	s_waitcnt lgkmcnt(5)
	v_mfma_f32_16x16x32_bf16 v[30:33], v[228:231], v[236:239], v[30:33]
	v_mfma_f32_16x16x32_bf16 v[26:29], v[228:231], v[240:243], v[26:29]
	s_waitcnt vmcnt(7)
	ds_write_b128 v159, v[178:181] offset:16384
	v_mfma_f32_16x16x32_bf16 v[22:25], v[228:231], v[244:247], v[22:25]
	v_mfma_f32_16x16x32_bf16 v[18:21], v[228:231], v[248:251], v[18:21]
	s_waitcnt vmcnt(6)
	ds_write_b128 v159, v[182:185] offset:20480
	s_waitcnt lgkmcnt(6)
	v_mfma_f32_16x16x32_bf16 v[14:17], v[232:235], v[236:239], v[14:17]
	v_mfma_f32_16x16x32_bf16 v[10:13], v[232:235], v[240:243], v[10:13]
	v_mfma_f32_16x16x32_bf16 v[6:9], v[232:235], v[244:247], v[6:9]
	v_mfma_f32_16x16x32_bf16 v[2:5], v[232:235], v[248:251], v[2:5]
	s_setprio 0
	s_addk_i32 s10, 0x80
	s_mov_b32 s11, s12
	s_waitcnt lgkmcnt(0)
	s_barrier
	s_cbranch_vccnz .LBB0_59
	s_lshl_b32 s16, s8, 8
	s_sub_i32 s17, s16, s9
	s_mov_b32 s10, 0
	s_mov_b64 s[6:7], -1
	s_branch .LBB0_62

; DI void cfence() { asm volatile("" ::: "memory"); }
; DI int swz4(int row) { const int g = (row >> 2) & 3; return ((g << 1) ^ ((g >> 1) * 3)) & 3; }
; #define LSTORE2(RA, RB, P)                                       \
;   {                                                              \
;     char* dA_ = smem + (P) * 24576 + wofs;                       \
;     _Pragma("unroll") for (int j = 0; j < 4; ++j) *(u32x4*)(dA_ + j * 4096) = RA[j]; \
;     _Pragma("unroll") for (int j = 0; j < 2; ++j) *(u32x4*)(dA_ + 16384 + j * 4096) = RB[j]; \
;   }
; DI void gemm256_kloop(f32x4 (&acc)[8][4], const bf16_t* __restrict__ A, int lda, const bf16_t* __restrict__ Bt, int ldb,
;                       int K, int b, int s0, int col0, char* smem) {
;     ...
;   GLOAD2(xa, xb, 0);
;   GLOAD2(ya, yb, 1);
;   cfence();
;   LSTORE2(xa, xb, 0);
;   __syncthreads();
;   const int co = ((fq ^ swz4(fr)) << 4);
;   const int aofs = (wr * 128 + fr) * 64 + co, bofs = (wc * 64 + fr) * 64 + co;
;   for (int kt = 0; kt < nk; kt += 2) {
;     GLOAD2(xa, xb, kt + 2);
;     cfence();
;     COMPUTE2(0);
;     LSTORE2(ya, yb, 1);
;     __syncthreads();
;     if (kt + 1 < nk) {
;       GLOAD2(ya, yb, kt + 3);
;       cfence();
;       COMPUTE2(1);
;       LSTORE2(xa, xb, 0);
;       __syncthreads();
.LBB0_81:
	s_add_i32 s9, s8, 2
	s_cmp_lt_u32 s8, 62
	s_cselect_b64 s[10:11], -1, 0
	s_and_b64 vcc, s[10:11], exec
	s_cselect_b32 s10, s7, 0xfc0
	buffer_load_dwordx4 v[162:165], v0, s[20:23], s10 offen
	buffer_load_dwordx4 v[166:169], v154, s[20:23], s10 offen
	buffer_load_dwordx4 v[170:173], v155, s[20:23], s10 offen
	buffer_load_dwordx4 v[174:177], v156, s[20:23], s10 offen
	buffer_load_dwordx4 v[178:181], v157, s[12:15], s10 offen
	buffer_load_dwordx4 v[182:185], v158, s[12:15], s10 offen
	ds_read_b128 v[236:239], v160 offset:16384
	ds_read_b128 v[240:243], v160 offset:17408
	ds_read_b128 v[244:247], v160 offset:18432
	ds_read_b128 v[248:251], v160 offset:19456
	ds_read_b128 v[186:189], v161
	ds_read_b128 v[190:193], v161 offset:1024
	ds_read_b128 v[212:215], v161 offset:2048
	ds_read_b128 v[216:219], v161 offset:3072
	ds_read_b128 v[220:223], v161 offset:4096
	ds_read_b128 v[224:227], v161 offset:5120
	ds_read_b128 v[228:231], v161 offset:6144
	ds_read_b128 v[232:235], v161 offset:7168
	s_setprio 1
	s_waitcnt lgkmcnt(7)
	v_mfma_f32_16x16x32_bf16 v[126:129], v[186:189], v[236:239], v[126:129]
	v_mfma_f32_16x16x32_bf16 v[122:125], v[186:189], v[240:243], v[122:125]
	v_mfma_f32_16x16x32_bf16 v[118:121], v[186:189], v[244:247], v[118:121]
	v_mfma_f32_16x16x32_bf16 v[114:117], v[186:189], v[248:251], v[114:117]
	s_waitcnt lgkmcnt(6)
	v_mfma_f32_16x16x32_bf16 v[110:113], v[190:193], v[236:239], v[110:113]
	v_mfma_f32_16x16x32_bf16 v[106:109], v[190:193], v[240:243], v[106:109]
	v_mfma_f32_16x16x32_bf16 v[102:105], v[190:193], v[244:247], v[102:105]
	v_mfma_f32_16x16x32_bf16 v[98:101], v[190:193], v[248:251], v[98:101]
	s_waitcnt lgkmcnt(5)
	v_mfma_f32_16x16x32_bf16 v[94:97], v[212:215], v[236:239], v[94:97]
	v_mfma_f32_16x16x32_bf16 v[90:93], v[212:215], v[240:243], v[90:93]
	v_mfma_f32_16x16x32_bf16 v[86:89], v[212:215], v[244:247], v[86:89]
	v_mfma_f32_16x16x32_bf16 v[82:85], v[212:215], v[248:251], v[82:85]
	s_waitcnt lgkmcnt(4)
	v_mfma_f32_16x16x32_bf16 v[78:81], v[216:219], v[236:239], v[78:81]
	v_mfma_f32_16x16x32_bf16 v[74:77], v[216:219], v[240:243], v[74:77]
	v_mfma_f32_16x16x32_bf16 v[70:73], v[216:219], v[244:247], v[70:73]
	v_mfma_f32_16x16x32_bf16 v[66:69], v[216:219], v[248:251], v[66:69]
	s_waitcnt lgkmcnt(3)
	v_mfma_f32_16x16x32_bf16 v[62:65], v[220:223], v[236:239], v[62:65]
	v_mfma_f32_16x16x32_bf16 v[58:61], v[220:223], v[240:243], v[58:61]
	s_waitcnt vmcnt(9)
	ds_write_b128 v159, v[138:141] offset:24576
	v_mfma_f32_16x16x32_bf16 v[54:57], v[220:223], v[244:247], v[54:57]
	v_mfma_f32_16x16x32_bf16 v[50:53], v[220:223], v[248:251], v[50:53]
	s_waitcnt vmcnt(8)
	ds_write_b128 v159, v[142:145] offset:28672
	s_waitcnt lgkmcnt(4)
	v_mfma_f32_16x16x32_bf16 v[46:49], v[224:227], v[236:239], v[46:49]
	v_mfma_f32_16x16x32_bf16 v[42:45], v[224:227], v[240:243], v[42:45]
	s_waitcnt vmcnt(7)
	ds_write_b128 v159, v[146:149] offset:32768
	v_mfma_f32_16x16x32_bf16 v[38:41], v[224:227], v[244:247], v[38:41]
	v_mfma_f32_16x16x32_bf16 v[34:37], v[224:227], v[248:251], v[34:37]
	s_waitcnt vmcnt(6)
	ds_write_b128 v159, v[150:153] offset:36864
	s_waitcnt lgkmcnt(5)
	v_mfma_f32_16x16x32_bf16 v[30:33], v[228:231], v[236:239], v[30:33]
	v_mfma_f32_16x16x32_bf16 v[26:29], v[228:231], v[240:243], v[26:29]
	ds_write_b128 v159, v[130:133] offset:40960
	v_mfma_f32_16x16x32_bf16 v[22:25], v[228:231], v[244:247], v[22:25]
	v_mfma_f32_16x16x32_bf16 v[18:21], v[228:231], v[248:251], v[18:21]
	ds_write_b128 v159, v[134:137] offset:45056
	s_waitcnt lgkmcnt(6)
	v_mfma_f32_16x16x32_bf16 v[14:17], v[232:235], v[236:239], v[14:17]
	v_mfma_f32_16x16x32_bf16 v[10:13], v[232:235], v[240:243], v[10:13]
	v_mfma_f32_16x16x32_bf16 v[6:9], v[232:235], v[244:247], v[6:9]
	v_mfma_f32_16x16x32_bf16 v[2:5], v[232:235], v[248:251], v[2:5]
	s_setprio 0
	s_min_u32 s8, s8, 60
	s_lshl_b32 s8, s8, 6
	s_addk_i32 s8, 0xc0
	s_waitcnt lgkmcnt(0)
	s_barrier
; DI int bidx() { int t = __builtin_amdgcn_workgroup_id_x(); asm volatile("" : "+s"(t)); return t; }
; DI int gdim() { int t = (int)__ockl_get_num_groups(0); asm volatile("" : "+s"(t)); return t; }
; DI void cfence() { asm volatile("" ::: "memory"); }
; DI int swz4(int row) { const int g = (row >> 2) & 3; return ((g << 1) ^ ((g >> 1) * 3)) & 3; }
; #define LSTORE2(RA, RB, P)                                       \
;   {                                                              \
;     char* dA_ = smem + (P) * 24576 + wofs;                       \
;     _Pragma("unroll") for (int j = 0; j < 4; ++j) *(u32x4*)(dA_ + j * 4096) = RA[j]; \
;     _Pragma("unroll") for (int j = 0; j < 2; ++j) *(u32x4*)(dA_ + 16384 + j * 4096) = RB[j]; \
;   }
; DI void gemm256_kloop(f32x4 (&acc)[8][4], const bf16_t* __restrict__ A, int lda, const bf16_t* __restrict__ Bt, int ldb,
;                       int K, int b, int s0, int col0, char* smem) {
;     ...
;   GLOAD2(xa, xb, 0);
;   GLOAD2(ya, yb, 1);
;   cfence();
;   LSTORE2(xa, xb, 0);
;   __syncthreads();
;   const int co = ((fq ^ swz4(fr)) << 4);
;   const int aofs = (wr * 128 + fr) * 64 + co, bofs = (wc * 64 + fr) * 64 + co;
;   for (int kt = 0; kt < nk; kt += 2) {
;     GLOAD2(xa, xb, kt + 2);
;     cfence();
;     COMPUTE2(0);
;     LSTORE2(ya, yb, 1);
;     __syncthreads();
;     if (kt + 1 < nk) {
;       GLOAD2(ya, yb, kt + 3);
;       cfence();
;       COMPUTE2(1);
;       LSTORE2(xa, xb, 0);
;       __syncthreads();
; template <class Epi>
; DI void gemm256_phase_overlap(const bf16_t* A, int lda, const bf16_t* Bt, int ldb, int K, int ntn, char* smem, const Epi& epi) {
;   const int total = 134 * ntn;
;   for (int it = bidx(); it < total; it += gdim()) {
;     int mt = it / ntn, nt = it - mt * ntn;
;     int b = mt / 67, s0 = (mt - b * 67) * 252 - 1;
;     gemm256_tile(A, lda, Bt, ldb, K, b, s0, nt * 128, smem, epi, 126);
	buffer_load_dwordx4 v[138:141], v0, s[20:23], s8 offen
	buffer_load_dwordx4 v[142:145], v154, s[20:23], s8 offen
	buffer_load_dwordx4 v[146:149], v155, s[20:23], s8 offen
	buffer_load_dwordx4 v[150:153], v156, s[20:23], s8 offen
	buffer_load_dwordx4 v[130:133], v157, s[12:15], s8 offen
	buffer_load_dwordx4 v[134:137], v158, s[12:15], s8 offen
	ds_read_b128 v[236:239], v160 offset:40960
	ds_read_b128 v[240:243], v160 offset:41984
	ds_read_b128 v[244:247], v160 offset:43008
	ds_read_b128 v[248:251], v160 offset:44032
	ds_read_b128 v[186:189], v161 offset:24576
	ds_read_b128 v[190:193], v161 offset:25600
	ds_read_b128 v[212:215], v161 offset:26624
	ds_read_b128 v[216:219], v161 offset:27648
	ds_read_b128 v[220:223], v161 offset:28672
	ds_read_b128 v[224:227], v161 offset:29696
	ds_read_b128 v[228:231], v161 offset:30720
	ds_read_b128 v[232:235], v161 offset:31744
	s_setprio 1
	s_waitcnt lgkmcnt(7)
	v_mfma_f32_16x16x32_bf16 v[126:129], v[186:189], v[236:239], v[126:129]
	v_mfma_f32_16x16x32_bf16 v[122:125], v[186:189], v[240:243], v[122:125]
	v_mfma_f32_16x16x32_bf16 v[118:121], v[186:189], v[244:247], v[118:121]
	v_mfma_f32_16x16x32_bf16 v[114:117], v[186:189], v[248:251], v[114:117]
	s_waitcnt lgkmcnt(6)
	v_mfma_f32_16x16x32_bf16 v[110:113], v[190:193], v[236:239], v[110:113]
	v_mfma_f32_16x16x32_bf16 v[106:109], v[190:193], v[240:243], v[106:109]
	v_mfma_f32_16x16x32_bf16 v[102:105], v[190:193], v[244:247], v[102:105]
	v_mfma_f32_16x16x32_bf16 v[98:101], v[190:193], v[248:251], v[98:101]
	s_waitcnt lgkmcnt(5)
	v_mfma_f32_16x16x32_bf16 v[94:97], v[212:215], v[236:239], v[94:97]
	v_mfma_f32_16x16x32_bf16 v[90:93], v[212:215], v[240:243], v[90:93]
	v_mfma_f32_16x16x32_bf16 v[86:89], v[212:215], v[244:247], v[86:89]
	v_mfma_f32_16x16x32_bf16 v[82:85], v[212:215], v[248:251], v[82:85]
	s_waitcnt lgkmcnt(4)
	v_mfma_f32_16x16x32_bf16 v[78:81], v[216:219], v[236:239], v[78:81]
	v_mfma_f32_16x16x32_bf16 v[74:77], v[216:219], v[240:243], v[74:77]
	v_mfma_f32_16x16x32_bf16 v[70:73], v[216:219], v[244:247], v[70:73]
	v_mfma_f32_16x16x32_bf16 v[66:69], v[216:219], v[248:251], v[66:69]
	s_waitcnt lgkmcnt(3)
	v_mfma_f32_16x16x32_bf16 v[62:65], v[220:223], v[236:239], v[62:65]
	v_mfma_f32_16x16x32_bf16 v[58:61], v[220:223], v[240:243], v[58:61]
	s_waitcnt vmcnt(11)
	ds_write_b128 v159, v[162:165]
	v_mfma_f32_16x16x32_bf16 v[54:57], v[220:223], v[244:247], v[54:57]
	v_mfma_f32_16x16x32_bf16 v[50:53], v[220:223], v[248:251], v[50:53]
	s_waitcnt vmcnt(10)
	ds_write_b128 v159, v[166:169] offset:4096
	s_waitcnt lgkmcnt(4)
	v_mfma_f32_16x16x32_bf16 v[46:49], v[224:227], v[236:239], v[46:49]
	v_mfma_f32_16x16x32_bf16 v[42:45], v[224:227], v[240:243], v[42:45]
	s_waitcnt vmcnt(9)
	ds_write_b128 v159, v[170:173] offset:8192
	v_mfma_f32_16x16x32_bf16 v[38:41], v[224:227], v[244:247], v[38:41]
	v_mfma_f32_16x16x32_bf16 v[34:37], v[224:227], v[248:251], v[34:37]
	s_waitcnt vmcnt(8)
	ds_write_b128 v159, v[174:177] offset:12288
	s_waitcnt lgkmcnt(5)
	v_mfma_f32_16x16x32_bf16 v[30:33], v[228:231], v[236:239], v[30:33]
	v_mfma_f32_16x16x32_bf16 v[26:29], v[228:231], v[240:243], v[26:29]
	s_waitcnt vmcnt(7)
	ds_write_b128 v159, v[178:181] offset:16384
	v_mfma_f32_16x16x32_bf16 v[22:25], v[228:231], v[244:247], v[22:25]
	v_mfma_f32_16x16x32_bf16 v[18:21], v[228:231], v[248:251], v[18:21]
	s_waitcnt vmcnt(6)
	ds_write_b128 v159, v[182:185] offset:20480
	s_waitcnt lgkmcnt(6)
	v_mfma_f32_16x16x32_bf16 v[14:17], v[232:235], v[236:239], v[14:17]
	v_mfma_f32_16x16x32_bf16 v[10:13], v[232:235], v[240:243], v[10:13]
	v_mfma_f32_16x16x32_bf16 v[6:9], v[232:235], v[244:247], v[6:9]
	v_mfma_f32_16x16x32_bf16 v[2:5], v[232:235], v[248:251], v[2:5]
	s_setprio 0
	s_addk_i32 s7, 0x80
	s_mov_b32 s8, s9
	s_waitcnt lgkmcnt(0)
	s_barrier
	s_cbranch_vccnz .LBB0_81
	s_lshl_b32 s39, s6, 6
	s_mulk_i32 s4, 0xfc
	s_mul_i32 s6, s5, 0x41f4
	s_sub_i32 s48, s4, s6
	s_mul_hi_i32 s4, s5, 0xb4c8000
	s_mul_i32 s5, s5, 0xb4c8000
	s_add_u32 s8, s34, s5
	s_addc_u32 s9, s38, s4
	s_mov_b32 s6, 0
	s_mov_b64 s[10:11], -1
	s_branch .LBB0_84

; DI void cfence() { asm volatile("" ::: "memory"); }
; DI int swz4(int row) { const int g = (row >> 2) & 3; return ((g << 1) ^ ((g >> 1) * 3)) & 3; }
; #define LSTORE2(RA, RB, P)                                       \
;   {                                                              \
;     char* dA_ = smem + (P) * 24576 + wofs;                       \
;     _Pragma("unroll") for (int j = 0; j < 4; ++j) *(u32x4*)(dA_ + j * 4096) = RA[j]; \
;     _Pragma("unroll") for (int j = 0; j < 2; ++j) *(u32x4*)(dA_ + 16384 + j * 4096) = RB[j]; \
;   }
; DI void gemm256_kloop(f32x4 (&acc)[8][4], const bf16_t* __restrict__ A, int lda, const bf16_t* __restrict__ Bt, int ldb,
;                       int K, int b, int s0, int col0, char* smem) {
;     ...
;   GLOAD2(xa, xb, 0);
;   GLOAD2(ya, yb, 1);
;   cfence();
;   LSTORE2(xa, xb, 0);
;   __syncthreads();
;   const int co = ((fq ^ swz4(fr)) << 4);
;   const int aofs = (wr * 128 + fr) * 64 + co, bofs = (wc * 64 + fr) * 64 + co;
;   for (int kt = 0; kt < nk; kt += 2) {
;     GLOAD2(xa, xb, kt + 2);
;     cfence();
;     COMPUTE2(0);
;     LSTORE2(ya, yb, 1);
;     __syncthreads();
;     if (kt + 1 < nk) {
;       GLOAD2(ya, yb, kt + 3);
;       cfence();
;       COMPUTE2(1);
;       LSTORE2(xa, xb, 0);
;       __syncthreads();
.LBB0_276:
	s_add_i32 s6, s5, 2
	s_cmp_lt_u32 s5, 62
	s_cselect_b64 s[8:9], -1, 0
	s_and_b64 vcc, s[8:9], exec
	s_cselect_b32 s7, s4, 0xfc0
	buffer_load_dwordx4 v[162:165], v0, s[20:23], s7 offen
	buffer_load_dwordx4 v[166:169], v154, s[20:23], s7 offen
	buffer_load_dwordx4 v[170:173], v155, s[20:23], s7 offen
	buffer_load_dwordx4 v[174:177], v156, s[20:23], s7 offen
	buffer_load_dwordx4 v[178:181], v157, s[12:15], s7 offen
	buffer_load_dwordx4 v[182:185], v158, s[12:15], s7 offen
	ds_read_b128 v[236:239], v160 offset:16384
	ds_read_b128 v[240:243], v160 offset:17408
	ds_read_b128 v[244:247], v160 offset:18432
	ds_read_b128 v[248:251], v160 offset:19456
	ds_read_b128 v[186:189], v161
	ds_read_b128 v[190:193], v161 offset:1024
	ds_read_b128 v[212:215], v161 offset:2048
	ds_read_b128 v[216:219], v161 offset:3072
	ds_read_b128 v[220:223], v161 offset:4096
	ds_read_b128 v[224:227], v161 offset:5120
	ds_read_b128 v[228:231], v161 offset:6144
	ds_read_b128 v[232:235], v161 offset:7168
	s_setprio 1
	s_waitcnt lgkmcnt(7)
	v_mfma_f32_16x16x32_bf16 v[126:129], v[186:189], v[236:239], v[126:129]
	v_mfma_f32_16x16x32_bf16 v[122:125], v[186:189], v[240:243], v[122:125]
	v_mfma_f32_16x16x32_bf16 v[118:121], v[186:189], v[244:247], v[118:121]
	v_mfma_f32_16x16x32_bf16 v[114:117], v[186:189], v[248:251], v[114:117]
	s_waitcnt lgkmcnt(6)
	v_mfma_f32_16x16x32_bf16 v[110:113], v[190:193], v[236:239], v[110:113]
	v_mfma_f32_16x16x32_bf16 v[106:109], v[190:193], v[240:243], v[106:109]
	v_mfma_f32_16x16x32_bf16 v[102:105], v[190:193], v[244:247], v[102:105]
	v_mfma_f32_16x16x32_bf16 v[98:101], v[190:193], v[248:251], v[98:101]
	s_waitcnt lgkmcnt(5)
	v_mfma_f32_16x16x32_bf16 v[94:97], v[212:215], v[236:239], v[94:97]
	v_mfma_f32_16x16x32_bf16 v[90:93], v[212:215], v[240:243], v[90:93]
	v_mfma_f32_16x16x32_bf16 v[86:89], v[212:215], v[244:247], v[86:89]
	v_mfma_f32_16x16x32_bf16 v[82:85], v[212:215], v[248:251], v[82:85]
	s_waitcnt lgkmcnt(4)
	v_mfma_f32_16x16x32_bf16 v[78:81], v[216:219], v[236:239], v[78:81]
	v_mfma_f32_16x16x32_bf16 v[74:77], v[216:219], v[240:243], v[74:77]
	v_mfma_f32_16x16x32_bf16 v[70:73], v[216:219], v[244:247], v[70:73]
	v_mfma_f32_16x16x32_bf16 v[66:69], v[216:219], v[248:251], v[66:69]
	s_waitcnt lgkmcnt(3)
	v_mfma_f32_16x16x32_bf16 v[62:65], v[220:223], v[236:239], v[62:65]
	v_mfma_f32_16x16x32_bf16 v[58:61], v[220:223], v[240:243], v[58:61]
	s_waitcnt vmcnt(10)
	ds_write_b128 v159, v[134:137] offset:24576
	v_mfma_f32_16x16x32_bf16 v[54:57], v[220:223], v[244:247], v[54:57]
	v_mfma_f32_16x16x32_bf16 v[50:53], v[220:223], v[248:251], v[50:53]
	s_waitcnt vmcnt(8)
	ds_write_b128 v159, v[142:145] offset:28672
	s_waitcnt lgkmcnt(4)
	v_mfma_f32_16x16x32_bf16 v[46:49], v[224:227], v[236:239], v[46:49]
	v_mfma_f32_16x16x32_bf16 v[42:45], v[224:227], v[240:243], v[42:45]
	s_waitcnt vmcnt(7)
	ds_write_b128 v159, v[146:149] offset:32768
	v_mfma_f32_16x16x32_bf16 v[38:41], v[224:227], v[244:247], v[38:41]
	v_mfma_f32_16x16x32_bf16 v[34:37], v[224:227], v[248:251], v[34:37]
	s_waitcnt vmcnt(6)
	ds_write_b128 v159, v[150:153] offset:36864
	s_waitcnt lgkmcnt(5)
	v_mfma_f32_16x16x32_bf16 v[30:33], v[228:231], v[236:239], v[30:33]
	v_mfma_f32_16x16x32_bf16 v[26:29], v[228:231], v[240:243], v[26:29]
	ds_write_b128 v159, v[130:133] offset:40960
	v_mfma_f32_16x16x32_bf16 v[22:25], v[228:231], v[244:247], v[22:25]
	v_mfma_f32_16x16x32_bf16 v[18:21], v[228:231], v[248:251], v[18:21]
	ds_write_b128 v159, v[138:141] offset:45056
	s_waitcnt lgkmcnt(6)
	v_mfma_f32_16x16x32_bf16 v[14:17], v[232:235], v[236:239], v[14:17]
	v_mfma_f32_16x16x32_bf16 v[10:13], v[232:235], v[240:243], v[10:13]
	v_mfma_f32_16x16x32_bf16 v[6:9], v[232:235], v[244:247], v[6:9]
	v_mfma_f32_16x16x32_bf16 v[2:5], v[232:235], v[248:251], v[2:5]
	s_setprio 0
	s_min_u32 s5, s5, 60
	s_lshl_b32 s5, s5, 6
	s_addk_i32 s5, 0xc0
	s_waitcnt lgkmcnt(0)
	s_barrier
; DI void cfence() { asm volatile("" ::: "memory"); }
; DI int swz4(int row) { const int g = (row >> 2) & 3; return ((g << 1) ^ ((g >> 1) * 3)) & 3; }
; #define LSTORE2(RA, RB, P)                                       \
;   {                                                              \
;     char* dA_ = smem + (P) * 24576 + wofs;                       \
;     _Pragma("unroll") for (int j = 0; j < 4; ++j) *(u32x4*)(dA_ + j * 4096) = RA[j]; \
;     _Pragma("unroll") for (int j = 0; j < 2; ++j) *(u32x4*)(dA_ + 16384 + j * 4096) = RB[j]; \
;   }
; DI void gemm256_kloop(f32x4 (&acc)[8][4], const bf16_t* __restrict__ A, int lda, const bf16_t* __restrict__ Bt, int ldb,
;                       int K, int b, int s0, int col0, char* smem) {
;     ...
;   GLOAD2(xa, xb, 0);
;   GLOAD2(ya, yb, 1);
;   cfence();
;   LSTORE2(xa, xb, 0);
;   __syncthreads();
;   const int co = ((fq ^ swz4(fr)) << 4);
;   const int aofs = (wr * 128 + fr) * 64 + co, bofs = (wc * 64 + fr) * 64 + co;
;   for (int kt = 0; kt < nk; kt += 2) {
;     GLOAD2(xa, xb, kt + 2);
;     cfence();
;     COMPUTE2(0);
;     LSTORE2(ya, yb, 1);
;     __syncthreads();
;     if (kt + 1 < nk) {
;       GLOAD2(ya, yb, kt + 3);
;       cfence();
;       COMPUTE2(1);
;       LSTORE2(xa, xb, 0);
;       __syncthreads();
	buffer_load_dwordx4 v[134:137], v0, s[20:23], s5 offen
	buffer_load_dwordx4 v[142:145], v154, s[20:23], s5 offen
	buffer_load_dwordx4 v[146:149], v155, s[20:23], s5 offen
	buffer_load_dwordx4 v[150:153], v156, s[20:23], s5 offen
	buffer_load_dwordx4 v[130:133], v157, s[12:15], s5 offen
	buffer_load_dwordx4 v[138:141], v158, s[12:15], s5 offen
	ds_read_b128 v[236:239], v160 offset:40960
	ds_read_b128 v[240:243], v160 offset:41984
	ds_read_b128 v[244:247], v160 offset:43008
	ds_read_b128 v[248:251], v160 offset:44032
	ds_read_b128 v[186:189], v161 offset:24576
	ds_read_b128 v[190:193], v161 offset:25600
	ds_read_b128 v[212:215], v161 offset:26624
	ds_read_b128 v[216:219], v161 offset:27648
	ds_read_b128 v[220:223], v161 offset:28672
	ds_read_b128 v[224:227], v161 offset:29696
	ds_read_b128 v[228:231], v161 offset:30720
	ds_read_b128 v[232:235], v161 offset:31744
	s_setprio 1
	s_waitcnt lgkmcnt(7)
	v_mfma_f32_16x16x32_bf16 v[126:129], v[186:189], v[236:239], v[126:129]
	v_mfma_f32_16x16x32_bf16 v[122:125], v[186:189], v[240:243], v[122:125]
	v_mfma_f32_16x16x32_bf16 v[118:121], v[186:189], v[244:247], v[118:121]
	v_mfma_f32_16x16x32_bf16 v[114:117], v[186:189], v[248:251], v[114:117]
	s_waitcnt lgkmcnt(6)
	v_mfma_f32_16x16x32_bf16 v[110:113], v[190:193], v[236:239], v[110:113]
	v_mfma_f32_16x16x32_bf16 v[106:109], v[190:193], v[240:243], v[106:109]
	v_mfma_f32_16x16x32_bf16 v[102:105], v[190:193], v[244:247], v[102:105]
	v_mfma_f32_16x16x32_bf16 v[98:101], v[190:193], v[248:251], v[98:101]
	s_waitcnt lgkmcnt(5)
	v_mfma_f32_16x16x32_bf16 v[94:97], v[212:215], v[236:239], v[94:97]
	v_mfma_f32_16x16x32_bf16 v[90:93], v[212:215], v[240:243], v[90:93]
	v_mfma_f32_16x16x32_bf16 v[86:89], v[212:215], v[244:247], v[86:89]
	v_mfma_f32_16x16x32_bf16 v[82:85], v[212:215], v[248:251], v[82:85]
	s_waitcnt lgkmcnt(4)
	v_mfma_f32_16x16x32_bf16 v[78:81], v[216:219], v[236:239], v[78:81]
	v_mfma_f32_16x16x32_bf16 v[74:77], v[216:219], v[240:243], v[74:77]
	v_mfma_f32_16x16x32_bf16 v[70:73], v[216:219], v[244:247], v[70:73]
	v_mfma_f32_16x16x32_bf16 v[66:69], v[216:219], v[248:251], v[66:69]
	s_waitcnt lgkmcnt(3)
	v_mfma_f32_16x16x32_bf16 v[62:65], v[220:223], v[236:239], v[62:65]
	v_mfma_f32_16x16x32_bf16 v[58:61], v[220:223], v[240:243], v[58:61]
	s_waitcnt vmcnt(11)
	ds_write_b128 v159, v[162:165]
	v_mfma_f32_16x16x32_bf16 v[54:57], v[220:223], v[244:247], v[54:57]
	v_mfma_f32_16x16x32_bf16 v[50:53], v[220:223], v[248:251], v[50:53]
	s_waitcnt vmcnt(10)
	ds_write_b128 v159, v[166:169] offset:4096
	s_waitcnt lgkmcnt(4)
	v_mfma_f32_16x16x32_bf16 v[46:49], v[224:227], v[236:239], v[46:49]
	v_mfma_f32_16x16x32_bf16 v[42:45], v[224:227], v[240:243], v[42:45]
	s_waitcnt vmcnt(9)
	ds_write_b128 v159, v[170:173] offset:8192
	v_mfma_f32_16x16x32_bf16 v[38:41], v[224:227], v[244:247], v[38:41]
	v_mfma_f32_16x16x32_bf16 v[34:37], v[224:227], v[248:251], v[34:37]
	s_waitcnt vmcnt(8)
	ds_write_b128 v159, v[174:177] offset:12288
	s_waitcnt lgkmcnt(5)
	v_mfma_f32_16x16x32_bf16 v[30:33], v[228:231], v[236:239], v[30:33]
	v_mfma_f32_16x16x32_bf16 v[26:29], v[228:231], v[240:243], v[26:29]
	s_waitcnt vmcnt(7)
	ds_write_b128 v159, v[178:181] offset:16384
	v_mfma_f32_16x16x32_bf16 v[22:25], v[228:231], v[244:247], v[22:25]
	v_mfma_f32_16x16x32_bf16 v[18:21], v[228:231], v[248:251], v[18:21]
	s_waitcnt vmcnt(6)
	ds_write_b128 v159, v[182:185] offset:20480
	s_waitcnt lgkmcnt(6)
	v_mfma_f32_16x16x32_bf16 v[14:17], v[232:235], v[236:239], v[14:17]
	v_mfma_f32_16x16x32_bf16 v[10:13], v[232:235], v[240:243], v[10:13]
	v_mfma_f32_16x16x32_bf16 v[6:9], v[232:235], v[244:247], v[6:9]
	v_mfma_f32_16x16x32_bf16 v[2:5], v[232:235], v[248:251], v[2:5]
	s_setprio 0
	s_addk_i32 s4, 0x80
	s_mov_b32 s5, s6
	s_waitcnt lgkmcnt(0)
	s_barrier
	s_cbranch_vccnz .LBB0_276
	s_lshl_b32 s14, s2, 8
	s_sub_i32 s15, s14, s3
	s_mov_b32 s8, 0
	s_mov_b64 s[2:3], -1
	s_branch .LBB0_279

; DI void cfence() { asm volatile("" ::: "memory"); }
; DI int swz4(int row) { const int g = (row >> 2) & 3; return ((g << 1) ^ ((g >> 1) * 3)) & 3; }
; #define LSTORE2(RA, RB, P)                                       \
;   {                                                              \
;     char* dA_ = smem + (P) * 24576 + wofs;                       \
;     _Pragma("unroll") for (int j = 0; j < 4; ++j) *(u32x4*)(dA_ + j * 4096) = RA[j]; \
;     _Pragma("unroll") for (int j = 0; j < 2; ++j) *(u32x4*)(dA_ + 16384 + j * 4096) = RB[j]; \
;   }
; DI void gemm256_kloop(f32x4 (&acc)[8][4], const bf16_t* __restrict__ A, int lda, const bf16_t* __restrict__ Bt, int ldb,
;                       int K, int b, int s0, int col0, char* smem) {
;     ...
;   GLOAD2(xa, xb, 0);
;   GLOAD2(ya, yb, 1);
;   cfence();
;   LSTORE2(xa, xb, 0);
;   __syncthreads();
;   const int co = ((fq ^ swz4(fr)) << 4);
;   const int aofs = (wr * 128 + fr) * 64 + co, bofs = (wc * 64 + fr) * 64 + co;
;   for (int kt = 0; kt < nk; kt += 2) {
;     GLOAD2(xa, xb, kt + 2);
;     cfence();
;     COMPUTE2(0);
;     LSTORE2(ya, yb, 1);
;     __syncthreads();
;     if (kt + 1 < nk) {
;       GLOAD2(ya, yb, kt + 3);
;       cfence();
;       COMPUTE2(1);
;       LSTORE2(xa, xb, 0);
;       __syncthreads();
.LBB0_353:
	s_add_i32 s13, s9, 2
	s_cmp_lt_u32 s9, 62
	s_cselect_b64 s[14:15], -1, 0
	s_and_b64 vcc, s[14:15], exec
	s_cselect_b32 s14, s8, 0xfc0
	buffer_load_dwordx4 v[162:165], v0, s[20:23], s14 offen
	buffer_load_dwordx4 v[166:169], v154, s[20:23], s14 offen
	buffer_load_dwordx4 v[170:173], v155, s[20:23], s14 offen
	buffer_load_dwordx4 v[174:177], v156, s[20:23], s14 offen
	buffer_load_dwordx4 v[178:181], v157, s[4:7], s14 offen
	buffer_load_dwordx4 v[182:185], v158, s[4:7], s14 offen
	ds_read_b128 v[236:239], v160 offset:16384
	ds_read_b128 v[240:243], v160 offset:17408
	ds_read_b128 v[244:247], v160 offset:18432
	ds_read_b128 v[248:251], v160 offset:19456
	ds_read_b128 v[186:189], v161
	ds_read_b128 v[190:193], v161 offset:1024
	ds_read_b128 v[212:215], v161 offset:2048
	ds_read_b128 v[216:219], v161 offset:3072
	ds_read_b128 v[220:223], v161 offset:4096
	ds_read_b128 v[224:227], v161 offset:5120
	ds_read_b128 v[228:231], v161 offset:6144
	ds_read_b128 v[232:235], v161 offset:7168
	s_setprio 1
	s_waitcnt lgkmcnt(7)
	v_mfma_f32_16x16x32_bf16 v[126:129], v[186:189], v[236:239], v[126:129]
	v_mfma_f32_16x16x32_bf16 v[122:125], v[186:189], v[240:243], v[122:125]
	v_mfma_f32_16x16x32_bf16 v[118:121], v[186:189], v[244:247], v[118:121]
	v_mfma_f32_16x16x32_bf16 v[114:117], v[186:189], v[248:251], v[114:117]
	s_waitcnt lgkmcnt(6)
	v_mfma_f32_16x16x32_bf16 v[110:113], v[190:193], v[236:239], v[110:113]
	v_mfma_f32_16x16x32_bf16 v[106:109], v[190:193], v[240:243], v[106:109]
	v_mfma_f32_16x16x32_bf16 v[102:105], v[190:193], v[244:247], v[102:105]
	v_mfma_f32_16x16x32_bf16 v[98:101], v[190:193], v[248:251], v[98:101]
	s_waitcnt lgkmcnt(5)
	v_mfma_f32_16x16x32_bf16 v[94:97], v[212:215], v[236:239], v[94:97]
	v_mfma_f32_16x16x32_bf16 v[90:93], v[212:215], v[240:243], v[90:93]
	v_mfma_f32_16x16x32_bf16 v[86:89], v[212:215], v[244:247], v[86:89]
	v_mfma_f32_16x16x32_bf16 v[82:85], v[212:215], v[248:251], v[82:85]
	s_waitcnt lgkmcnt(4)
	v_mfma_f32_16x16x32_bf16 v[78:81], v[216:219], v[236:239], v[78:81]
	v_mfma_f32_16x16x32_bf16 v[74:77], v[216:219], v[240:243], v[74:77]
	v_mfma_f32_16x16x32_bf16 v[70:73], v[216:219], v[244:247], v[70:73]
	v_mfma_f32_16x16x32_bf16 v[66:69], v[216:219], v[248:251], v[66:69]
	s_waitcnt lgkmcnt(3)
	v_mfma_f32_16x16x32_bf16 v[62:65], v[220:223], v[236:239], v[62:65]
	v_mfma_f32_16x16x32_bf16 v[58:61], v[220:223], v[240:243], v[58:61]
	s_waitcnt vmcnt(9)
	ds_write_b128 v159, v[138:141] offset:24576
	v_mfma_f32_16x16x32_bf16 v[54:57], v[220:223], v[244:247], v[54:57]
	v_mfma_f32_16x16x32_bf16 v[50:53], v[220:223], v[248:251], v[50:53]
	s_waitcnt vmcnt(8)
	ds_write_b128 v159, v[142:145] offset:28672
	s_waitcnt lgkmcnt(4)
	v_mfma_f32_16x16x32_bf16 v[46:49], v[224:227], v[236:239], v[46:49]
	v_mfma_f32_16x16x32_bf16 v[42:45], v[224:227], v[240:243], v[42:45]
	s_waitcnt vmcnt(7)
	ds_write_b128 v159, v[146:149] offset:32768
	v_mfma_f32_16x16x32_bf16 v[38:41], v[224:227], v[244:247], v[38:41]
	v_mfma_f32_16x16x32_bf16 v[34:37], v[224:227], v[248:251], v[34:37]
	s_waitcnt vmcnt(6)
	ds_write_b128 v159, v[150:153] offset:36864
	s_waitcnt lgkmcnt(5)
	v_mfma_f32_16x16x32_bf16 v[30:33], v[228:231], v[236:239], v[30:33]
	v_mfma_f32_16x16x32_bf16 v[26:29], v[228:231], v[240:243], v[26:29]
	ds_write_b128 v159, v[130:133] offset:40960
	v_mfma_f32_16x16x32_bf16 v[22:25], v[228:231], v[244:247], v[22:25]
	v_mfma_f32_16x16x32_bf16 v[18:21], v[228:231], v[248:251], v[18:21]
	ds_write_b128 v159, v[134:137] offset:45056
	s_waitcnt lgkmcnt(6)
	v_mfma_f32_16x16x32_bf16 v[14:17], v[232:235], v[236:239], v[14:17]
	v_mfma_f32_16x16x32_bf16 v[10:13], v[232:235], v[240:243], v[10:13]
	v_mfma_f32_16x16x32_bf16 v[6:9], v[232:235], v[244:247], v[6:9]
	v_mfma_f32_16x16x32_bf16 v[2:5], v[232:235], v[248:251], v[2:5]
	s_setprio 0
	s_min_u32 s9, s9, 60
	s_lshl_b32 s9, s9, 6
	s_addk_i32 s9, 0xc0
	s_waitcnt lgkmcnt(0)
	s_barrier
; DI int bidx() { int t = __builtin_amdgcn_workgroup_id_x(); asm volatile("" : "+s"(t)); return t; }
; DI int gdim() { int t = (int)__ockl_get_num_groups(0); asm volatile("" : "+s"(t)); return t; }
; DI void cfence() { asm volatile("" ::: "memory"); }
; DI int swz4(int row) { const int g = (row >> 2) & 3; return ((g << 1) ^ ((g >> 1) * 3)) & 3; }
; #define LSTORE2(RA, RB, P)                                       \
;   {                                                              \
;     char* dA_ = smem + (P) * 24576 + wofs;                       \
;     _Pragma("unroll") for (int j = 0; j < 4; ++j) *(u32x4*)(dA_ + j * 4096) = RA[j]; \
;     _Pragma("unroll") for (int j = 0; j < 2; ++j) *(u32x4*)(dA_ + 16384 + j * 4096) = RB[j]; \
;   }
; DI void gemm256_kloop(f32x4 (&acc)[8][4], const bf16_t* __restrict__ A, int lda, const bf16_t* __restrict__ Bt, int ldb,
;                       int K, int b, int s0, int col0, char* smem) {
;     ...
;   GLOAD2(xa, xb, 0);
;   GLOAD2(ya, yb, 1);
;   cfence();
;   LSTORE2(xa, xb, 0);
;   __syncthreads();
;   const int co = ((fq ^ swz4(fr)) << 4);
;   const int aofs = (wr * 128 + fr) * 64 + co, bofs = (wc * 64 + fr) * 64 + co;
;   for (int kt = 0; kt < nk; kt += 2) {
;     GLOAD2(xa, xb, kt + 2);
;     cfence();
;     COMPUTE2(0);
;     LSTORE2(ya, yb, 1);
;     __syncthreads();
;     if (kt + 1 < nk) {
;       GLOAD2(ya, yb, kt + 3);
;       cfence();
;       COMPUTE2(1);
;       LSTORE2(xa, xb, 0);
;       __syncthreads();
; template <class Epi>
; DI void gemm256_phase_plain(const bf16_t* A, int lda, const bf16_t* Bt, int ldb, int K, int ntn, char* smem, const Epi& epi,
;                             bool skip_ctx = false) {
;   if (!skip_ctx) {
;     const int total = 130 * ntn;
;     for (int it = bidx(); it < total; it += gdim()) gemm256_item_plain(A, lda, Bt, ldb, K, ntn, smem, epi, it);
;   } else {
;     const int total = 128 * ntn;
;     for (int it = bidx(); it < total; it += gdim()) {
;       const int mt = it / ntn, nt = it - mt * ntn;
;       const int mt2 = mt + 1 + (mt >= 64 ? 1 : 0);
;       gemm256_item_plain(A, lda, Bt, ldb, K, ntn, smem, epi, mt2 * ntn + nt);
;     }
;   }
; }
	buffer_load_dwordx4 v[138:141], v0, s[20:23], s9 offen
	buffer_load_dwordx4 v[142:145], v154, s[20:23], s9 offen
	buffer_load_dwordx4 v[146:149], v155, s[20:23], s9 offen
	buffer_load_dwordx4 v[150:153], v156, s[20:23], s9 offen
	buffer_load_dwordx4 v[130:133], v157, s[4:7], s9 offen
	buffer_load_dwordx4 v[134:137], v158, s[4:7], s9 offen
	ds_read_b128 v[236:239], v160 offset:40960
	ds_read_b128 v[240:243], v160 offset:41984
	ds_read_b128 v[244:247], v160 offset:43008
	ds_read_b128 v[248:251], v160 offset:44032
	ds_read_b128 v[186:189], v161 offset:24576
	ds_read_b128 v[190:193], v161 offset:25600
	ds_read_b128 v[212:215], v161 offset:26624
	ds_read_b128 v[216:219], v161 offset:27648
	ds_read_b128 v[220:223], v161 offset:28672
	ds_read_b128 v[224:227], v161 offset:29696
	ds_read_b128 v[228:231], v161 offset:30720
	ds_read_b128 v[232:235], v161 offset:31744
	s_setprio 1
	s_waitcnt lgkmcnt(7)
	v_mfma_f32_16x16x32_bf16 v[126:129], v[186:189], v[236:239], v[126:129]
	v_mfma_f32_16x16x32_bf16 v[122:125], v[186:189], v[240:243], v[122:125]
	v_mfma_f32_16x16x32_bf16 v[118:121], v[186:189], v[244:247], v[118:121]
	v_mfma_f32_16x16x32_bf16 v[114:117], v[186:189], v[248:251], v[114:117]
	s_waitcnt lgkmcnt(6)
	v_mfma_f32_16x16x32_bf16 v[110:113], v[190:193], v[236:239], v[110:113]
	v_mfma_f32_16x16x32_bf16 v[106:109], v[190:193], v[240:243], v[106:109]
	v_mfma_f32_16x16x32_bf16 v[102:105], v[190:193], v[244:247], v[102:105]
	v_mfma_f32_16x16x32_bf16 v[98:101], v[190:193], v[248:251], v[98:101]
	s_waitcnt lgkmcnt(5)
	v_mfma_f32_16x16x32_bf16 v[94:97], v[212:215], v[236:239], v[94:97]
	v_mfma_f32_16x16x32_bf16 v[90:93], v[212:215], v[240:243], v[90:93]
	v_mfma_f32_16x16x32_bf16 v[86:89], v[212:215], v[244:247], v[86:89]
	v_mfma_f32_16x16x32_bf16 v[82:85], v[212:215], v[248:251], v[82:85]
	s_waitcnt lgkmcnt(4)
	v_mfma_f32_16x16x32_bf16 v[78:81], v[216:219], v[236:239], v[78:81]
	v_mfma_f32_16x16x32_bf16 v[74:77], v[216:219], v[240:243], v[74:77]
	v_mfma_f32_16x16x32_bf16 v[70:73], v[216:219], v[244:247], v[70:73]
	v_mfma_f32_16x16x32_bf16 v[66:69], v[216:219], v[248:251], v[66:69]
	s_waitcnt lgkmcnt(3)
	v_mfma_f32_16x16x32_bf16 v[62:65], v[220:223], v[236:239], v[62:65]
	v_mfma_f32_16x16x32_bf16 v[58:61], v[220:223], v[240:243], v[58:61]
	s_waitcnt vmcnt(11)
	ds_write_b128 v159, v[162:165]
	v_mfma_f32_16x16x32_bf16 v[54:57], v[220:223], v[244:247], v[54:57]
	v_mfma_f32_16x16x32_bf16 v[50:53], v[220:223], v[248:251], v[50:53]
	s_waitcnt vmcnt(10)
	ds_write_b128 v159, v[166:169] offset:4096
	s_waitcnt lgkmcnt(4)
	v_mfma_f32_16x16x32_bf16 v[46:49], v[224:227], v[236:239], v[46:49]
	v_mfma_f32_16x16x32_bf16 v[42:45], v[224:227], v[240:243], v[42:45]
	s_waitcnt vmcnt(9)
	ds_write_b128 v159, v[170:173] offset:8192
	v_mfma_f32_16x16x32_bf16 v[38:41], v[224:227], v[244:247], v[38:41]
	v_mfma_f32_16x16x32_bf16 v[34:37], v[224:227], v[248:251], v[34:37]
	s_waitcnt vmcnt(8)
	ds_write_b128 v159, v[174:177] offset:12288
	s_waitcnt lgkmcnt(5)
	v_mfma_f32_16x16x32_bf16 v[30:33], v[228:231], v[236:239], v[30:33]
	v_mfma_f32_16x16x32_bf16 v[26:29], v[228:231], v[240:243], v[26:29]
	s_waitcnt vmcnt(7)
	ds_write_b128 v159, v[178:181] offset:16384
	v_mfma_f32_16x16x32_bf16 v[22:25], v[228:231], v[244:247], v[22:25]
	v_mfma_f32_16x16x32_bf16 v[18:21], v[228:231], v[248:251], v[18:21]
	s_waitcnt vmcnt(6)
	ds_write_b128 v159, v[182:185] offset:20480
	s_waitcnt lgkmcnt(6)
	v_mfma_f32_16x16x32_bf16 v[14:17], v[232:235], v[236:239], v[14:17]
	v_mfma_f32_16x16x32_bf16 v[10:13], v[232:235], v[240:243], v[10:13]
	v_mfma_f32_16x16x32_bf16 v[6:9], v[232:235], v[244:247], v[6:9]
	v_mfma_f32_16x16x32_bf16 v[2:5], v[232:235], v[248:251], v[2:5]
	s_setprio 0
	s_addk_i32 s8, 0x80
	s_mov_b32 s9, s13
	s_waitcnt lgkmcnt(0)
	s_barrier
	s_cbranch_vccnz .LBB0_353
	s_mul_hi_i32 s13, s3, 0x4100
	s_lshl_b32 s3, s2, 8
	s_sub_i32 s14, s3, s12
	s_lshl_b32 s3, s11, 7
	s_mulk_i32 s2, 0x1800
	s_sub_i32 s15, s3, s2
	s_mov_b32 s8, 0
	s_mov_b64 s[2:3], -1
	s_waitcnt vmcnt(0)
	s_branch .LBB0_356

; DI void cfence() { asm volatile("" ::: "memory"); }
; DI int swz4(int row) { const int g = (row >> 2) & 3; return ((g << 1) ^ ((g >> 1) * 3)) & 3; }
; #define LSTORE2(RA, RB, P)                                       \
;   {                                                              \
;     char* dA_ = smem + (P) * 24576 + wofs;                       \
;     _Pragma("unroll") for (int j = 0; j < 4; ++j) *(u32x4*)(dA_ + j * 4096) = RA[j]; \
;     _Pragma("unroll") for (int j = 0; j < 2; ++j) *(u32x4*)(dA_ + 16384 + j * 4096) = RB[j]; \
;   }
; DI void gemm256_kloop(f32x4 (&acc)[8][4], const bf16_t* __restrict__ A, int lda, const bf16_t* __restrict__ Bt, int ldb,
;                       int K, int b, int s0, int col0, char* smem) {
;     ...
;   GLOAD2(xa, xb, 0);
;   GLOAD2(ya, yb, 1);
;   cfence();
;   LSTORE2(xa, xb, 0);
;   __syncthreads();
;   const int co = ((fq ^ swz4(fr)) << 4);
;   const int aofs = (wr * 128 + fr) * 64 + co, bofs = (wc * 64 + fr) * 64 + co;
;   for (int kt = 0; kt < nk; kt += 2) {
;     GLOAD2(xa, xb, kt + 2);
;     cfence();
;     COMPUTE2(0);
;     LSTORE2(ya, yb, 1);
;     __syncthreads();
;     if (kt + 1 < nk) {
;       GLOAD2(ya, yb, kt + 3);
;       cfence();
;       COMPUTE2(1);
;       LSTORE2(xa, xb, 0);
;       __syncthreads();
.LBB0_367:
	s_add_i32 s13, s9, 2
	s_cmp_lt_u32 s9, 62
	s_cselect_b64 s[14:15], -1, 0
	s_and_b64 vcc, s[14:15], exec
	s_cselect_b32 s14, s8, 0xfc0
	buffer_load_dwordx4 v[162:165], v0, s[20:23], s14 offen
	buffer_load_dwordx4 v[166:169], v154, s[20:23], s14 offen
	buffer_load_dwordx4 v[170:173], v155, s[20:23], s14 offen
	buffer_load_dwordx4 v[174:177], v156, s[20:23], s14 offen
	buffer_load_dwordx4 v[178:181], v157, s[4:7], s14 offen
	buffer_load_dwordx4 v[182:185], v158, s[4:7], s14 offen
	ds_read_b128 v[236:239], v160 offset:16384
	ds_read_b128 v[240:243], v160 offset:17408
	ds_read_b128 v[244:247], v160 offset:18432
	ds_read_b128 v[248:251], v160 offset:19456
	ds_read_b128 v[186:189], v161
	ds_read_b128 v[190:193], v161 offset:1024
	ds_read_b128 v[212:215], v161 offset:2048
	ds_read_b128 v[216:219], v161 offset:3072
	ds_read_b128 v[220:223], v161 offset:4096
	ds_read_b128 v[224:227], v161 offset:5120
	ds_read_b128 v[228:231], v161 offset:6144
	ds_read_b128 v[232:235], v161 offset:7168
	s_setprio 1
	s_waitcnt lgkmcnt(7)
	v_mfma_f32_16x16x32_bf16 v[126:129], v[186:189], v[236:239], v[126:129]
	v_mfma_f32_16x16x32_bf16 v[122:125], v[186:189], v[240:243], v[122:125]
	v_mfma_f32_16x16x32_bf16 v[118:121], v[186:189], v[244:247], v[118:121]
	v_mfma_f32_16x16x32_bf16 v[114:117], v[186:189], v[248:251], v[114:117]
	s_waitcnt lgkmcnt(6)
	v_mfma_f32_16x16x32_bf16 v[110:113], v[190:193], v[236:239], v[110:113]
	v_mfma_f32_16x16x32_bf16 v[106:109], v[190:193], v[240:243], v[106:109]
	v_mfma_f32_16x16x32_bf16 v[102:105], v[190:193], v[244:247], v[102:105]
	v_mfma_f32_16x16x32_bf16 v[98:101], v[190:193], v[248:251], v[98:101]
	s_waitcnt lgkmcnt(5)
	v_mfma_f32_16x16x32_bf16 v[94:97], v[212:215], v[236:239], v[94:97]
	v_mfma_f32_16x16x32_bf16 v[90:93], v[212:215], v[240:243], v[90:93]
	v_mfma_f32_16x16x32_bf16 v[86:89], v[212:215], v[244:247], v[86:89]
	v_mfma_f32_16x16x32_bf16 v[82:85], v[212:215], v[248:251], v[82:85]
	s_waitcnt lgkmcnt(4)
	v_mfma_f32_16x16x32_bf16 v[78:81], v[216:219], v[236:239], v[78:81]
	v_mfma_f32_16x16x32_bf16 v[74:77], v[216:219], v[240:243], v[74:77]
	v_mfma_f32_16x16x32_bf16 v[70:73], v[216:219], v[244:247], v[70:73]
	v_mfma_f32_16x16x32_bf16 v[66:69], v[216:219], v[248:251], v[66:69]
	s_waitcnt lgkmcnt(3)
	v_mfma_f32_16x16x32_bf16 v[62:65], v[220:223], v[236:239], v[62:65]
	v_mfma_f32_16x16x32_bf16 v[58:61], v[220:223], v[240:243], v[58:61]
	s_waitcnt vmcnt(9)
	ds_write_b128 v159, v[138:141] offset:24576
	v_mfma_f32_16x16x32_bf16 v[54:57], v[220:223], v[244:247], v[54:57]
	v_mfma_f32_16x16x32_bf16 v[50:53], v[220:223], v[248:251], v[50:53]
	s_waitcnt vmcnt(8)
	ds_write_b128 v159, v[142:145] offset:28672
	s_waitcnt lgkmcnt(4)
	v_mfma_f32_16x16x32_bf16 v[46:49], v[224:227], v[236:239], v[46:49]
	v_mfma_f32_16x16x32_bf16 v[42:45], v[224:227], v[240:243], v[42:45]
	s_waitcnt vmcnt(7)
	ds_write_b128 v159, v[146:149] offset:32768
	v_mfma_f32_16x16x32_bf16 v[38:41], v[224:227], v[244:247], v[38:41]
	v_mfma_f32_16x16x32_bf16 v[34:37], v[224:227], v[248:251], v[34:37]
	s_waitcnt vmcnt(6)
	ds_write_b128 v159, v[150:153] offset:36864
	s_waitcnt lgkmcnt(5)
	v_mfma_f32_16x16x32_bf16 v[30:33], v[228:231], v[236:239], v[30:33]
	v_mfma_f32_16x16x32_bf16 v[26:29], v[228:231], v[240:243], v[26:29]
	ds_write_b128 v159, v[130:133] offset:40960
	v_mfma_f32_16x16x32_bf16 v[22:25], v[228:231], v[244:247], v[22:25]
	v_mfma_f32_16x16x32_bf16 v[18:21], v[228:231], v[248:251], v[18:21]
	ds_write_b128 v159, v[134:137] offset:45056
	s_waitcnt lgkmcnt(6)
	v_mfma_f32_16x16x32_bf16 v[14:17], v[232:235], v[236:239], v[14:17]
	v_mfma_f32_16x16x32_bf16 v[10:13], v[232:235], v[240:243], v[10:13]
	v_mfma_f32_16x16x32_bf16 v[6:9], v[232:235], v[244:247], v[6:9]
	v_mfma_f32_16x16x32_bf16 v[2:5], v[232:235], v[248:251], v[2:5]
	s_setprio 0
	s_min_u32 s9, s9, 60
	s_lshl_b32 s9, s9, 6
	s_addk_i32 s9, 0xc0
	s_waitcnt lgkmcnt(0)
	s_barrier
; DI void cfence() { asm volatile("" ::: "memory"); }
; DI int swz4(int row) { const int g = (row >> 2) & 3; return ((g << 1) ^ ((g >> 1) * 3)) & 3; }
; #define LSTORE2(RA, RB, P)                                       \
;   {                                                              \
;     char* dA_ = smem + (P) * 24576 + wofs;                       \
;     _Pragma("unroll") for (int j = 0; j < 4; ++j) *(u32x4*)(dA_ + j * 4096) = RA[j]; \
;     _Pragma("unroll") for (int j = 0; j < 2; ++j) *(u32x4*)(dA_ + 16384 + j * 4096) = RB[j]; \
;   }
; DI void gemm256_kloop(f32x4 (&acc)[8][4], const bf16_t* __restrict__ A, int lda, const bf16_t* __restrict__ Bt, int ldb,
;                       int K, int b, int s0, int col0, char* smem) {
;     ...
;   GLOAD2(xa, xb, 0);
;   GLOAD2(ya, yb, 1);
;   cfence();
;   LSTORE2(xa, xb, 0);
;   __syncthreads();
;   const int co = ((fq ^ swz4(fr)) << 4);
;   const int aofs = (wr * 128 + fr) * 64 + co, bofs = (wc * 64 + fr) * 64 + co;
;   for (int kt = 0; kt < nk; kt += 2) {
;     GLOAD2(xa, xb, kt + 2);
;     cfence();
;     COMPUTE2(0);
;     LSTORE2(ya, yb, 1);
;     __syncthreads();
;     if (kt + 1 < nk) {
;       GLOAD2(ya, yb, kt + 3);
;       cfence();
;       COMPUTE2(1);
;       LSTORE2(xa, xb, 0);
;       __syncthreads();
	buffer_load_dwordx4 v[138:141], v0, s[20:23], s9 offen
	buffer_load_dwordx4 v[142:145], v154, s[20:23], s9 offen
	buffer_load_dwordx4 v[146:149], v155, s[20:23], s9 offen
	buffer_load_dwordx4 v[150:153], v156, s[20:23], s9 offen
	buffer_load_dwordx4 v[130:133], v157, s[4:7], s9 offen
	buffer_load_dwordx4 v[134:137], v158, s[4:7], s9 offen
	ds_read_b128 v[236:239], v160 offset:40960
	ds_read_b128 v[240:243], v160 offset:41984
	ds_read_b128 v[244:247], v160 offset:43008
	ds_read_b128 v[248:251], v160 offset:44032
	ds_read_b128 v[186:189], v161 offset:24576
	ds_read_b128 v[190:193], v161 offset:25600
	ds_read_b128 v[212:215], v161 offset:26624
	ds_read_b128 v[216:219], v161 offset:27648
	ds_read_b128 v[220:223], v161 offset:28672
	ds_read_b128 v[224:227], v161 offset:29696
	ds_read_b128 v[228:231], v161 offset:30720
	ds_read_b128 v[232:235], v161 offset:31744
	s_setprio 1
	s_waitcnt lgkmcnt(7)
	v_mfma_f32_16x16x32_bf16 v[126:129], v[186:189], v[236:239], v[126:129]
	v_mfma_f32_16x16x32_bf16 v[122:125], v[186:189], v[240:243], v[122:125]
	v_mfma_f32_16x16x32_bf16 v[118:121], v[186:189], v[244:247], v[118:121]
	v_mfma_f32_16x16x32_bf16 v[114:117], v[186:189], v[248:251], v[114:117]
	s_waitcnt lgkmcnt(6)
	v_mfma_f32_16x16x32_bf16 v[110:113], v[190:193], v[236:239], v[110:113]
	v_mfma_f32_16x16x32_bf16 v[106:109], v[190:193], v[240:243], v[106:109]
	v_mfma_f32_16x16x32_bf16 v[102:105], v[190:193], v[244:247], v[102:105]
	v_mfma_f32_16x16x32_bf16 v[98:101], v[190:193], v[248:251], v[98:101]
	s_waitcnt lgkmcnt(5)
	v_mfma_f32_16x16x32_bf16 v[94:97], v[212:215], v[236:239], v[94:97]
	v_mfma_f32_16x16x32_bf16 v[90:93], v[212:215], v[240:243], v[90:93]
	v_mfma_f32_16x16x32_bf16 v[86:89], v[212:215], v[244:247], v[86:89]
	v_mfma_f32_16x16x32_bf16 v[82:85], v[212:215], v[248:251], v[82:85]
	s_waitcnt lgkmcnt(4)
	v_mfma_f32_16x16x32_bf16 v[78:81], v[216:219], v[236:239], v[78:81]
	v_mfma_f32_16x16x32_bf16 v[74:77], v[216:219], v[240:243], v[74:77]
	v_mfma_f32_16x16x32_bf16 v[70:73], v[216:219], v[244:247], v[70:73]
	v_mfma_f32_16x16x32_bf16 v[66:69], v[216:219], v[248:251], v[66:69]
	s_waitcnt lgkmcnt(3)
	v_mfma_f32_16x16x32_bf16 v[62:65], v[220:223], v[236:239], v[62:65]
	v_mfma_f32_16x16x32_bf16 v[58:61], v[220:223], v[240:243], v[58:61]
	s_waitcnt vmcnt(11)
	ds_write_b128 v159, v[162:165]
	v_mfma_f32_16x16x32_bf16 v[54:57], v[220:223], v[244:247], v[54:57]
	v_mfma_f32_16x16x32_bf16 v[50:53], v[220:223], v[248:251], v[50:53]
	s_waitcnt vmcnt(10)
	ds_write_b128 v159, v[166:169] offset:4096
	s_waitcnt lgkmcnt(4)
	v_mfma_f32_16x16x32_bf16 v[46:49], v[224:227], v[236:239], v[46:49]
	v_mfma_f32_16x16x32_bf16 v[42:45], v[224:227], v[240:243], v[42:45]
	s_waitcnt vmcnt(9)
	ds_write_b128 v159, v[170:173] offset:8192
	v_mfma_f32_16x16x32_bf16 v[38:41], v[224:227], v[244:247], v[38:41]
	v_mfma_f32_16x16x32_bf16 v[34:37], v[224:227], v[248:251], v[34:37]
	s_waitcnt vmcnt(8)
	ds_write_b128 v159, v[174:177] offset:12288
	s_waitcnt lgkmcnt(5)
	v_mfma_f32_16x16x32_bf16 v[30:33], v[228:231], v[236:239], v[30:33]
	v_mfma_f32_16x16x32_bf16 v[26:29], v[228:231], v[240:243], v[26:29]
	s_waitcnt vmcnt(7)
	ds_write_b128 v159, v[178:181] offset:16384
	v_mfma_f32_16x16x32_bf16 v[22:25], v[228:231], v[244:247], v[22:25]
	v_mfma_f32_16x16x32_bf16 v[18:21], v[228:231], v[248:251], v[18:21]
	s_waitcnt vmcnt(6)
	ds_write_b128 v159, v[182:185] offset:20480
	s_waitcnt lgkmcnt(6)
	v_mfma_f32_16x16x32_bf16 v[14:17], v[232:235], v[236:239], v[14:17]
	v_mfma_f32_16x16x32_bf16 v[10:13], v[232:235], v[240:243], v[10:13]
	v_mfma_f32_16x16x32_bf16 v[6:9], v[232:235], v[244:247], v[6:9]
	v_mfma_f32_16x16x32_bf16 v[2:5], v[232:235], v[248:251], v[2:5]
	s_setprio 0
	s_addk_i32 s8, 0x80
	s_mov_b32 s9, s13
	s_waitcnt lgkmcnt(0)
	s_barrier
	s_cbranch_vccnz .LBB0_367
	s_lshl_b32 s2, s2, 8
	s_mul_hi_i32 s13, s3, 0x4100
	s_sub_i32 s14, s2, s12
	s_mov_b32 s8, 0
	s_mov_b64 s[2:3], -1
	s_waitcnt vmcnt(0)
	s_branch .LBB0_370

; DI int tidx() { int t = __builtin_amdgcn_workitem_id_x(); asm volatile("" : "+v"(t)); return t; }
; DI brsrc_t make_rsrc(const void* p) { return __builtin_amdgcn_make_buffer_rsrc((void*)p, 0, 0x7fffffff, 0x00020000); }
; template <int DQK, int DV>
; DI void attn_tile(const bf16_t* Q, int ldq, const bf16_t* Kb, int ldk, const bf16_t* Vt, bf16_t* O, int ldo, int b, int sq0,
;                   int r0a, int r0b, int r1a, int r1b, float m_init, float l_init, char* smem) {
;   const int tid = tidx(), lane = tid & 63, wid = tid >> 6;
;   const int ql = lane & 31, hh = lane >> 5;
;   constexpr int NS = DQK / 16, NB = DV / 32;
;   constexpr int KB = 32 * DQK * 2, VB = DV * 64, BUF = KB + VB;
;   const int qs = sq0 + wid * 32 + ql;
;   bf16x8 qf[NS];
;   {
;     const bf16_t* qp = Q + (size_t)(b * SB + qs) * ldq + 8 * hh;
; #pragma unroll
;     for (int s = 0; s < NS; ++s) qf[s] = *(const bf16x8*)(qp + 16 * s);
;   }
;   f32x16 acc[NB];
; #pragma unroll
;   for (int i = 0; i < NB; ++i)
; #pragma unroll
;     for (int r = 0; r < 16; ++r) acc[i][r] = 0.f;
;   float m = m_init, lsum = l_init;
;   const int n0 = (r0b - r0a) >> 5, n1 = (r1b > r1a) ? ((r1b - r1a) >> 5) : 0;
;   const int nt = n0 + n1;
;   const brsrc_t Kbase = make_rsrc(Kb + (size_t)b * SB * ldk);
;   const brsrc_t Vbase = make_rsrc(Vt);
;   AttnMap<DQK, DV> mp;
;   mp.init(ldk);
;   u32x4 rk[DQK / 64], rv[DV / 64];
;   attn_load<DQK, DV>(rk, rv, mp, Kbase, ldk, Vbase, r0a);
;   attn_store<DQK, DV>(rk, rv, mp, smem, smem + KB);
;   __syncthreads();
; DI void phase_attn(const Params& P, int l, char* smem) {
;     ...
;       if (it < nmla_l) {
;         const int j = (it & 7) * (nmla_l >> 3) + (it >> 3);
;         int bh = j >> 7, qt = j & 127; b = bh >> 3; h = bh & 7; sq0 = CTXL + 128 * qt; kend = SB;
;       }
;       else { int i2 = it - nmla_l; int bh = i2 >> 1, qt = i2 & 1; b = bh >> 3; h = bh & 7; sq0 = 128 * qt; kend = CTXL; }
;       attn_tile<192, 128>((const bf16_t*)(Bg + B_QMLA) + h * 192, LDKQ, (const bf16_t*)(Bg + B_KMLA) + h * 192, LDKQ,
;                           (const bf16_t*)(Bg + B_VTMLA) + ((size_t)b * 1024 + h * 128) * SB, (bf16_t*)(P.ws + OFF_OC) + h * 128, 1024,
;                           b, sq0, 0, kend, 0, 0, -1e30f, 0.f, smem);
.LBB0_406:
	s_and_b32 s3, s1, 7
	s_mul_i32 s1, s3, 0x180
	s_add_u32 s6, s14, s1
	s_addc_u32 s7, s15, 0
	s_add_u32 s34, s16, s1
	s_addc_u32 s38, s17, 0
	s_ashr_i32 s1, s0, 31
	s_lshl_b64 s[20:21], s[0:1], 10
	s_lshl_b32 s1, s3, 7
	s_or_b32 s3, s20, s1
	s_mul_i32 s4, s3, 0x8200
	s_mul_hi_u32 s3, s3, 0x8200
	s_mul_i32 s20, s21, 0x8200
	s_add_i32 s3, s3, s20
	s_waitcnt vmcnt(3)
	v_mov_b32_e32 v28, v194
	s_add_u32 s4, s18, s4
	s_mul_i32 s20, s0, 0x4100
	v_ashrrev_i32_e32 v0, 1, v28
	s_addc_u32 s3, s19, s3
	v_and_b32_e32 v29, 31, v28
	v_and_b32_e32 v0, 0xffffffe0, v0
	s_add_i32 s20, s20, s5
	v_bfe_u32 v154, v28, 5, 1
	v_add3_u32 v152, s20, v29, v0
	s_waitcnt vmcnt(1)
	v_mov_b64_e32 v[2:3], s[6:7]
	v_mad_i64_i32 v[2:3], s[6:7], v152, s66, v[2:3]
	v_lshlrev_b32_e32 v0, 4, v154
	v_lshl_add_u64 v[2:3], v[2:3], 0, v[0:1]
	v_mov_b32_e32 v0, v194
	global_load_dwordx4 v[140:143], v[2:3], off
	global_load_dwordx4 v[136:139], v[2:3], off offset:32
	global_load_dwordx4 v[132:135], v[2:3], off offset:64
	global_load_dwordx4 v[128:131], v[2:3], off offset:96
	global_load_dwordx4 v[124:127], v[2:3], off offset:128
	global_load_dwordx4 v[120:123], v[2:3], off offset:160
	global_load_dwordx4 v[116:119], v[2:3], off offset:192
	global_load_dwordx4 v[112:115], v[2:3], off offset:224
	global_load_dwordx4 v[108:111], v[2:3], off offset:256
	global_load_dwordx4 v[104:107], v[2:3], off offset:288
	global_load_dwordx4 v[100:103], v[2:3], off offset:320
	global_load_dwordx4 v[96:99], v[2:3], off offset:352
	s_mul_hi_i32 s5, s0, 0x32c8000
	v_mul_hi_i32 v2, v0, s69
	s_mul_i32 s0, s0, 0x32c8000
	v_lshrrev_b32_e32 v3, 31, v2
	v_ashrrev_i32_e32 v2, 2, v2
	s_add_u32 s20, s34, s0
	s_waitcnt vmcnt(12)
	v_add_u32_e32 v30, v2, v3
	s_addc_u32 s0, s38, s5
	v_mad_u64_u32 v[22:23], s[38:39], v30, s50, v[0:1]
	v_mul_lo_u32 v2, v30, s66
	v_lshl_add_u32 v165, v22, 4, v2
	v_add_u32_e32 v2, 0x100, v0
	v_mul_hi_i32 v3, v2, s69
	v_lshrrev_b32_e32 v4, 31, v3
	v_ashrrev_i32_e32 v3, 2, v3
	v_add_u32_e32 v23, v3, v4
	v_mad_u64_u32 v[24:25], s[38:39], v23, s50, v[2:3]
	v_mul_lo_u32 v3, v23, s66
	v_add_u32_e32 v4, 0x200, v0
	v_lshl_add_u32 v166, v24, 4, v3
	v_mul_hi_i32 v3, v4, s69
	v_lshrrev_b32_e32 v5, 31, v3
	v_ashrrev_i32_e32 v3, 2, v3
	v_add_u32_e32 v25, v3, v5
	v_mad_u64_u32 v[26:27], s[38:39], v25, s50, v[4:5]
	v_mul_lo_u32 v3, v25, s66
	s_and_b32 s21, s0, 0xffff
	v_lshl_add_u32 v167, v26, 4, v3
	v_lshlrev_b32_e32 v3, 4, v0
	v_ashrrev_i32_e32 v27, 2, v0
	s_mov_b32 s0, 0x8200
	v_and_b32_e32 v18, 48, v3
	v_mul_lo_u32 v3, v27, s0
	s_and_b32 s5, s3, 0xffff
	s_mov_b32 s6, s22
	s_mov_b32 s7, s23
	v_or_b32_e32 v168, v3, v18
	v_ashrrev_i32_e32 v31, 2, v2
	buffer_load_dwordx4 v[2:5], v165, s[20:23], 0 offen
	buffer_load_dwordx4 v[6:9], v166, s[20:23], 0 offen
	buffer_load_dwordx4 v[10:13], v167, s[20:23], 0 offen
	buffer_load_dwordx4 v[14:17], v168, s[4:7], 0 offen
	v_mul_lo_u32 v19, v31, s0
	v_or_b32_e32 v169, v19, v18
	buffer_load_dwordx4 v[18:21], v169, s[4:7], 0 offen
	v_lshrrev_b32_e32 v33, 1, v30
	v_bitop3_b32 v33, v33, 7, v0 bitop3:0x48
	v_and_or_b32 v22, v22, s48, v33
	v_mul_lo_u32 v30, v30, s79
	v_lshl_add_u32 v155, v22, 4, v30
	v_lshrrev_b32_e32 v22, 1, v23
	v_bitop3_b32 v22, v22, 7, v0 bitop3:0x48
	v_and_or_b32 v22, v24, s48, v22
	v_mul_lo_u32 v23, v23, s79
	v_lshl_add_u32 v156, v22, 4, v23
	v_lshrrev_b32_e32 v22, 1, v25
	v_bitop3_b32 v22, v22, 7, v0 bitop3:0x48
	v_and_or_b32 v22, v26, s48, v22
	v_mul_lo_u32 v23, v25, s79
	v_lshl_add_u32 v157, v22, 4, v23
	v_bfe_i32 v22, v0, 6, 1
	v_and_b32_e32 v23, 2, v0
	v_lshrrev_b32_e32 v25, 2, v27
	v_or_b32_e32 v24, 1, v23
	v_bitop3_b32 v25, v25, v22, 3 bitop3:0x28
	v_lshlrev_b32_e32 v0, 3, v0
	v_lshlrev_b32_e32 v26, 6, v27
	v_xor_b32_e32 v27, v25, v23
	v_xor_b32_e32 v25, v25, v24
	v_and_b32_e32 v0, 8, v0
	v_lshlrev_b32_e32 v25, 4, v25
	v_or3_b32 v161, v25, v26, v0
	v_lshrrev_b32_e32 v25, 2, v31
	v_bitop3_b32 v22, v25, v22, 3 bitop3:0x28
	v_xor_b32_e32 v23, v22, v23
	v_xor_b32_e32 v22, v22, v24
	v_lshlrev_b32_e32 v27, 4, v27
	v_lshlrev_b32_e32 v25, 6, v31
	v_lshlrev_b32_e32 v23, 4, v23
	v_lshlrev_b32_e32 v22, 4, v22
	v_or3_b32 v160, v27, v26, v0
	v_or3_b32 v158, v23, v25, v0
	v_or3_b32 v159, v22, v25, v0
	v_bfe_u32 v0, v28, 1, 3
	v_lshrrev_b32_e32 v32, 5, v28
	s_waitcnt vmcnt(4)
	ds_write_b128 v155, v[2:5]
	s_waitcnt vmcnt(3)
	ds_write_b128 v156, v[6:9]
	s_waitcnt vmcnt(2)
	ds_write_b128 v157, v[10:13]
	s_waitcnt vmcnt(1)
	ds_write_b64 v160, v[14:15] offset:12288
	ds_write_b64 v161, v[16:17] offset:12288
	s_waitcnt vmcnt(0)
	ds_write_b64 v158, v[18:19] offset:12288
	ds_write_b64 v159, v[20:21] offset:12288
	v_lshrrev_b32_e32 v2, 2, v28
	v_bfe_i32 v3, v28, 4, 1
	v_bitop3_b32 v4, v154, v0, 2 bitop3:0x36
	v_xor_b32_e32 v2, v3, v2
	v_bitop3_b32 v3, v32, v0, 1 bitop3:0x6c
	v_lshlrev_b32_e32 v174, 4, v4
	v_bitop3_b32 v4, v154, v0, 4 bitop3:0x36
	v_bitop3_b32 v0, v154, v0, 6 bitop3:0x36
	v_lshlrev_b32_e32 v173, 4, v3
	v_or_b32_e32 v3, 2, v154
	v_lshlrev_b32_e32 v171, 4, v0
	v_bitop3_b32 v0, v2, v154, 3 bitop3:0x6c
	v_lshlrev_b32_e32 v164, 4, v0
	v_bitop3_b32 v0, v2, v3, 3 bitop3:0x6c
	v_mov_b32_e32 v14, v1
	v_mov_b32_e32 v15, v1
	v_mul_u32_u24_e32 v170, 0x180, v29
	v_lshlrev_b32_e32 v163, 6, v29
	v_lshlrev_b32_e32 v172, 4, v4
	v_lshlrev_b32_e32 v162, 4, v0
	v_mov_b32_e32 v0, v1
	v_mov_b32_e32 v2, v1
	v_mov_b32_e32 v3, v1
	v_mov_b32_e32 v4, v1
	v_mov_b32_e32 v5, v1
	v_mov_b32_e32 v6, v1
	v_mov_b32_e32 v7, v1
	v_mov_b32_e32 v8, v1
	v_mov_b32_e32 v9, v1
	v_mov_b32_e32 v10, v1
	v_mov_b32_e32 v11, v1
	v_mov_b32_e32 v12, v1
	v_mov_b32_e32 v13, v1
	v_mov_b64_e32 v[30:31], v[14:15]
	v_mov_b64_e32 v[46:47], v[14:15]
	v_mov_b64_e32 v[62:63], v[14:15]
	v_mov_b64_e32 v[78:79], v[14:15]
	v_ashrrev_i32_e32 v153, 31, v152
	s_mov_b32 s0, 0
	s_add_i32 s2, s2, 1
	v_mov_b32_e32 v176, 0
	v_mov_b32_e32 v175, 0xf149f2ca
	s_mov_b32 s3, 0
	v_mov_b64_e32 v[28:29], v[12:13]
	v_mov_b64_e32 v[26:27], v[10:11]
	v_mov_b64_e32 v[24:25], v[8:9]
	v_mov_b64_e32 v[22:23], v[6:7]
	v_mov_b64_e32 v[20:21], v[4:5]
	v_mov_b64_e32 v[18:19], v[2:3]
	v_mov_b64_e32 v[16:17], v[0:1]
	v_mov_b64_e32 v[44:45], v[12:13]
	v_mov_b64_e32 v[42:43], v[10:11]
	v_mov_b64_e32 v[40:41], v[8:9]
	v_mov_b64_e32 v[38:39], v[6:7]
	v_mov_b64_e32 v[36:37], v[4:5]
	v_mov_b64_e32 v[34:35], v[2:3]
	v_mov_b64_e32 v[32:33], v[0:1]
	v_mov_b64_e32 v[60:61], v[12:13]
	v_mov_b64_e32 v[58:59], v[10:11]
	v_mov_b64_e32 v[56:57], v[8:9]
	v_mov_b64_e32 v[54:55], v[6:7]
	v_mov_b64_e32 v[52:53], v[4:5]
	v_mov_b64_e32 v[50:51], v[2:3]
	v_mov_b64_e32 v[48:49], v[0:1]
	v_mov_b64_e32 v[76:77], v[12:13]
	v_mov_b64_e32 v[74:75], v[10:11]
	v_mov_b64_e32 v[72:73], v[8:9]
	v_mov_b64_e32 v[70:71], v[6:7]
	v_mov_b64_e32 v[68:69], v[4:5]
	v_mov_b64_e32 v[66:67], v[2:3]
	v_mov_b64_e32 v[64:65], v[0:1]
	v_readlane_b32 s98, v253, 0
	s_nop 3
	s_bitcmp1_b32 s98, 8
	s_cbranch_scc0 .Lmla_prio_lo
	s_setprio 3
; DI void cfence() { asm volatile("" ::: "memory"); }
; #define MFMA32(a, b, c) __builtin_amdgcn_mfma_f32_32x32x16_bf16((a), (b), (c), 0, 0, 0)
; template <int DQK, int DV>
; DI void attn_tile(const bf16_t* Q, int ldq, const bf16_t* Kb, int ldk, const bf16_t* Vt, bf16_t* O, int ldo, int b, int sq0,
;                   int r0a, int r0b, int r1a, int r1b, float m_init, float l_init, char* smem) {
;     ...
;   for (int it = 0; it < nt; ++it) {
;     const int key0 = it < n0 ? r0a + 32 * it : r1a + 32 * (it - n0);
;     const bool masked = it >= n0;
;     {
;       const int itn = (it + 1 < nt) ? it + 1 : it;
;       const int nk0 = itn < n0 ? r0a + 32 * itn : r1a + 32 * (itn - n0);
;       attn_load<DQK, DV>(rk, rv, mp, Kbase, ldk, Vbase, nk0);
;     }
;     cfence();
;     const char* sK = smem + (it & 1) * BUF;
;     const char* sV = sK + KB;
;     f32x16 S;
; #pragma unroll
;     for (int r = 0; r < 16; ++r) S[r] = 0.f;
;     {
;       const char* kr = sK + ql * (DQK * 2);
;       const int f = (ql >> 1) & 7;
; #pragma unroll
;       for (int s = 0; s < NS; ++s) {
;         const int c = 2 * s + hh;
;         const int pc = (c & ~7) | ((c & 7) ^ f);
;         bf16x8 kf = *(const bf16x8*)(kr + pc * 16);
;         S = MFMA32(kf, qf[s], S);
;       }
;     }
;     if (masked) {
; #pragma unroll
;       for (int r = 0; r < 16; ++r) {
;         int ks = key0 + (r & 3) + 8 * (r >> 2) + 4 * hh;
;         int df = ks - qs;
;         if (df > 128 || df < -128) S[r] = -1e30f;
;       }
;     }
;     float mx = S[0];
; #pragma unroll
;     for (int r = 1; r < 16; ++r) mx = fmaxf(mx, S[r]);
;     mx = xhalf_max(mx);
;     const float mn = fmaxf(m, mx);
;     const float alpha = __builtin_amdgcn_exp2f(m - mn);
;     m = mn;
;     float p[16], rsum = 0.f;
; #pragma unroll
;     for (int r = 0; r < 16; ++r) { p[r] = __builtin_amdgcn_exp2f(S[r] - mn); rsum += p[r]; }
;     rsum = xhalf_sum(rsum);
;     lsum = lsum * alpha + rsum;
;     if (__any(alpha != 1.f)) {
; #pragma unroll
;       for (int i = 0; i < NB; ++i)
; #pragma unroll
;         for (int r = 0; r < 16; ++r) acc[i][r] *= alpha;
;     }
.Lmla_prio_lo:
	s_mov_b32 s34, 0
	s_waitcnt lgkmcnt(0)
	s_barrier
.LBB0_407:
	s_add_i32 s0, s0, 64
	s_add_i32 s3, s3, 0x19000
	s_mov_b32 s6, s22
	s_mov_b32 s7, s23
	s_bitcmp1_b32 s34, 0
	buffer_load_dwordx4 v[148:151], v165, s[20:23], s3 offen
	buffer_load_dwordx4 v[10:13], v166, s[20:23], s3 offen
	buffer_load_dwordx4 v[6:9], v167, s[20:23], s3 offen
	buffer_load_dwordx4 v[144:147], v168, s[4:7], s0 offen
	buffer_load_dwordx4 v[2:5], v169, s[4:7], s0 offen
	s_cselect_b32 s6, 0x5000, 0
	v_add_u32_e32 v14, s6, v170
	v_add_u32_e32 v15, v14, v173
	ds_read_b128 v[80:83], v15
	v_mov_b32_e32 v0, v175
	v_add_u32_e32 v175, v14, v174
	ds_read_b128 v[178:181], v175
	v_add_u32_e32 v177, v14, v172
	v_add_u32_e32 v14, v14, v171
	ds_read_b128 v[182:185], v177
	ds_read_b128 v[186:189], v14
	ds_read_b128 v[190:193], v15 offset:128
	s_waitcnt lgkmcnt(4)
	v_mfma_f32_32x32x16_bf16 v[80:95], v[80:83], v[140:143], 0
	s_waitcnt lgkmcnt(3)
	v_mfma_f32_32x32x16_bf16 v[80:95], v[178:181], v[136:139], v[80:95]
	ds_read_b128 v[178:181], v175 offset:128
	s_waitcnt lgkmcnt(3)
	v_mfma_f32_32x32x16_bf16 v[80:95], v[182:185], v[132:135], v[80:95]
	ds_read_b128 v[182:185], v177 offset:128
	s_waitcnt lgkmcnt(3)
	v_mfma_f32_32x32x16_bf16 v[80:95], v[186:189], v[128:131], v[80:95]
	ds_read_b128 v[186:189], v14 offset:128
	s_waitcnt lgkmcnt(3)
	v_mfma_f32_32x32x16_bf16 v[80:95], v[190:193], v[124:127], v[80:95]
	ds_read_b128 v[190:193], v15 offset:256
	s_waitcnt lgkmcnt(3)
	v_mfma_f32_32x32x16_bf16 v[80:95], v[178:181], v[120:123], v[80:95]
	ds_read_b128 v[178:181], v175 offset:256
	s_waitcnt lgkmcnt(3)
	v_mfma_f32_32x32x16_bf16 v[80:95], v[182:185], v[116:119], v[80:95]
	ds_read_b128 v[182:185], v177 offset:256
	s_waitcnt lgkmcnt(3)
	v_mfma_f32_32x32x16_bf16 v[80:95], v[186:189], v[112:115], v[80:95]
	ds_read_b128 v[186:189], v14 offset:256
	s_waitcnt lgkmcnt(3)
	v_mfma_f32_32x32x16_bf16 v[80:95], v[190:193], v[108:111], v[80:95]
	s_waitcnt lgkmcnt(2)
	v_mfma_f32_32x32x16_bf16 v[80:95], v[178:181], v[104:107], v[80:95]
	s_waitcnt lgkmcnt(1)
	v_mfma_f32_32x32x16_bf16 v[80:95], v[182:185], v[100:103], v[80:95]
	s_waitcnt lgkmcnt(0)
	v_mfma_f32_32x32x16_bf16 v[80:95], v[186:189], v[96:99], v[80:95]
	v_add_u32_e32 v244, s6, v163
	v_add_u32_e32 v245, v244, v162
	v_add_u32_e32 v244, v244, v164
	ds_read_b128 v[212:215], v244 offset:12288
	ds_read_b128 v[216:219], v245 offset:12288
	ds_read_b128 v[220:223], v244 offset:14336
	ds_read_b128 v[224:227], v245 offset:14336
	ds_read_b128 v[228:231], v244 offset:16384
	ds_read_b128 v[232:235], v245 offset:16384
	ds_read_b128 v[236:239], v244 offset:18432
	ds_read_b128 v[240:243], v245 offset:18432
	s_nop 0
	v_max_f32_e32 v14, v81, v81
	v_max_f32_e32 v15, v80, v80
	v_max_f32_e32 v14, v15, v14
	v_max3_f32 v14, v14, v82, v83
	v_max3_f32 v14, v14, v84, v85
	v_max3_f32 v14, v14, v86, v87
	v_max3_f32 v14, v14, v88, v89
	v_max3_f32 v14, v14, v90, v91
	v_max3_f32 v14, v14, v92, v93
	v_max3_f32 v14, v14, v94, v95
	v_mov_b32_e32 v15, v14
	s_nop 1
	v_permlane32_swap_b32_e32 v14, v15
	v_max3_f32 v175, v0, v14, v15
	v_sub_f32_e32 v14, v80, v175
	v_exp_f32_e32 v15, v14
	v_sub_f32_e32 v80, v81, v175
	v_exp_f32_e32 v80, v80
	v_sub_f32_e32 v81, v82, v175
	v_exp_f32_e32 v81, v81
	v_sub_f32_e32 v82, v83, v175
	v_exp_f32_e32 v82, v82
	v_sub_f32_e32 v83, v84, v175
	v_add_f32_e32 v14, 0, v15
	v_exp_f32_e32 v83, v83
	v_sub_f32_e32 v84, v85, v175
	v_add_f32_e32 v14, v80, v14
	v_exp_f32_e32 v84, v84
	v_sub_f32_e32 v85, v86, v175
	v_add_f32_e32 v14, v81, v14
	v_exp_f32_e32 v85, v85
	v_sub_f32_e32 v86, v87, v175
	v_add_f32_e32 v14, v82, v14
	v_exp_f32_e32 v86, v86
	v_sub_f32_e32 v87, v88, v175
	v_add_f32_e32 v14, v83, v14
	v_exp_f32_e32 v87, v87
	v_sub_f32_e32 v88, v89, v175
	v_add_f32_e32 v14, v84, v14
	v_exp_f32_e32 v88, v88
	v_sub_f32_e32 v89, v90, v175
	v_add_f32_e32 v14, v85, v14
	v_exp_f32_e32 v89, v89
	v_sub_f32_e32 v90, v91, v175
	v_add_f32_e32 v14, v86, v14
	v_exp_f32_e32 v90, v90
	v_sub_f32_e32 v91, v92, v175
	v_add_f32_e32 v14, v87, v14
	v_exp_f32_e32 v91, v91
	v_sub_f32_e32 v92, v93, v175
	v_add_f32_e32 v14, v88, v14
	v_exp_f32_e32 v92, v92
	v_sub_f32_e32 v93, v94, v175
	v_add_f32_e32 v14, v89, v14
	v_exp_f32_e32 v93, v93
	v_sub_f32_e32 v94, v95, v175
	v_add_f32_e32 v14, v90, v14
	v_exp_f32_e32 v94, v94
	v_sub_f32_e32 v0, v0, v175
	v_add_f32_e32 v14, v91, v14
	v_add_f32_e32 v14, v92, v14
	v_exp_f32_e32 v0, v0
	v_add_f32_e32 v14, v93, v14
	v_add_f32_e32 v14, v94, v14
	v_mov_b32_e32 v95, v14
	s_nop 1
	v_permlane32_swap_b32_e32 v14, v95
	v_cmp_neq_f32_e32 vcc, 1.0, v0
	s_cbranch_vccz .LBB0_409
	v_pk_mul_f32 v[78:79], v[78:79], v[0:1] op_sel_hi:[1,0]
	v_pk_mul_f32 v[76:77], v[76:77], v[0:1] op_sel_hi:[1,0]
	v_pk_mul_f32 v[74:75], v[74:75], v[0:1] op_sel_hi:[1,0]
	v_pk_mul_f32 v[72:73], v[72:73], v[0:1] op_sel_hi:[1,0]
	v_pk_mul_f32 v[70:71], v[70:71], v[0:1] op_sel_hi:[1,0]
	v_pk_mul_f32 v[68:69], v[68:69], v[0:1] op_sel_hi:[1,0]
	v_pk_mul_f32 v[66:67], v[66:67], v[0:1] op_sel_hi:[1,0]
	v_pk_mul_f32 v[64:65], v[64:65], v[0:1] op_sel_hi:[1,0]
	v_pk_mul_f32 v[62:63], v[62:63], v[0:1] op_sel_hi:[1,0]
	v_pk_mul_f32 v[60:61], v[60:61], v[0:1] op_sel_hi:[1,0]
	v_pk_mul_f32 v[58:59], v[58:59], v[0:1] op_sel_hi:[1,0]
	v_pk_mul_f32 v[56:57], v[56:57], v[0:1] op_sel_hi:[1,0]
	v_pk_mul_f32 v[54:55], v[54:55], v[0:1] op_sel_hi:[1,0]
	v_pk_mul_f32 v[52:53], v[52:53], v[0:1] op_sel_hi:[1,0]
	v_pk_mul_f32 v[50:51], v[50:51], v[0:1] op_sel_hi:[1,0]
	v_pk_mul_f32 v[48:49], v[48:49], v[0:1] op_sel_hi:[1,0]
	v_pk_mul_f32 v[46:47], v[46:47], v[0:1] op_sel_hi:[1,0]
	v_pk_mul_f32 v[44:45], v[44:45], v[0:1] op_sel_hi:[1,0]
	v_pk_mul_f32 v[42:43], v[42:43], v[0:1] op_sel_hi:[1,0]
	v_pk_mul_f32 v[40:41], v[40:41], v[0:1] op_sel_hi:[1,0]
	v_pk_mul_f32 v[38:39], v[38:39], v[0:1] op_sel_hi:[1,0]
	v_pk_mul_f32 v[36:37], v[36:37], v[0:1] op_sel_hi:[1,0]
	v_pk_mul_f32 v[34:35], v[34:35], v[0:1] op_sel_hi:[1,0]
	v_pk_mul_f32 v[32:33], v[32:33], v[0:1] op_sel_hi:[1,0]
	v_pk_mul_f32 v[30:31], v[30:31], v[0:1] op_sel_hi:[1,0]
	v_pk_mul_f32 v[28:29], v[28:29], v[0:1] op_sel_hi:[1,0]
	v_pk_mul_f32 v[26:27], v[26:27], v[0:1] op_sel_hi:[1,0]
	v_pk_mul_f32 v[24:25], v[24:25], v[0:1] op_sel_hi:[1,0]
	v_pk_mul_f32 v[22:23], v[22:23], v[0:1] op_sel_hi:[1,0]
	v_pk_mul_f32 v[20:21], v[20:21], v[0:1] op_sel_hi:[1,0]
	v_pk_mul_f32 v[18:19], v[18:19], v[0:1] op_sel_hi:[1,0]
	v_pk_mul_f32 v[16:17], v[16:17], v[0:1] op_sel_hi:[1,0]
; #define MFMA32(a, b, c) __builtin_amdgcn_mfma_f32_32x32x16_bf16((a), (b), (c), 0, 0, 0)
; DI int vswz(int d) { const int g = (d >> 2) & 7; return (g ^ ((g >> 2) * 3)) & 3; }
; template <int DQK, int DV>
; DI void attn_tile(const bf16_t* Q, int ldq, const bf16_t* Kb, int ldk, const bf16_t* Vt, bf16_t* O, int ldo, int b, int sq0,
;                   int r0a, int r0b, int r1a, int r1b, float m_init, float l_init, char* smem) {
;     ...
;     lsum = lsum * alpha + rsum;
;     if (__any(alpha != 1.f)) {
; #pragma unroll
;       for (int i = 0; i < NB; ++i)
; #pragma unroll
;         for (int r = 0; r < 16; ++r) acc[i][r] *= alpha;
;     }
;     bf16x8 pf[2];
; #pragma unroll
;     for (int s2 = 0; s2 < 2; ++s2) {
;       unsigned w0 = pack2(p[8 * s2 + 0], p[8 * s2 + 1]), w1 = pack2(p[8 * s2 + 2], p[8 * s2 + 3]);
;       unsigned w2 = pack2(p[8 * s2 + 4], p[8 * s2 + 5]), w3 = pack2(p[8 * s2 + 6], p[8 * s2 + 7]);
;       uint4 u = {w0, w1, w2, w3};
;       pf[s2] = __builtin_bit_cast(bf16x8, u);
;     }
; #pragma unroll
;     for (int i = 0; i < NB; ++i) {
;       const int d = i * 32 + ql, f = vswz(d);
;       const char* vr = sV + d * 64;
; #pragma unroll
;       for (int s2 = 0; s2 < 2; ++s2) {
;         bf16x8 vf = *(const bf16x8*)(vr + (((2 * s2 + hh) ^ f) << 4));
;         acc[i] = MFMA32(vf, pf[s2], acc[i]);
;       }
;     }
;     {
;       char* dK = smem + ((it + 1) & 1) * BUF;
;       attn_store<DQK, DV>(rk, rv, mp, dK, dK + KB);
;     }
;     __syncthreads();
.LBB0_409:
	v_add_f32_e32 v14, v14, v95
	v_fmac_f32_e32 v14, v176, v0
	v_cvt_pk_bf16_f32 v80, v15, v80
	v_cvt_pk_bf16_f32 v81, v81, v82
	v_cvt_pk_bf16_f32 v82, v83, v84
	v_cvt_pk_bf16_f32 v83, v85, v86
	v_cvt_pk_bf16_f32 v84, v87, v88
	v_cvt_pk_bf16_f32 v85, v89, v90
	v_cvt_pk_bf16_f32 v86, v91, v92
	v_cvt_pk_bf16_f32 v87, v93, v94
	s_add_i32 s34, s34, 1
	s_bitcmp1_b32 s34, 0
	s_cselect_b32 s38, 0x5000, 0
	s_cmp_eq_u32 s2, s34
	s_waitcnt lgkmcnt(0)
	v_mfma_f32_32x32x16_bf16 v[64:79], v[212:215], v[80:83], v[64:79]
	v_add_u32_e32 v0, s38, v155
	s_waitcnt vmcnt(4)
	ds_write_b128 v0, v[148:151]
	v_mfma_f32_32x32x16_bf16 v[64:79], v[216:219], v[84:87], v[64:79]
	v_add_u32_e32 v0, s38, v156
	s_waitcnt vmcnt(3)
	ds_write_b128 v0, v[10:13]
	v_mfma_f32_32x32x16_bf16 v[48:63], v[220:223], v[80:83], v[48:63]
	v_add_u32_e32 v0, s38, v157
	s_waitcnt vmcnt(2)
	ds_write_b128 v0, v[6:9]
	v_mfma_f32_32x32x16_bf16 v[48:63], v[224:227], v[84:87], v[48:63]
	v_add_u32_e32 v0, s38, v160
	s_waitcnt vmcnt(1)
	ds_write_b64 v0, v[144:145] offset:12288
	v_mfma_f32_32x32x16_bf16 v[32:47], v[228:231], v[80:83], v[32:47]
	v_add_u32_e32 v0, s38, v161
	ds_write_b64 v0, v[146:147] offset:12288
	v_mfma_f32_32x32x16_bf16 v[32:47], v[232:235], v[84:87], v[32:47]
	v_add_u32_e32 v0, s38, v158
	s_waitcnt vmcnt(0)
	ds_write_b64 v0, v[2:3] offset:12288
	v_mfma_f32_32x32x16_bf16 v[16:31], v[236:239], v[80:83], v[16:31]
	v_add_u32_e32 v0, s38, v159
	ds_write_b64 v0, v[4:5] offset:12288
	v_mfma_f32_32x32x16_bf16 v[16:31], v[240:243], v[84:87], v[16:31]
	s_waitcnt lgkmcnt(0)
	s_barrier
	s_cbranch_scc1 .LBB0_411
	v_mov_b32_e32 v176, v14
	s_branch .LBB0_407
; DI void cfence() { asm volatile("" ::: "memory"); }
; #define MFMA32(a, b, c) __builtin_amdgcn_mfma_f32_32x32x16_bf16((a), (b), (c), 0, 0, 0)
; template <int DQK, int DV>
; DI void attn_tile(const bf16_t* Q, int ldq, const bf16_t* Kb, int ldk, const bf16_t* Vt, bf16_t* O, int ldo, int b, int sq0,
;                   int r0a, int r0b, int r1a, int r1b, float m_init, float l_init, char* smem) {
;     ...
;   for (int it = 0; it < nt; ++it) {
;     const int key0 = it < n0 ? r0a + 32 * it : r1a + 32 * (it - n0);
;     const bool masked = it >= n0;
;     {
;       const int itn = (it + 1 < nt) ? it + 1 : it;
;       const int nk0 = itn < n0 ? r0a + 32 * itn : r1a + 32 * (itn - n0);
;       attn_load<DQK, DV>(rk, rv, mp, Kbase, ldk, Vbase, nk0);
;     }
;     cfence();
;     const char* sK = smem + (it & 1) * BUF;
;     const char* sV = sK + KB;
;     f32x16 S;
; #pragma unroll
;     for (int r = 0; r < 16; ++r) S[r] = 0.f;
;     {
;       const char* kr = sK + ql * (DQK * 2);
;       const int f = (ql >> 1) & 7;
; #pragma unroll
;       for (int s = 0; s < NS; ++s) {
;         const int c = 2 * s + hh;
;         const int pc = (c & ~7) | ((c & 7) ^ f);
;         bf16x8 kf = *(const bf16x8*)(kr + pc * 16);
;         S = MFMA32(kf, qf[s], S);
;       }
;     }
;     if (masked) {
; #pragma unroll
;       for (int r = 0; r < 16; ++r) {
;         int ks = key0 + (r & 3) + 8 * (r >> 2) + 4 * hh;
;         int df = ks - qs;
;         if (df > 128 || df < -128) S[r] = -1e30f;
;       }
;     }
;     float mx = S[0];
; #pragma unroll
;     for (int r = 1; r < 16; ++r) mx = fmaxf(mx, S[r]);
;     mx = xhalf_max(mx);
;     const float mn = fmaxf(m, mx);
;     const float alpha = __builtin_amdgcn_exp2f(m - mn);
;     m = mn;
;     float p[16], rsum = 0.f;
; #pragma unroll
;     for (int r = 0; r < 16; ++r) { p[r] = __builtin_amdgcn_exp2f(S[r] - mn); rsum += p[r]; }
;     rsum = xhalf_sum(rsum);
;     lsum = lsum * alpha + rsum;
;     if (__any(alpha != 1.f)) {
; #pragma unroll
;       for (int i = 0; i < NB; ++i)
; #pragma unroll
;         for (int r = 0; r < 16; ++r) acc[i][r] *= alpha;
;     }
.LBB0_411:
	s_setprio 0
	s_mov_b32 s6, s22
	s_mov_b32 s7, s23
	v_add_u32_e32 v0, s38, v170
	buffer_load_dwordx4 v[6:9], v165, s[20:23], s3 offen
	buffer_load_dwordx4 v[10:13], v166, s[20:23], s3 offen
	buffer_load_dwordx4 v[144:147], v167, s[20:23], s3 offen
	buffer_load_dwordx4 v[148:151], v168, s[4:7], s0 offen
	buffer_load_dwordx4 v[2:5], v169, s[4:7], s0 offen
	v_add_u32_e32 v15, v0, v173
	ds_read_b128 v[80:83], v15
	v_add_u32_e32 v165, v0, v174
	s_waitcnt lgkmcnt(0)
	v_mfma_f32_32x32x16_bf16 v[80:95], v[80:83], v[140:143], 0
	ds_read_b128 v[140:143], v165
	s_waitcnt lgkmcnt(0)
	v_mfma_f32_32x32x16_bf16 v[80:95], v[140:143], v[136:139], v[80:95]
	v_add_u32_e32 v140, v0, v172
	ds_read_b128 v[136:139], v140
	v_add_u32_e32 v0, v0, v171
	s_waitcnt lgkmcnt(0)
	v_mfma_f32_32x32x16_bf16 v[80:95], v[136:139], v[132:135], v[80:95]
	ds_read_b128 v[132:135], v0
	s_waitcnt lgkmcnt(0)
	v_mfma_f32_32x32x16_bf16 v[80:95], v[132:135], v[128:131], v[80:95]
	ds_read_b128 v[128:131], v15 offset:128
	s_waitcnt lgkmcnt(0)
	v_mfma_f32_32x32x16_bf16 v[80:95], v[128:131], v[124:127], v[80:95]
	ds_read_b128 v[124:127], v165 offset:128
	s_waitcnt lgkmcnt(0)
	v_mfma_f32_32x32x16_bf16 v[80:95], v[124:127], v[120:123], v[80:95]
	ds_read_b128 v[120:123], v140 offset:128
	s_waitcnt lgkmcnt(0)
	v_mfma_f32_32x32x16_bf16 v[80:95], v[120:123], v[116:119], v[80:95]
	ds_read_b128 v[116:119], v0 offset:128
	s_waitcnt lgkmcnt(0)
	v_mfma_f32_32x32x16_bf16 v[80:95], v[116:119], v[112:115], v[80:95]
	ds_read_b128 v[112:115], v15 offset:256
	s_waitcnt lgkmcnt(0)
	v_mfma_f32_32x32x16_bf16 v[80:95], v[112:115], v[108:111], v[80:95]
	ds_read_b128 v[108:111], v165 offset:256
	s_waitcnt lgkmcnt(0)
	v_mfma_f32_32x32x16_bf16 v[80:95], v[108:111], v[104:107], v[80:95]
	ds_read_b128 v[104:107], v140 offset:256
	s_waitcnt lgkmcnt(0)
	v_mfma_f32_32x32x16_bf16 v[80:95], v[104:107], v[100:103], v[80:95]
	ds_read_b128 v[100:103], v0 offset:256
	s_waitcnt lgkmcnt(0)
	v_mfma_f32_32x32x16_bf16 v[80:95], v[100:103], v[96:99], v[80:95]
	s_nop 11
	v_max_f32_e32 v0, v81, v81
	v_max_f32_e32 v15, v80, v80
	v_max_f32_e32 v0, v15, v0
	v_max3_f32 v0, v0, v82, v83
	v_max3_f32 v0, v0, v84, v85
	v_max3_f32 v0, v0, v86, v87
	v_max3_f32 v0, v0, v88, v89
	v_max3_f32 v0, v0, v90, v91
	v_max3_f32 v0, v0, v92, v93
	v_max3_f32 v0, v0, v94, v95
	v_mov_b32_e32 v15, v0
	s_nop 1
	v_permlane32_swap_b32_e32 v0, v15
	v_max3_f32 v0, v175, v0, v15
	v_sub_f32_e32 v15, v80, v0
	v_exp_f32_e32 v80, v15
	v_sub_f32_e32 v81, v81, v0
	v_exp_f32_e32 v96, v81
	v_sub_f32_e32 v81, v82, v0
	v_exp_f32_e32 v82, v81
	v_sub_f32_e32 v81, v83, v0
	v_exp_f32_e32 v83, v81
	v_sub_f32_e32 v81, v84, v0
	v_add_f32_e32 v15, 0, v80
	v_exp_f32_e32 v84, v81
	v_sub_f32_e32 v81, v85, v0
	v_add_f32_e32 v15, v96, v15
	v_exp_f32_e32 v85, v81
	v_sub_f32_e32 v81, v86, v0
	v_add_f32_e32 v15, v82, v15
	v_exp_f32_e32 v86, v81
	v_sub_f32_e32 v81, v87, v0
	v_add_f32_e32 v15, v83, v15
	v_exp_f32_e32 v87, v81
	v_sub_f32_e32 v81, v88, v0
	v_add_f32_e32 v15, v84, v15
	v_exp_f32_e32 v88, v81
	v_sub_f32_e32 v81, v89, v0
	v_add_f32_e32 v15, v85, v15
	v_exp_f32_e32 v89, v81
	v_sub_f32_e32 v81, v90, v0
	v_add_f32_e32 v15, v86, v15
	v_exp_f32_e32 v90, v81
	v_sub_f32_e32 v81, v91, v0
	v_add_f32_e32 v15, v87, v15
	v_exp_f32_e32 v91, v81
	v_sub_f32_e32 v81, v92, v0
	v_add_f32_e32 v15, v88, v15
	v_exp_f32_e32 v92, v81
	v_sub_f32_e32 v81, v93, v0
	v_add_f32_e32 v15, v89, v15
	v_exp_f32_e32 v93, v81
	v_sub_f32_e32 v81, v94, v0
	v_sub_f32_e32 v97, v175, v0
	v_add_f32_e32 v15, v90, v15
	v_exp_f32_e32 v94, v81
	v_sub_f32_e32 v0, v95, v0
	v_add_f32_e32 v15, v91, v15
	v_exp_f32_e32 v95, v0
	v_add_f32_e32 v15, v92, v15
	v_add_f32_e32 v15, v93, v15
	v_exp_f32_e32 v0, v97
	v_add_f32_e32 v15, v94, v15
	v_add_f32_e32 v15, v95, v15
	v_mov_b32_e32 v81, v15
	s_nop 1
	v_permlane32_swap_b32_e32 v15, v81
	v_cmp_neq_f32_e32 vcc, 1.0, v0
	s_cbranch_vccz .LBB0_380
	v_pk_mul_f32 v[78:79], v[78:79], v[0:1] op_sel_hi:[1,0]
	v_pk_mul_f32 v[76:77], v[76:77], v[0:1] op_sel_hi:[1,0]
	v_pk_mul_f32 v[74:75], v[74:75], v[0:1] op_sel_hi:[1,0]
	v_pk_mul_f32 v[72:73], v[72:73], v[0:1] op_sel_hi:[1,0]
	v_pk_mul_f32 v[70:71], v[70:71], v[0:1] op_sel_hi:[1,0]
	v_pk_mul_f32 v[68:69], v[68:69], v[0:1] op_sel_hi:[1,0]
	v_pk_mul_f32 v[66:67], v[66:67], v[0:1] op_sel_hi:[1,0]
	v_pk_mul_f32 v[64:65], v[64:65], v[0:1] op_sel_hi:[1,0]
	v_pk_mul_f32 v[62:63], v[62:63], v[0:1] op_sel_hi:[1,0]
	v_pk_mul_f32 v[60:61], v[60:61], v[0:1] op_sel_hi:[1,0]
	v_pk_mul_f32 v[58:59], v[58:59], v[0:1] op_sel_hi:[1,0]
	v_pk_mul_f32 v[56:57], v[56:57], v[0:1] op_sel_hi:[1,0]
	v_pk_mul_f32 v[54:55], v[54:55], v[0:1] op_sel_hi:[1,0]
	v_pk_mul_f32 v[52:53], v[52:53], v[0:1] op_sel_hi:[1,0]
	v_pk_mul_f32 v[50:51], v[50:51], v[0:1] op_sel_hi:[1,0]
	v_pk_mul_f32 v[48:49], v[48:49], v[0:1] op_sel_hi:[1,0]
	v_pk_mul_f32 v[46:47], v[46:47], v[0:1] op_sel_hi:[1,0]
	v_pk_mul_f32 v[44:45], v[44:45], v[0:1] op_sel_hi:[1,0]
	v_pk_mul_f32 v[42:43], v[42:43], v[0:1] op_sel_hi:[1,0]
	v_pk_mul_f32 v[40:41], v[40:41], v[0:1] op_sel_hi:[1,0]
	v_pk_mul_f32 v[38:39], v[38:39], v[0:1] op_sel_hi:[1,0]
	v_pk_mul_f32 v[36:37], v[36:37], v[0:1] op_sel_hi:[1,0]
	v_pk_mul_f32 v[34:35], v[34:35], v[0:1] op_sel_hi:[1,0]
	v_pk_mul_f32 v[32:33], v[32:33], v[0:1] op_sel_hi:[1,0]
	v_pk_mul_f32 v[30:31], v[30:31], v[0:1] op_sel_hi:[1,0]
	v_pk_mul_f32 v[28:29], v[28:29], v[0:1] op_sel_hi:[1,0]
	v_pk_mul_f32 v[26:27], v[26:27], v[0:1] op_sel_hi:[1,0]
	v_pk_mul_f32 v[24:25], v[24:25], v[0:1] op_sel_hi:[1,0]
	v_pk_mul_f32 v[22:23], v[22:23], v[0:1] op_sel_hi:[1,0]
	v_pk_mul_f32 v[20:21], v[20:21], v[0:1] op_sel_hi:[1,0]
	v_pk_mul_f32 v[18:19], v[18:19], v[0:1] op_sel_hi:[1,0]
	v_pk_mul_f32 v[16:17], v[16:17], v[0:1] op_sel_hi:[1,0]
	s_branch .LBB0_380

; DI void cfence() { asm volatile("" ::: "memory"); }
; DI int swz4(int row) { const int g = (row >> 2) & 3; return ((g << 1) ^ ((g >> 1) * 3)) & 3; }
; #define LSTORE2(RA, RB, P)                                       \
;   {                                                              \
;     char* dA_ = smem + (P) * 24576 + wofs;                       \
;     _Pragma("unroll") for (int j = 0; j < 4; ++j) *(u32x4*)(dA_ + j * 4096) = RA[j]; \
;     _Pragma("unroll") for (int j = 0; j < 2; ++j) *(u32x4*)(dA_ + 16384 + j * 4096) = RB[j]; \
;   }
; DI void gemm256_kloop(f32x4 (&acc)[8][4], const bf16_t* __restrict__ A, int lda, const bf16_t* __restrict__ Bt, int ldb,
;                       int K, int b, int s0, int col0, char* smem) {
;     ...
;   GLOAD2(xa, xb, 0);
;   GLOAD2(ya, yb, 1);
;   cfence();
;   LSTORE2(xa, xb, 0);
;   __syncthreads();
;   const int co = ((fq ^ swz4(fr)) << 4);
;   const int aofs = (wr * 128 + fr) * 64 + co, bofs = (wc * 64 + fr) * 64 + co;
;   for (int kt = 0; kt < nk; kt += 2) {
;     GLOAD2(xa, xb, kt + 2);
;     cfence();
;     COMPUTE2(0);
;     LSTORE2(ya, yb, 1);
;     __syncthreads();
;     if (kt + 1 < nk) {
;       GLOAD2(ya, yb, kt + 3);
;       cfence();
;       COMPUTE2(1);
;       LSTORE2(xa, xb, 0);
;       __syncthreads();
.LBB0_425:
	s_add_i32 s26, s11, 2
	s_cmp_lt_u32 s11, 14
	s_cselect_b64 s[50:51], -1, 0
	s_and_b64 vcc, s[50:51], exec
	s_cselect_b32 s27, s10, 0x3c0
	buffer_load_dwordx4 v[162:165], v0, s[12:15], s27 offen
	buffer_load_dwordx4 v[166:169], v154, s[12:15], s27 offen
	buffer_load_dwordx4 v[170:173], v155, s[12:15], s27 offen
	buffer_load_dwordx4 v[174:177], v156, s[12:15], s27 offen
	buffer_load_dwordx4 v[178:181], v157, s[16:19], s27 offen
	buffer_load_dwordx4 v[182:185], v158, s[16:19], s27 offen
	ds_read_b128 v[236:239], v160 offset:16384
	ds_read_b128 v[240:243], v160 offset:17408
	ds_read_b128 v[244:247], v160 offset:18432
	ds_read_b128 v[248:251], v160 offset:19456
	ds_read_b128 v[186:189], v161
	ds_read_b128 v[190:193], v161 offset:1024
	ds_read_b128 v[212:215], v161 offset:2048
	ds_read_b128 v[216:219], v161 offset:3072
	ds_read_b128 v[220:223], v161 offset:4096
	ds_read_b128 v[224:227], v161 offset:5120
	ds_read_b128 v[228:231], v161 offset:6144
	ds_read_b128 v[232:235], v161 offset:7168
	s_setprio 1
	s_waitcnt lgkmcnt(7)
	v_mfma_f32_16x16x32_bf16 v[126:129], v[186:189], v[236:239], v[126:129]
	v_mfma_f32_16x16x32_bf16 v[122:125], v[186:189], v[240:243], v[122:125]
	v_mfma_f32_16x16x32_bf16 v[118:121], v[186:189], v[244:247], v[118:121]
	v_mfma_f32_16x16x32_bf16 v[114:117], v[186:189], v[248:251], v[114:117]
	s_waitcnt lgkmcnt(6)
	v_mfma_f32_16x16x32_bf16 v[110:113], v[190:193], v[236:239], v[110:113]
	v_mfma_f32_16x16x32_bf16 v[106:109], v[190:193], v[240:243], v[106:109]
	v_mfma_f32_16x16x32_bf16 v[102:105], v[190:193], v[244:247], v[102:105]
	v_mfma_f32_16x16x32_bf16 v[98:101], v[190:193], v[248:251], v[98:101]
	s_waitcnt lgkmcnt(5)
	v_mfma_f32_16x16x32_bf16 v[94:97], v[212:215], v[236:239], v[94:97]
	v_mfma_f32_16x16x32_bf16 v[90:93], v[212:215], v[240:243], v[90:93]
	v_mfma_f32_16x16x32_bf16 v[86:89], v[212:215], v[244:247], v[86:89]
	v_mfma_f32_16x16x32_bf16 v[82:85], v[212:215], v[248:251], v[82:85]
	s_waitcnt lgkmcnt(4)
	v_mfma_f32_16x16x32_bf16 v[78:81], v[216:219], v[236:239], v[78:81]
	v_mfma_f32_16x16x32_bf16 v[74:77], v[216:219], v[240:243], v[74:77]
	v_mfma_f32_16x16x32_bf16 v[70:73], v[216:219], v[244:247], v[70:73]
	v_mfma_f32_16x16x32_bf16 v[66:69], v[216:219], v[248:251], v[66:69]
	s_waitcnt lgkmcnt(3)
	v_mfma_f32_16x16x32_bf16 v[62:65], v[220:223], v[236:239], v[62:65]
	v_mfma_f32_16x16x32_bf16 v[58:61], v[220:223], v[240:243], v[58:61]
	s_waitcnt vmcnt(9)
	ds_write_b128 v159, v[138:141] offset:24576
	v_mfma_f32_16x16x32_bf16 v[54:57], v[220:223], v[244:247], v[54:57]
	v_mfma_f32_16x16x32_bf16 v[50:53], v[220:223], v[248:251], v[50:53]
	s_waitcnt vmcnt(8)
	ds_write_b128 v159, v[142:145] offset:28672
	s_waitcnt lgkmcnt(4)
	v_mfma_f32_16x16x32_bf16 v[46:49], v[224:227], v[236:239], v[46:49]
	v_mfma_f32_16x16x32_bf16 v[42:45], v[224:227], v[240:243], v[42:45]
	s_waitcnt vmcnt(7)
	ds_write_b128 v159, v[146:149] offset:32768
	v_mfma_f32_16x16x32_bf16 v[38:41], v[224:227], v[244:247], v[38:41]
	v_mfma_f32_16x16x32_bf16 v[34:37], v[224:227], v[248:251], v[34:37]
	s_waitcnt vmcnt(6)
	ds_write_b128 v159, v[150:153] offset:36864
	s_waitcnt lgkmcnt(5)
	v_mfma_f32_16x16x32_bf16 v[30:33], v[228:231], v[236:239], v[30:33]
	v_mfma_f32_16x16x32_bf16 v[26:29], v[228:231], v[240:243], v[26:29]
	ds_write_b128 v159, v[130:133] offset:40960
	v_mfma_f32_16x16x32_bf16 v[22:25], v[228:231], v[244:247], v[22:25]
	v_mfma_f32_16x16x32_bf16 v[18:21], v[228:231], v[248:251], v[18:21]
	ds_write_b128 v159, v[134:137] offset:45056
	s_waitcnt lgkmcnt(6)
	v_mfma_f32_16x16x32_bf16 v[14:17], v[232:235], v[236:239], v[14:17]
	v_mfma_f32_16x16x32_bf16 v[10:13], v[232:235], v[240:243], v[10:13]
	v_mfma_f32_16x16x32_bf16 v[6:9], v[232:235], v[244:247], v[6:9]
	v_mfma_f32_16x16x32_bf16 v[2:5], v[232:235], v[248:251], v[2:5]
	s_setprio 0
	s_min_u32 s11, s11, 12
	s_lshl_b32 s11, s11, 6
	s_addk_i32 s11, 0xc0
	s_waitcnt lgkmcnt(0)
	s_barrier
; DI int bidx() { int t = __builtin_amdgcn_workgroup_id_x(); asm volatile("" : "+s"(t)); return t; }
; DI int gdim() { int t = (int)__ockl_get_num_groups(0); asm volatile("" : "+s"(t)); return t; }
; DI void cfence() { asm volatile("" ::: "memory"); }
; DI int swz4(int row) { const int g = (row >> 2) & 3; return ((g << 1) ^ ((g >> 1) * 3)) & 3; }
; #define LSTORE2(RA, RB, P)                                       \
;   {                                                              \
;     char* dA_ = smem + (P) * 24576 + wofs;                       \
;     _Pragma("unroll") for (int j = 0; j < 4; ++j) *(u32x4*)(dA_ + j * 4096) = RA[j]; \
;     _Pragma("unroll") for (int j = 0; j < 2; ++j) *(u32x4*)(dA_ + 16384 + j * 4096) = RB[j]; \
;   }
; DI void gemm256_kloop(f32x4 (&acc)[8][4], const bf16_t* __restrict__ A, int lda, const bf16_t* __restrict__ Bt, int ldb,
;                       int K, int b, int s0, int col0, char* smem) {
;     ...
;   GLOAD2(xa, xb, 0);
;   GLOAD2(ya, yb, 1);
;   cfence();
;   LSTORE2(xa, xb, 0);
;   __syncthreads();
;   const int co = ((fq ^ swz4(fr)) << 4);
;   const int aofs = (wr * 128 + fr) * 64 + co, bofs = (wc * 64 + fr) * 64 + co;
;   for (int kt = 0; kt < nk; kt += 2) {
;     GLOAD2(xa, xb, kt + 2);
;     cfence();
;     COMPUTE2(0);
;     LSTORE2(ya, yb, 1);
;     __syncthreads();
;     if (kt + 1 < nk) {
;       GLOAD2(ya, yb, kt + 3);
;       cfence();
;       COMPUTE2(1);
;       LSTORE2(xa, xb, 0);
;       __syncthreads();
; DI void phase_uproj(const Params& P, int l, char* smem) {
;     ...
;   const int nq = 130 * 12, nkv = 130 * 16;
;   for (int it = bidx(); it < nq + nkv; it += gdim()) {
;     if (it < nq) {
;       EpiUQ e{(bf16_t*)(Bg + B_QMLA), ssq, cs, sn};
;       gemm256_item_plain(Z, 1088, (const bf16_t*)(W + W_UQ), LDUQ, 512, 12, smem, e, it);
;     } else {
;       EpiUKV e{Kd, (bf16_t*)(Bg + B_VTMLA), ssq};
;       gemm256_item_plain(Z + 512, 1088, (const bf16_t*)(W + W_UKV), LDUQ, 512, 16, smem, e, it - nq);
;     }
	buffer_load_dwordx4 v[138:141], v0, s[12:15], s11 offen
	buffer_load_dwordx4 v[142:145], v154, s[12:15], s11 offen
	buffer_load_dwordx4 v[146:149], v155, s[12:15], s11 offen
	buffer_load_dwordx4 v[150:153], v156, s[12:15], s11 offen
	buffer_load_dwordx4 v[130:133], v157, s[16:19], s11 offen
	buffer_load_dwordx4 v[134:137], v158, s[16:19], s11 offen
	ds_read_b128 v[236:239], v160 offset:40960
	ds_read_b128 v[240:243], v160 offset:41984
	ds_read_b128 v[244:247], v160 offset:43008
	ds_read_b128 v[248:251], v160 offset:44032
	ds_read_b128 v[186:189], v161 offset:24576
	ds_read_b128 v[190:193], v161 offset:25600
	ds_read_b128 v[212:215], v161 offset:26624
	ds_read_b128 v[216:219], v161 offset:27648
	ds_read_b128 v[220:223], v161 offset:28672
	ds_read_b128 v[224:227], v161 offset:29696
	ds_read_b128 v[228:231], v161 offset:30720
	ds_read_b128 v[232:235], v161 offset:31744
	s_setprio 1
	s_waitcnt lgkmcnt(7)
	v_mfma_f32_16x16x32_bf16 v[126:129], v[186:189], v[236:239], v[126:129]
	v_mfma_f32_16x16x32_bf16 v[122:125], v[186:189], v[240:243], v[122:125]
	v_mfma_f32_16x16x32_bf16 v[118:121], v[186:189], v[244:247], v[118:121]
	v_mfma_f32_16x16x32_bf16 v[114:117], v[186:189], v[248:251], v[114:117]
	s_waitcnt lgkmcnt(6)
	v_mfma_f32_16x16x32_bf16 v[110:113], v[190:193], v[236:239], v[110:113]
	v_mfma_f32_16x16x32_bf16 v[106:109], v[190:193], v[240:243], v[106:109]
	v_mfma_f32_16x16x32_bf16 v[102:105], v[190:193], v[244:247], v[102:105]
	v_mfma_f32_16x16x32_bf16 v[98:101], v[190:193], v[248:251], v[98:101]
	s_waitcnt lgkmcnt(5)
	v_mfma_f32_16x16x32_bf16 v[94:97], v[212:215], v[236:239], v[94:97]
	v_mfma_f32_16x16x32_bf16 v[90:93], v[212:215], v[240:243], v[90:93]
	v_mfma_f32_16x16x32_bf16 v[86:89], v[212:215], v[244:247], v[86:89]
	v_mfma_f32_16x16x32_bf16 v[82:85], v[212:215], v[248:251], v[82:85]
	s_waitcnt lgkmcnt(4)
	v_mfma_f32_16x16x32_bf16 v[78:81], v[216:219], v[236:239], v[78:81]
	v_mfma_f32_16x16x32_bf16 v[74:77], v[216:219], v[240:243], v[74:77]
	v_mfma_f32_16x16x32_bf16 v[70:73], v[216:219], v[244:247], v[70:73]
	v_mfma_f32_16x16x32_bf16 v[66:69], v[216:219], v[248:251], v[66:69]
	s_waitcnt lgkmcnt(3)
	v_mfma_f32_16x16x32_bf16 v[62:65], v[220:223], v[236:239], v[62:65]
	v_mfma_f32_16x16x32_bf16 v[58:61], v[220:223], v[240:243], v[58:61]
	s_waitcnt vmcnt(11)
	ds_write_b128 v159, v[162:165]
	v_mfma_f32_16x16x32_bf16 v[54:57], v[220:223], v[244:247], v[54:57]
	v_mfma_f32_16x16x32_bf16 v[50:53], v[220:223], v[248:251], v[50:53]
	s_waitcnt vmcnt(10)
	ds_write_b128 v159, v[166:169] offset:4096
	s_waitcnt lgkmcnt(4)
	v_mfma_f32_16x16x32_bf16 v[46:49], v[224:227], v[236:239], v[46:49]
	v_mfma_f32_16x16x32_bf16 v[42:45], v[224:227], v[240:243], v[42:45]
	s_waitcnt vmcnt(9)
	ds_write_b128 v159, v[170:173] offset:8192
	v_mfma_f32_16x16x32_bf16 v[38:41], v[224:227], v[244:247], v[38:41]
	v_mfma_f32_16x16x32_bf16 v[34:37], v[224:227], v[248:251], v[34:37]
	s_waitcnt vmcnt(8)
	ds_write_b128 v159, v[174:177] offset:12288
	s_waitcnt lgkmcnt(5)
	v_mfma_f32_16x16x32_bf16 v[30:33], v[228:231], v[236:239], v[30:33]
	v_mfma_f32_16x16x32_bf16 v[26:29], v[228:231], v[240:243], v[26:29]
	s_waitcnt vmcnt(7)
	ds_write_b128 v159, v[178:181] offset:16384
	v_mfma_f32_16x16x32_bf16 v[22:25], v[228:231], v[244:247], v[22:25]
	v_mfma_f32_16x16x32_bf16 v[18:21], v[228:231], v[248:251], v[18:21]
	s_waitcnt vmcnt(6)
	ds_write_b128 v159, v[182:185] offset:20480
	s_waitcnt lgkmcnt(6)
	v_mfma_f32_16x16x32_bf16 v[14:17], v[232:235], v[236:239], v[14:17]
	v_mfma_f32_16x16x32_bf16 v[10:13], v[232:235], v[240:243], v[10:13]
	v_mfma_f32_16x16x32_bf16 v[6:9], v[232:235], v[244:247], v[6:9]
	v_mfma_f32_16x16x32_bf16 v[2:5], v[232:235], v[248:251], v[2:5]
	s_setprio 0
	s_addk_i32 s10, 0x80
	s_mov_b32 s11, s26
	s_waitcnt lgkmcnt(0)
	s_barrier
	s_cbranch_vccnz .LBB0_425
	s_bitcmp1_b32 s34, 0
	s_cselect_b64 s[14:15], -1, 0
	s_and_b64 s[10:11], s[2:3], exec
	s_cselect_b32 s10, 0x400, 0
	s_lshr_b32 s5, s5, 1
	s_and_b32 s5, s5, 0x380
	s_or_b32 s10, s10, s5
	s_and_b64 s[2:3], s[2:3], exec
	s_cselect_b32 s11, 0x4100, 0
	s_bfe_u32 s2, s4, 0x30008
	s_mulk_i32 s2, 0x180
	s_add_u32 s18, s48, s2
	s_mov_b32 s50, 0
	s_addc_u32 s19, s49, 0
	s_mov_b64 s[26:27], -1
	s_branch .LBB0_429

; DI void cfence() { asm volatile("" ::: "memory"); }
; DI int swz4(int row) { const int g = (row >> 2) & 3; return ((g << 1) ^ ((g >> 1) * 3)) & 3; }
; #define LSTORE2(RA, RB, P)                                       \
;   {                                                              \
;     char* dA_ = smem + (P) * 24576 + wofs;                       \
;     _Pragma("unroll") for (int j = 0; j < 4; ++j) *(u32x4*)(dA_ + j * 4096) = RA[j]; \
;     _Pragma("unroll") for (int j = 0; j < 2; ++j) *(u32x4*)(dA_ + 16384 + j * 4096) = RB[j]; \
;   }
; DI void gemm256_kloop(f32x4 (&acc)[8][4], const bf16_t* __restrict__ A, int lda, const bf16_t* __restrict__ Bt, int ldb,
;                       int K, int b, int s0, int col0, char* smem) {
;     ...
;   GLOAD2(xa, xb, 0);
;   GLOAD2(ya, yb, 1);
;   cfence();
;   LSTORE2(xa, xb, 0);
;   __syncthreads();
;   const int co = ((fq ^ swz4(fr)) << 4);
;   const int aofs = (wr * 128 + fr) * 64 + co, bofs = (wc * 64 + fr) * 64 + co;
;   for (int kt = 0; kt < nk; kt += 2) {
;     GLOAD2(xa, xb, kt + 2);
;     cfence();
;     COMPUTE2(0);
;     LSTORE2(ya, yb, 1);
;     __syncthreads();
;     if (kt + 1 < nk) {
;       GLOAD2(ya, yb, kt + 3);
;       cfence();
;       COMPUTE2(1);
;       LSTORE2(xa, xb, 0);
;       __syncthreads();
;     }
;   }
.LBB0_440:
	s_add_i32 s11, s9, 2
	s_cmp_lt_u32 s9, 14
	s_cselect_b64 s[14:15], -1, 0
	s_and_b64 vcc, s[14:15], exec
	s_cselect_b32 s14, s8, 0x3c0
	buffer_load_dwordx4 v[162:165], v0, s[20:23], s14 offen
	buffer_load_dwordx4 v[166:169], v154, s[20:23], s14 offen
	buffer_load_dwordx4 v[170:173], v155, s[20:23], s14 offen
	buffer_load_dwordx4 v[174:177], v156, s[20:23], s14 offen
	buffer_load_dwordx4 v[178:181], v157, s[24:27], s14 offen
	buffer_load_dwordx4 v[182:185], v158, s[24:27], s14 offen
	ds_read_b128 v[236:239], v160 offset:16384
	ds_read_b128 v[240:243], v160 offset:17408
	ds_read_b128 v[244:247], v160 offset:18432
	ds_read_b128 v[248:251], v160 offset:19456
	ds_read_b128 v[186:189], v161
	ds_read_b128 v[190:193], v161 offset:1024
	ds_read_b128 v[212:215], v161 offset:2048
	ds_read_b128 v[216:219], v161 offset:3072
	ds_read_b128 v[220:223], v161 offset:4096
	ds_read_b128 v[224:227], v161 offset:5120
	ds_read_b128 v[228:231], v161 offset:6144
	ds_read_b128 v[232:235], v161 offset:7168
	s_setprio 1
	s_waitcnt lgkmcnt(7)
	v_mfma_f32_16x16x32_bf16 v[126:129], v[186:189], v[236:239], v[126:129]
	v_mfma_f32_16x16x32_bf16 v[122:125], v[186:189], v[240:243], v[122:125]
	v_mfma_f32_16x16x32_bf16 v[118:121], v[186:189], v[244:247], v[118:121]
	v_mfma_f32_16x16x32_bf16 v[114:117], v[186:189], v[248:251], v[114:117]
	s_waitcnt lgkmcnt(6)
	v_mfma_f32_16x16x32_bf16 v[110:113], v[190:193], v[236:239], v[110:113]
	v_mfma_f32_16x16x32_bf16 v[106:109], v[190:193], v[240:243], v[106:109]
	v_mfma_f32_16x16x32_bf16 v[102:105], v[190:193], v[244:247], v[102:105]
	v_mfma_f32_16x16x32_bf16 v[98:101], v[190:193], v[248:251], v[98:101]
	s_waitcnt lgkmcnt(5)
	v_mfma_f32_16x16x32_bf16 v[94:97], v[212:215], v[236:239], v[94:97]
	v_mfma_f32_16x16x32_bf16 v[90:93], v[212:215], v[240:243], v[90:93]
	v_mfma_f32_16x16x32_bf16 v[86:89], v[212:215], v[244:247], v[86:89]
	v_mfma_f32_16x16x32_bf16 v[82:85], v[212:215], v[248:251], v[82:85]
	s_waitcnt lgkmcnt(4)
	v_mfma_f32_16x16x32_bf16 v[78:81], v[216:219], v[236:239], v[78:81]
	v_mfma_f32_16x16x32_bf16 v[74:77], v[216:219], v[240:243], v[74:77]
	v_mfma_f32_16x16x32_bf16 v[70:73], v[216:219], v[244:247], v[70:73]
	v_mfma_f32_16x16x32_bf16 v[66:69], v[216:219], v[248:251], v[66:69]
	s_waitcnt lgkmcnt(3)
	v_mfma_f32_16x16x32_bf16 v[62:65], v[220:223], v[236:239], v[62:65]
	v_mfma_f32_16x16x32_bf16 v[58:61], v[220:223], v[240:243], v[58:61]
	s_waitcnt vmcnt(9)
	ds_write_b128 v159, v[138:141] offset:24576
	v_mfma_f32_16x16x32_bf16 v[54:57], v[220:223], v[244:247], v[54:57]
	v_mfma_f32_16x16x32_bf16 v[50:53], v[220:223], v[248:251], v[50:53]
	s_waitcnt vmcnt(8)
	ds_write_b128 v159, v[142:145] offset:28672
	s_waitcnt lgkmcnt(4)
	v_mfma_f32_16x16x32_bf16 v[46:49], v[224:227], v[236:239], v[46:49]
	v_mfma_f32_16x16x32_bf16 v[42:45], v[224:227], v[240:243], v[42:45]
	s_waitcnt vmcnt(7)
	ds_write_b128 v159, v[146:149] offset:32768
	v_mfma_f32_16x16x32_bf16 v[38:41], v[224:227], v[244:247], v[38:41]
	v_mfma_f32_16x16x32_bf16 v[34:37], v[224:227], v[248:251], v[34:37]
	s_waitcnt vmcnt(6)
	ds_write_b128 v159, v[150:153] offset:36864
	s_waitcnt lgkmcnt(5)
	v_mfma_f32_16x16x32_bf16 v[30:33], v[228:231], v[236:239], v[30:33]
	v_mfma_f32_16x16x32_bf16 v[26:29], v[228:231], v[240:243], v[26:29]
	ds_write_b128 v159, v[130:133] offset:40960
	v_mfma_f32_16x16x32_bf16 v[22:25], v[228:231], v[244:247], v[22:25]
	v_mfma_f32_16x16x32_bf16 v[18:21], v[228:231], v[248:251], v[18:21]
	ds_write_b128 v159, v[134:137] offset:45056
	s_waitcnt lgkmcnt(6)
	v_mfma_f32_16x16x32_bf16 v[14:17], v[232:235], v[236:239], v[14:17]
	v_mfma_f32_16x16x32_bf16 v[10:13], v[232:235], v[240:243], v[10:13]
	v_mfma_f32_16x16x32_bf16 v[6:9], v[232:235], v[244:247], v[6:9]
	v_mfma_f32_16x16x32_bf16 v[2:5], v[232:235], v[248:251], v[2:5]
	s_setprio 0
	s_min_u32 s9, s9, 12
	s_lshl_b32 s9, s9, 6
	s_addk_i32 s9, 0xc0
	s_waitcnt lgkmcnt(0)
	s_barrier
; DI void cfence() { asm volatile("" ::: "memory"); }
; DI int swz4(int row) { const int g = (row >> 2) & 3; return ((g << 1) ^ ((g >> 1) * 3)) & 3; }
; #define LSTORE2(RA, RB, P)                                       \
;   {                                                              \
;     char* dA_ = smem + (P) * 24576 + wofs;                       \
;     _Pragma("unroll") for (int j = 0; j < 4; ++j) *(u32x4*)(dA_ + j * 4096) = RA[j]; \
;     _Pragma("unroll") for (int j = 0; j < 2; ++j) *(u32x4*)(dA_ + 16384 + j * 4096) = RB[j]; \
;   }
; DI void gemm256_kloop(f32x4 (&acc)[8][4], const bf16_t* __restrict__ A, int lda, const bf16_t* __restrict__ Bt, int ldb,
;                       int K, int b, int s0, int col0, char* smem) {
;     ...
;   GLOAD2(xa, xb, 0);
;   GLOAD2(ya, yb, 1);
;   cfence();
;   LSTORE2(xa, xb, 0);
;   __syncthreads();
;   const int co = ((fq ^ swz4(fr)) << 4);
;   const int aofs = (wr * 128 + fr) * 64 + co, bofs = (wc * 64 + fr) * 64 + co;
;   for (int kt = 0; kt < nk; kt += 2) {
;     GLOAD2(xa, xb, kt + 2);
;     cfence();
;     COMPUTE2(0);
;     LSTORE2(ya, yb, 1);
;     __syncthreads();
;     if (kt + 1 < nk) {
;       GLOAD2(ya, yb, kt + 3);
;       cfence();
;       COMPUTE2(1);
;       LSTORE2(xa, xb, 0);
;       __syncthreads();
;     }
;   }
	buffer_load_dwordx4 v[138:141], v0, s[20:23], s9 offen
	buffer_load_dwordx4 v[142:145], v154, s[20:23], s9 offen
	buffer_load_dwordx4 v[146:149], v155, s[20:23], s9 offen
	buffer_load_dwordx4 v[150:153], v156, s[20:23], s9 offen
	buffer_load_dwordx4 v[130:133], v157, s[24:27], s9 offen
	buffer_load_dwordx4 v[134:137], v158, s[24:27], s9 offen
	ds_read_b128 v[236:239], v160 offset:40960
	ds_read_b128 v[240:243], v160 offset:41984
	ds_read_b128 v[244:247], v160 offset:43008
	ds_read_b128 v[248:251], v160 offset:44032
	ds_read_b128 v[186:189], v161 offset:24576
	ds_read_b128 v[190:193], v161 offset:25600
	ds_read_b128 v[212:215], v161 offset:26624
	ds_read_b128 v[216:219], v161 offset:27648
	ds_read_b128 v[220:223], v161 offset:28672
	ds_read_b128 v[224:227], v161 offset:29696
	ds_read_b128 v[228:231], v161 offset:30720
	ds_read_b128 v[232:235], v161 offset:31744
	s_setprio 1
	s_waitcnt lgkmcnt(7)
	v_mfma_f32_16x16x32_bf16 v[126:129], v[186:189], v[236:239], v[126:129]
	v_mfma_f32_16x16x32_bf16 v[122:125], v[186:189], v[240:243], v[122:125]
	v_mfma_f32_16x16x32_bf16 v[118:121], v[186:189], v[244:247], v[118:121]
	v_mfma_f32_16x16x32_bf16 v[114:117], v[186:189], v[248:251], v[114:117]
	s_waitcnt lgkmcnt(6)
	v_mfma_f32_16x16x32_bf16 v[110:113], v[190:193], v[236:239], v[110:113]
	v_mfma_f32_16x16x32_bf16 v[106:109], v[190:193], v[240:243], v[106:109]
	v_mfma_f32_16x16x32_bf16 v[102:105], v[190:193], v[244:247], v[102:105]
	v_mfma_f32_16x16x32_bf16 v[98:101], v[190:193], v[248:251], v[98:101]
	s_waitcnt lgkmcnt(5)
	v_mfma_f32_16x16x32_bf16 v[94:97], v[212:215], v[236:239], v[94:97]
	v_mfma_f32_16x16x32_bf16 v[90:93], v[212:215], v[240:243], v[90:93]
	v_mfma_f32_16x16x32_bf16 v[86:89], v[212:215], v[244:247], v[86:89]
	v_mfma_f32_16x16x32_bf16 v[82:85], v[212:215], v[248:251], v[82:85]
	s_waitcnt lgkmcnt(4)
	v_mfma_f32_16x16x32_bf16 v[78:81], v[216:219], v[236:239], v[78:81]
	v_mfma_f32_16x16x32_bf16 v[74:77], v[216:219], v[240:243], v[74:77]
	v_mfma_f32_16x16x32_bf16 v[70:73], v[216:219], v[244:247], v[70:73]
	v_mfma_f32_16x16x32_bf16 v[66:69], v[216:219], v[248:251], v[66:69]
	s_waitcnt lgkmcnt(3)
	v_mfma_f32_16x16x32_bf16 v[62:65], v[220:223], v[236:239], v[62:65]
	v_mfma_f32_16x16x32_bf16 v[58:61], v[220:223], v[240:243], v[58:61]
	s_waitcnt vmcnt(11)
	ds_write_b128 v159, v[162:165]
	v_mfma_f32_16x16x32_bf16 v[54:57], v[220:223], v[244:247], v[54:57]
	v_mfma_f32_16x16x32_bf16 v[50:53], v[220:223], v[248:251], v[50:53]
	s_waitcnt vmcnt(10)
	ds_write_b128 v159, v[166:169] offset:4096
	s_waitcnt lgkmcnt(4)
	v_mfma_f32_16x16x32_bf16 v[46:49], v[224:227], v[236:239], v[46:49]
	v_mfma_f32_16x16x32_bf16 v[42:45], v[224:227], v[240:243], v[42:45]
	s_waitcnt vmcnt(9)
	ds_write_b128 v159, v[170:173] offset:8192
	v_mfma_f32_16x16x32_bf16 v[38:41], v[224:227], v[244:247], v[38:41]
	v_mfma_f32_16x16x32_bf16 v[34:37], v[224:227], v[248:251], v[34:37]
	s_waitcnt vmcnt(8)
	ds_write_b128 v159, v[174:177] offset:12288
	s_waitcnt lgkmcnt(5)
	v_mfma_f32_16x16x32_bf16 v[30:33], v[228:231], v[236:239], v[30:33]
	v_mfma_f32_16x16x32_bf16 v[26:29], v[228:231], v[240:243], v[26:29]
	s_waitcnt vmcnt(7)
	ds_write_b128 v159, v[178:181] offset:16384
	v_mfma_f32_16x16x32_bf16 v[22:25], v[228:231], v[244:247], v[22:25]
	v_mfma_f32_16x16x32_bf16 v[18:21], v[228:231], v[248:251], v[18:21]
	s_waitcnt vmcnt(6)
	ds_write_b128 v159, v[182:185] offset:20480
	s_waitcnt lgkmcnt(6)
	v_mfma_f32_16x16x32_bf16 v[14:17], v[232:235], v[236:239], v[14:17]
	v_mfma_f32_16x16x32_bf16 v[10:13], v[232:235], v[240:243], v[10:13]
	v_mfma_f32_16x16x32_bf16 v[6:9], v[232:235], v[244:247], v[6:9]
	v_mfma_f32_16x16x32_bf16 v[2:5], v[232:235], v[248:251], v[2:5]
	s_setprio 0
	s_addk_i32 s8, 0x80
	s_mov_b32 s9, s11
	s_waitcnt lgkmcnt(0)
	s_barrier
	s_cbranch_vccnz .LBB0_440
	s_lshl_b32 s26, s3, 1
	s_mul_hi_i32 s3, s5, 0x4100
	s_ashr_i32 s5, s4, 31
	s_lshl_b64 s[4:5], s[4:5], 1
	s_add_u32 s8, s38, s4
	s_addc_u32 s9, s39, s5
	s_lshl_b32 s4, s10, 8
	s_sub_i32 s27, s4, s2
	s_mov_b32 s18, 0
	s_mov_b64 s[10:11], -1
	s_branch .LBB0_443

; DI void cfence() { asm volatile("" ::: "memory"); }
; DI int swz4(int row) { const int g = (row >> 2) & 3; return ((g << 1) ^ ((g >> 1) * 3)) & 3; }
; #define LSTORE2(RA, RB, P)                                       \
;   {                                                              \
;     char* dA_ = smem + (P) * 24576 + wofs;                       \
;     _Pragma("unroll") for (int j = 0; j < 4; ++j) *(u32x4*)(dA_ + j * 4096) = RA[j]; \
;     _Pragma("unroll") for (int j = 0; j < 2; ++j) *(u32x4*)(dA_ + 16384 + j * 4096) = RB[j]; \
;   }
; DI void gemm256_kloop(f32x4 (&acc)[8][4], const bf16_t* __restrict__ A, int lda, const bf16_t* __restrict__ Bt, int ldb,
;                       int K, int b, int s0, int col0, char* smem) {
;     ...
;   GLOAD2(xa, xb, 0);
;   GLOAD2(ya, yb, 1);
;   cfence();
;   LSTORE2(xa, xb, 0);
;   __syncthreads();
;   const int co = ((fq ^ swz4(fr)) << 4);
;   const int aofs = (wr * 128 + fr) * 64 + co, bofs = (wc * 64 + fr) * 64 + co;
;   for (int kt = 0; kt < nk; kt += 2) {
;     GLOAD2(xa, xb, kt + 2);
;     cfence();
;     COMPUTE2(0);
;     LSTORE2(ya, yb, 1);
;     __syncthreads();
;     if (kt + 1 < nk) {
;       GLOAD2(ya, yb, kt + 3);
;       cfence();
;       COMPUTE2(1);
;       LSTORE2(xa, xb, 0);
;       __syncthreads();
;     }
;   }
.LBB0_462:
	s_add_i32 s8, s7, 2
	s_cmp_lt_u32 s7, 62
	s_cselect_b64 s[10:11], -1, 0
	s_and_b64 vcc, s[10:11], exec
	s_cselect_b32 s9, s6, 0xfc0
	buffer_load_dwordx4 v[162:165], v0, s[20:23], s9 offen
	buffer_load_dwordx4 v[166:169], v154, s[20:23], s9 offen
	buffer_load_dwordx4 v[170:173], v155, s[20:23], s9 offen
	buffer_load_dwordx4 v[174:177], v156, s[20:23], s9 offen
	buffer_load_dwordx4 v[178:181], v157, s[12:15], s9 offen
	buffer_load_dwordx4 v[182:185], v158, s[12:15], s9 offen
	ds_read_b128 v[236:239], v160 offset:16384
	ds_read_b128 v[240:243], v160 offset:17408
	ds_read_b128 v[244:247], v160 offset:18432
	ds_read_b128 v[248:251], v160 offset:19456
	ds_read_b128 v[186:189], v161
	ds_read_b128 v[190:193], v161 offset:1024
	ds_read_b128 v[212:215], v161 offset:2048
	ds_read_b128 v[216:219], v161 offset:3072
	ds_read_b128 v[220:223], v161 offset:4096
	ds_read_b128 v[224:227], v161 offset:5120
	ds_read_b128 v[228:231], v161 offset:6144
	ds_read_b128 v[232:235], v161 offset:7168
	s_setprio 1
	s_waitcnt lgkmcnt(7)
	v_mfma_f32_16x16x32_bf16 v[126:129], v[186:189], v[236:239], v[126:129]
	v_mfma_f32_16x16x32_bf16 v[122:125], v[186:189], v[240:243], v[122:125]
	v_mfma_f32_16x16x32_bf16 v[118:121], v[186:189], v[244:247], v[118:121]
	v_mfma_f32_16x16x32_bf16 v[114:117], v[186:189], v[248:251], v[114:117]
	s_waitcnt lgkmcnt(6)
	v_mfma_f32_16x16x32_bf16 v[110:113], v[190:193], v[236:239], v[110:113]
	v_mfma_f32_16x16x32_bf16 v[106:109], v[190:193], v[240:243], v[106:109]
	v_mfma_f32_16x16x32_bf16 v[102:105], v[190:193], v[244:247], v[102:105]
	v_mfma_f32_16x16x32_bf16 v[98:101], v[190:193], v[248:251], v[98:101]
	s_waitcnt lgkmcnt(5)
	v_mfma_f32_16x16x32_bf16 v[94:97], v[212:215], v[236:239], v[94:97]
	v_mfma_f32_16x16x32_bf16 v[90:93], v[212:215], v[240:243], v[90:93]
	v_mfma_f32_16x16x32_bf16 v[86:89], v[212:215], v[244:247], v[86:89]
	v_mfma_f32_16x16x32_bf16 v[82:85], v[212:215], v[248:251], v[82:85]
	s_waitcnt lgkmcnt(4)
	v_mfma_f32_16x16x32_bf16 v[78:81], v[216:219], v[236:239], v[78:81]
	v_mfma_f32_16x16x32_bf16 v[74:77], v[216:219], v[240:243], v[74:77]
	v_mfma_f32_16x16x32_bf16 v[70:73], v[216:219], v[244:247], v[70:73]
	v_mfma_f32_16x16x32_bf16 v[66:69], v[216:219], v[248:251], v[66:69]
	s_waitcnt lgkmcnt(3)
	v_mfma_f32_16x16x32_bf16 v[62:65], v[220:223], v[236:239], v[62:65]
	v_mfma_f32_16x16x32_bf16 v[58:61], v[220:223], v[240:243], v[58:61]
	s_waitcnt vmcnt(9)
	ds_write_b128 v159, v[138:141] offset:24576
	v_mfma_f32_16x16x32_bf16 v[54:57], v[220:223], v[244:247], v[54:57]
	v_mfma_f32_16x16x32_bf16 v[50:53], v[220:223], v[248:251], v[50:53]
	s_waitcnt vmcnt(8)
	ds_write_b128 v159, v[142:145] offset:28672
	s_waitcnt lgkmcnt(4)
	v_mfma_f32_16x16x32_bf16 v[46:49], v[224:227], v[236:239], v[46:49]
	v_mfma_f32_16x16x32_bf16 v[42:45], v[224:227], v[240:243], v[42:45]
	s_waitcnt vmcnt(7)
	ds_write_b128 v159, v[146:149] offset:32768
	v_mfma_f32_16x16x32_bf16 v[38:41], v[224:227], v[244:247], v[38:41]
	v_mfma_f32_16x16x32_bf16 v[34:37], v[224:227], v[248:251], v[34:37]
	s_waitcnt vmcnt(6)
	ds_write_b128 v159, v[150:153] offset:36864
	s_waitcnt lgkmcnt(5)
	v_mfma_f32_16x16x32_bf16 v[30:33], v[228:231], v[236:239], v[30:33]
	v_mfma_f32_16x16x32_bf16 v[26:29], v[228:231], v[240:243], v[26:29]
	ds_write_b128 v159, v[130:133] offset:40960
	v_mfma_f32_16x16x32_bf16 v[22:25], v[228:231], v[244:247], v[22:25]
	v_mfma_f32_16x16x32_bf16 v[18:21], v[228:231], v[248:251], v[18:21]
	ds_write_b128 v159, v[134:137] offset:45056
	s_waitcnt lgkmcnt(6)
	v_mfma_f32_16x16x32_bf16 v[14:17], v[232:235], v[236:239], v[14:17]
	v_mfma_f32_16x16x32_bf16 v[10:13], v[232:235], v[240:243], v[10:13]
	v_mfma_f32_16x16x32_bf16 v[6:9], v[232:235], v[244:247], v[6:9]
	v_mfma_f32_16x16x32_bf16 v[2:5], v[232:235], v[248:251], v[2:5]
	s_setprio 0
	s_min_u32 s7, s7, 60
	s_lshl_b32 s7, s7, 6
	s_addk_i32 s7, 0xc0
	s_waitcnt lgkmcnt(0)
	s_barrier
; DI void cfence() { asm volatile("" ::: "memory"); }
; DI int swz4(int row) { const int g = (row >> 2) & 3; return ((g << 1) ^ ((g >> 1) * 3)) & 3; }
; #define LSTORE2(RA, RB, P)                                       \
;   {                                                              \
;     char* dA_ = smem + (P) * 24576 + wofs;                       \
;     _Pragma("unroll") for (int j = 0; j < 4; ++j) *(u32x4*)(dA_ + j * 4096) = RA[j]; \
;     _Pragma("unroll") for (int j = 0; j < 2; ++j) *(u32x4*)(dA_ + 16384 + j * 4096) = RB[j]; \
;   }
; DI void gemm256_kloop(f32x4 (&acc)[8][4], const bf16_t* __restrict__ A, int lda, const bf16_t* __restrict__ Bt, int ldb,
;                       int K, int b, int s0, int col0, char* smem) {
;     ...
;   GLOAD2(xa, xb, 0);
;   GLOAD2(ya, yb, 1);
;   cfence();
;   LSTORE2(xa, xb, 0);
;   __syncthreads();
;   const int co = ((fq ^ swz4(fr)) << 4);
;   const int aofs = (wr * 128 + fr) * 64 + co, bofs = (wc * 64 + fr) * 64 + co;
;   for (int kt = 0; kt < nk; kt += 2) {
;     GLOAD2(xa, xb, kt + 2);
;     cfence();
;     COMPUTE2(0);
;     LSTORE2(ya, yb, 1);
;     __syncthreads();
;     if (kt + 1 < nk) {
;       GLOAD2(ya, yb, kt + 3);
;       cfence();
;       COMPUTE2(1);
;       LSTORE2(xa, xb, 0);
;       __syncthreads();
;     }
;   }
	buffer_load_dwordx4 v[138:141], v0, s[20:23], s7 offen
	buffer_load_dwordx4 v[142:145], v154, s[20:23], s7 offen
	buffer_load_dwordx4 v[146:149], v155, s[20:23], s7 offen
	buffer_load_dwordx4 v[150:153], v156, s[20:23], s7 offen
	buffer_load_dwordx4 v[130:133], v157, s[12:15], s7 offen
	buffer_load_dwordx4 v[134:137], v158, s[12:15], s7 offen
	ds_read_b128 v[236:239], v160 offset:40960
	ds_read_b128 v[240:243], v160 offset:41984
	ds_read_b128 v[244:247], v160 offset:43008
	ds_read_b128 v[248:251], v160 offset:44032
	ds_read_b128 v[186:189], v161 offset:24576
	ds_read_b128 v[190:193], v161 offset:25600
	ds_read_b128 v[212:215], v161 offset:26624
	ds_read_b128 v[216:219], v161 offset:27648
	ds_read_b128 v[220:223], v161 offset:28672
	ds_read_b128 v[224:227], v161 offset:29696
	ds_read_b128 v[228:231], v161 offset:30720
	ds_read_b128 v[232:235], v161 offset:31744
	s_setprio 1
	s_waitcnt lgkmcnt(7)
	v_mfma_f32_16x16x32_bf16 v[126:129], v[186:189], v[236:239], v[126:129]
	v_mfma_f32_16x16x32_bf16 v[122:125], v[186:189], v[240:243], v[122:125]
	v_mfma_f32_16x16x32_bf16 v[118:121], v[186:189], v[244:247], v[118:121]
	v_mfma_f32_16x16x32_bf16 v[114:117], v[186:189], v[248:251], v[114:117]
	s_waitcnt lgkmcnt(6)
	v_mfma_f32_16x16x32_bf16 v[110:113], v[190:193], v[236:239], v[110:113]
	v_mfma_f32_16x16x32_bf16 v[106:109], v[190:193], v[240:243], v[106:109]
	v_mfma_f32_16x16x32_bf16 v[102:105], v[190:193], v[244:247], v[102:105]
	v_mfma_f32_16x16x32_bf16 v[98:101], v[190:193], v[248:251], v[98:101]
	s_waitcnt lgkmcnt(5)
	v_mfma_f32_16x16x32_bf16 v[94:97], v[212:215], v[236:239], v[94:97]
	v_mfma_f32_16x16x32_bf16 v[90:93], v[212:215], v[240:243], v[90:93]
	v_mfma_f32_16x16x32_bf16 v[86:89], v[212:215], v[244:247], v[86:89]
	v_mfma_f32_16x16x32_bf16 v[82:85], v[212:215], v[248:251], v[82:85]
	s_waitcnt lgkmcnt(4)
	v_mfma_f32_16x16x32_bf16 v[78:81], v[216:219], v[236:239], v[78:81]
	v_mfma_f32_16x16x32_bf16 v[74:77], v[216:219], v[240:243], v[74:77]
	v_mfma_f32_16x16x32_bf16 v[70:73], v[216:219], v[244:247], v[70:73]
	v_mfma_f32_16x16x32_bf16 v[66:69], v[216:219], v[248:251], v[66:69]
	s_waitcnt lgkmcnt(3)
	v_mfma_f32_16x16x32_bf16 v[62:65], v[220:223], v[236:239], v[62:65]
	v_mfma_f32_16x16x32_bf16 v[58:61], v[220:223], v[240:243], v[58:61]
	s_waitcnt vmcnt(11)
	ds_write_b128 v159, v[162:165]
	v_mfma_f32_16x16x32_bf16 v[54:57], v[220:223], v[244:247], v[54:57]
	v_mfma_f32_16x16x32_bf16 v[50:53], v[220:223], v[248:251], v[50:53]
	s_waitcnt vmcnt(10)
	ds_write_b128 v159, v[166:169] offset:4096
	s_waitcnt lgkmcnt(4)
	v_mfma_f32_16x16x32_bf16 v[46:49], v[224:227], v[236:239], v[46:49]
	v_mfma_f32_16x16x32_bf16 v[42:45], v[224:227], v[240:243], v[42:45]
	s_waitcnt vmcnt(9)
	ds_write_b128 v159, v[170:173] offset:8192
	v_mfma_f32_16x16x32_bf16 v[38:41], v[224:227], v[244:247], v[38:41]
	v_mfma_f32_16x16x32_bf16 v[34:37], v[224:227], v[248:251], v[34:37]
	s_waitcnt vmcnt(8)
	ds_write_b128 v159, v[174:177] offset:12288
	s_waitcnt lgkmcnt(5)
	v_mfma_f32_16x16x32_bf16 v[30:33], v[228:231], v[236:239], v[30:33]
	v_mfma_f32_16x16x32_bf16 v[26:29], v[228:231], v[240:243], v[26:29]
	s_waitcnt vmcnt(7)
	ds_write_b128 v159, v[178:181] offset:16384
	v_mfma_f32_16x16x32_bf16 v[22:25], v[228:231], v[244:247], v[22:25]
	v_mfma_f32_16x16x32_bf16 v[18:21], v[228:231], v[248:251], v[18:21]
	s_waitcnt vmcnt(6)
	ds_write_b128 v159, v[182:185] offset:20480
	s_waitcnt lgkmcnt(6)
	v_mfma_f32_16x16x32_bf16 v[14:17], v[232:235], v[236:239], v[14:17]
	v_mfma_f32_16x16x32_bf16 v[10:13], v[232:235], v[240:243], v[10:13]
	v_mfma_f32_16x16x32_bf16 v[6:9], v[232:235], v[244:247], v[6:9]
	v_mfma_f32_16x16x32_bf16 v[2:5], v[232:235], v[248:251], v[2:5]
	s_setprio 0
	s_addk_i32 s6, 0x80
	s_mov_b32 s7, s8
	s_waitcnt lgkmcnt(0)
	s_barrier
	s_cbranch_vccnz .LBB0_462
	s_ashr_i32 s6, s5, 2
	s_cmp_lt_i32 s6, 2
	s_cselect_b64 s[8:9], -1, 0
	s_ashr_i32 s7, s6, 31
	s_lshl_b64 s[6:7], s[6:7], 2
	s_add_u32 s10, s52, s6
	s_addc_u32 s11, s53, s7
	s_lshl_b32 s5, s51, 7
	s_mulk_i32 s4, 0x480
	s_sub_i32 s71, s5, s4
	s_add_i32 s71, s71, 0xfffcf400
	s_mov_b32 s38, 0
	s_mov_b64 s[14:15], -1
	s_waitcnt vmcnt(0)
	s_branch .LBB0_465

; DI void cfence() { asm volatile("" ::: "memory"); }
; DI int swz4(int row) { const int g = (row >> 2) & 3; return ((g << 1) ^ ((g >> 1) * 3)) & 3; }
; #define LSTORE2(RA, RB, P)                                       \
;   {                                                              \
;     char* dA_ = smem + (P) * 24576 + wofs;                       \
;     _Pragma("unroll") for (int j = 0; j < 4; ++j) *(u32x4*)(dA_ + j * 4096) = RA[j]; \
;     _Pragma("unroll") for (int j = 0; j < 2; ++j) *(u32x4*)(dA_ + 16384 + j * 4096) = RB[j]; \
;   }
; DI void gemm256_kloop(f32x4 (&acc)[8][4], const bf16_t* __restrict__ A, int lda, const bf16_t* __restrict__ Bt, int ldb,
;                       int K, int b, int s0, int col0, char* smem) {
;     ...
;   GLOAD2(xa, xb, 0);
;   GLOAD2(ya, yb, 1);
;   cfence();
;   LSTORE2(xa, xb, 0);
;   __syncthreads();
;   const int co = ((fq ^ swz4(fr)) << 4);
;   const int aofs = (wr * 128 + fr) * 64 + co, bofs = (wc * 64 + fr) * 64 + co;
;   for (int kt = 0; kt < nk; kt += 2) {
;     GLOAD2(xa, xb, kt + 2);
;     cfence();
;     COMPUTE2(0);
;     LSTORE2(ya, yb, 1);
;     __syncthreads();
;     if (kt + 1 < nk) {
;       GLOAD2(ya, yb, kt + 3);
;       cfence();
;       COMPUTE2(1);
;       LSTORE2(xa, xb, 0);
;       __syncthreads();
;     }
;   }
.LBB0_479:
	s_add_i32 s9, s8, 2
	s_cmp_lt_u32 s8, 62
	s_cselect_b64 s[10:11], -1, 0
	s_and_b64 vcc, s[10:11], exec
	s_cselect_b32 s10, s7, 0xfc0
	buffer_load_dwordx4 v[162:165], v0, s[20:23], s10 offen
	buffer_load_dwordx4 v[166:169], v154, s[20:23], s10 offen
	buffer_load_dwordx4 v[170:173], v155, s[20:23], s10 offen
	buffer_load_dwordx4 v[174:177], v156, s[20:23], s10 offen
	buffer_load_dwordx4 v[178:181], v157, s[16:19], s10 offen
	buffer_load_dwordx4 v[182:185], v158, s[16:19], s10 offen
	ds_read_b128 v[236:239], v160 offset:16384
	ds_read_b128 v[240:243], v160 offset:17408
	ds_read_b128 v[244:247], v160 offset:18432
	ds_read_b128 v[248:251], v160 offset:19456
	ds_read_b128 v[186:189], v161
	ds_read_b128 v[190:193], v161 offset:1024
	ds_read_b128 v[212:215], v161 offset:2048
	ds_read_b128 v[216:219], v161 offset:3072
	ds_read_b128 v[220:223], v161 offset:4096
	ds_read_b128 v[224:227], v161 offset:5120
	ds_read_b128 v[228:231], v161 offset:6144
	ds_read_b128 v[232:235], v161 offset:7168
	s_setprio 1
	s_waitcnt lgkmcnt(7)
	v_mfma_f32_16x16x32_bf16 v[126:129], v[186:189], v[236:239], v[126:129]
	v_mfma_f32_16x16x32_bf16 v[122:125], v[186:189], v[240:243], v[122:125]
	v_mfma_f32_16x16x32_bf16 v[118:121], v[186:189], v[244:247], v[118:121]
	v_mfma_f32_16x16x32_bf16 v[114:117], v[186:189], v[248:251], v[114:117]
	s_waitcnt lgkmcnt(6)
	v_mfma_f32_16x16x32_bf16 v[110:113], v[190:193], v[236:239], v[110:113]
	v_mfma_f32_16x16x32_bf16 v[106:109], v[190:193], v[240:243], v[106:109]
	v_mfma_f32_16x16x32_bf16 v[102:105], v[190:193], v[244:247], v[102:105]
	v_mfma_f32_16x16x32_bf16 v[98:101], v[190:193], v[248:251], v[98:101]
	s_waitcnt lgkmcnt(5)
	v_mfma_f32_16x16x32_bf16 v[94:97], v[212:215], v[236:239], v[94:97]
	v_mfma_f32_16x16x32_bf16 v[90:93], v[212:215], v[240:243], v[90:93]
	v_mfma_f32_16x16x32_bf16 v[86:89], v[212:215], v[244:247], v[86:89]
	v_mfma_f32_16x16x32_bf16 v[82:85], v[212:215], v[248:251], v[82:85]
	s_waitcnt lgkmcnt(4)
	v_mfma_f32_16x16x32_bf16 v[78:81], v[216:219], v[236:239], v[78:81]
	v_mfma_f32_16x16x32_bf16 v[74:77], v[216:219], v[240:243], v[74:77]
	v_mfma_f32_16x16x32_bf16 v[70:73], v[216:219], v[244:247], v[70:73]
	v_mfma_f32_16x16x32_bf16 v[66:69], v[216:219], v[248:251], v[66:69]
	s_waitcnt lgkmcnt(3)
	v_mfma_f32_16x16x32_bf16 v[62:65], v[220:223], v[236:239], v[62:65]
	v_mfma_f32_16x16x32_bf16 v[58:61], v[220:223], v[240:243], v[58:61]
	s_waitcnt vmcnt(9)
	ds_write_b128 v159, v[138:141] offset:24576
	v_mfma_f32_16x16x32_bf16 v[54:57], v[220:223], v[244:247], v[54:57]
	v_mfma_f32_16x16x32_bf16 v[50:53], v[220:223], v[248:251], v[50:53]
	s_waitcnt vmcnt(8)
	ds_write_b128 v159, v[142:145] offset:28672
	s_waitcnt lgkmcnt(4)
	v_mfma_f32_16x16x32_bf16 v[46:49], v[224:227], v[236:239], v[46:49]
	v_mfma_f32_16x16x32_bf16 v[42:45], v[224:227], v[240:243], v[42:45]
	s_waitcnt vmcnt(7)
	ds_write_b128 v159, v[146:149] offset:32768
	v_mfma_f32_16x16x32_bf16 v[38:41], v[224:227], v[244:247], v[38:41]
	v_mfma_f32_16x16x32_bf16 v[34:37], v[224:227], v[248:251], v[34:37]
	s_waitcnt vmcnt(6)
	ds_write_b128 v159, v[150:153] offset:36864
	s_waitcnt lgkmcnt(5)
	v_mfma_f32_16x16x32_bf16 v[30:33], v[228:231], v[236:239], v[30:33]
	v_mfma_f32_16x16x32_bf16 v[26:29], v[228:231], v[240:243], v[26:29]
	ds_write_b128 v159, v[130:133] offset:40960
	v_mfma_f32_16x16x32_bf16 v[22:25], v[228:231], v[244:247], v[22:25]
	v_mfma_f32_16x16x32_bf16 v[18:21], v[228:231], v[248:251], v[18:21]
	ds_write_b128 v159, v[134:137] offset:45056
	s_waitcnt lgkmcnt(6)
	v_mfma_f32_16x16x32_bf16 v[14:17], v[232:235], v[236:239], v[14:17]
	v_mfma_f32_16x16x32_bf16 v[10:13], v[232:235], v[240:243], v[10:13]
	v_mfma_f32_16x16x32_bf16 v[6:9], v[232:235], v[244:247], v[6:9]
	v_mfma_f32_16x16x32_bf16 v[2:5], v[232:235], v[248:251], v[2:5]
	s_setprio 0
	s_min_u32 s8, s8, 60
	s_lshl_b32 s8, s8, 6
	s_addk_i32 s8, 0xc0
	s_waitcnt lgkmcnt(0)
	s_barrier
; DI void cfence() { asm volatile("" ::: "memory"); }
; DI int swz4(int row) { const int g = (row >> 2) & 3; return ((g << 1) ^ ((g >> 1) * 3)) & 3; }
; #define LSTORE2(RA, RB, P)                                       \
;   {                                                              \
;     char* dA_ = smem + (P) * 24576 + wofs;                       \
;     _Pragma("unroll") for (int j = 0; j < 4; ++j) *(u32x4*)(dA_ + j * 4096) = RA[j]; \
;     _Pragma("unroll") for (int j = 0; j < 2; ++j) *(u32x4*)(dA_ + 16384 + j * 4096) = RB[j]; \
;   }
; DI void gemm256_kloop(f32x4 (&acc)[8][4], const bf16_t* __restrict__ A, int lda, const bf16_t* __restrict__ Bt, int ldb,
;                       int K, int b, int s0, int col0, char* smem) {
;     ...
;   GLOAD2(xa, xb, 0);
;   GLOAD2(ya, yb, 1);
;   cfence();
;   LSTORE2(xa, xb, 0);
;   __syncthreads();
;   const int co = ((fq ^ swz4(fr)) << 4);
;   const int aofs = (wr * 128 + fr) * 64 + co, bofs = (wc * 64 + fr) * 64 + co;
;   for (int kt = 0; kt < nk; kt += 2) {
;     GLOAD2(xa, xb, kt + 2);
;     cfence();
;     COMPUTE2(0);
;     LSTORE2(ya, yb, 1);
;     __syncthreads();
;     if (kt + 1 < nk) {
;       GLOAD2(ya, yb, kt + 3);
;       cfence();
;       COMPUTE2(1);
;       LSTORE2(xa, xb, 0);
;       __syncthreads();
;     }
;   }
	buffer_load_dwordx4 v[138:141], v0, s[20:23], s8 offen
	buffer_load_dwordx4 v[142:145], v154, s[20:23], s8 offen
	buffer_load_dwordx4 v[146:149], v155, s[20:23], s8 offen
	buffer_load_dwordx4 v[150:153], v156, s[20:23], s8 offen
	buffer_load_dwordx4 v[130:133], v157, s[16:19], s8 offen
	buffer_load_dwordx4 v[134:137], v158, s[16:19], s8 offen
	ds_read_b128 v[236:239], v160 offset:40960
	ds_read_b128 v[240:243], v160 offset:41984
	ds_read_b128 v[244:247], v160 offset:43008
	ds_read_b128 v[248:251], v160 offset:44032
	ds_read_b128 v[186:189], v161 offset:24576
	ds_read_b128 v[190:193], v161 offset:25600
	ds_read_b128 v[212:215], v161 offset:26624
	ds_read_b128 v[216:219], v161 offset:27648
	ds_read_b128 v[220:223], v161 offset:28672
	ds_read_b128 v[224:227], v161 offset:29696
	ds_read_b128 v[228:231], v161 offset:30720
	ds_read_b128 v[232:235], v161 offset:31744
	s_setprio 1
	s_waitcnt lgkmcnt(7)
	v_mfma_f32_16x16x32_bf16 v[126:129], v[186:189], v[236:239], v[126:129]
	v_mfma_f32_16x16x32_bf16 v[122:125], v[186:189], v[240:243], v[122:125]
	v_mfma_f32_16x16x32_bf16 v[118:121], v[186:189], v[244:247], v[118:121]
	v_mfma_f32_16x16x32_bf16 v[114:117], v[186:189], v[248:251], v[114:117]
	s_waitcnt lgkmcnt(6)
	v_mfma_f32_16x16x32_bf16 v[110:113], v[190:193], v[236:239], v[110:113]
	v_mfma_f32_16x16x32_bf16 v[106:109], v[190:193], v[240:243], v[106:109]
	v_mfma_f32_16x16x32_bf16 v[102:105], v[190:193], v[244:247], v[102:105]
	v_mfma_f32_16x16x32_bf16 v[98:101], v[190:193], v[248:251], v[98:101]
	s_waitcnt lgkmcnt(5)
	v_mfma_f32_16x16x32_bf16 v[94:97], v[212:215], v[236:239], v[94:97]
	v_mfma_f32_16x16x32_bf16 v[90:93], v[212:215], v[240:243], v[90:93]
	v_mfma_f32_16x16x32_bf16 v[86:89], v[212:215], v[244:247], v[86:89]
	v_mfma_f32_16x16x32_bf16 v[82:85], v[212:215], v[248:251], v[82:85]
	s_waitcnt lgkmcnt(4)
	v_mfma_f32_16x16x32_bf16 v[78:81], v[216:219], v[236:239], v[78:81]
	v_mfma_f32_16x16x32_bf16 v[74:77], v[216:219], v[240:243], v[74:77]
	v_mfma_f32_16x16x32_bf16 v[70:73], v[216:219], v[244:247], v[70:73]
	v_mfma_f32_16x16x32_bf16 v[66:69], v[216:219], v[248:251], v[66:69]
	s_waitcnt lgkmcnt(3)
	v_mfma_f32_16x16x32_bf16 v[62:65], v[220:223], v[236:239], v[62:65]
	v_mfma_f32_16x16x32_bf16 v[58:61], v[220:223], v[240:243], v[58:61]
	s_waitcnt vmcnt(11)
	ds_write_b128 v159, v[162:165]
	v_mfma_f32_16x16x32_bf16 v[54:57], v[220:223], v[244:247], v[54:57]
	v_mfma_f32_16x16x32_bf16 v[50:53], v[220:223], v[248:251], v[50:53]
	s_waitcnt vmcnt(10)
	ds_write_b128 v159, v[166:169] offset:4096
	s_waitcnt lgkmcnt(4)
	v_mfma_f32_16x16x32_bf16 v[46:49], v[224:227], v[236:239], v[46:49]
	v_mfma_f32_16x16x32_bf16 v[42:45], v[224:227], v[240:243], v[42:45]
	s_waitcnt vmcnt(9)
	ds_write_b128 v159, v[170:173] offset:8192
	v_mfma_f32_16x16x32_bf16 v[38:41], v[224:227], v[244:247], v[38:41]
	v_mfma_f32_16x16x32_bf16 v[34:37], v[224:227], v[248:251], v[34:37]
	s_waitcnt vmcnt(8)
	ds_write_b128 v159, v[174:177] offset:12288
	s_waitcnt lgkmcnt(5)
	v_mfma_f32_16x16x32_bf16 v[30:33], v[228:231], v[236:239], v[30:33]
	v_mfma_f32_16x16x32_bf16 v[26:29], v[228:231], v[240:243], v[26:29]
	s_waitcnt vmcnt(7)
	ds_write_b128 v159, v[178:181] offset:16384
	v_mfma_f32_16x16x32_bf16 v[22:25], v[228:231], v[244:247], v[22:25]
	v_mfma_f32_16x16x32_bf16 v[18:21], v[228:231], v[248:251], v[18:21]
	s_waitcnt vmcnt(6)
	ds_write_b128 v159, v[182:185] offset:20480
	s_waitcnt lgkmcnt(6)
	v_mfma_f32_16x16x32_bf16 v[14:17], v[232:235], v[236:239], v[14:17]
	v_mfma_f32_16x16x32_bf16 v[10:13], v[232:235], v[240:243], v[10:13]
	v_mfma_f32_16x16x32_bf16 v[6:9], v[232:235], v[244:247], v[6:9]
	v_mfma_f32_16x16x32_bf16 v[2:5], v[232:235], v[248:251], v[2:5]
	s_setprio 0
	s_addk_i32 s7, 0x80
	s_mov_b32 s8, s9
	s_waitcnt lgkmcnt(0)
	s_barrier
	s_cbranch_vccnz .LBB0_479
	s_cmp_gt_i32 s5, 9
	s_cselect_b64 s[8:9], -1, 0
	s_ashr_i32 s7, s6, 31
	s_lshl_b64 s[10:11], s[6:7], 8
	s_add_i32 s7, s34, 0xfffffb00
	s_add_u32 s10, s10, s7
	s_addc_u32 s11, s11, 0
	s_cmp_gt_i32 s5, 7
	s_cselect_b64 s[14:15], -1, 0
	s_cmp_lt_i32 s5, 8
	s_cselect_b64 vcc, -1, 0
	s_mul_hi_i32 s5, s6, 0x4100
	s_ashr_i32 s19, s34, 31
	s_lshl_b64 s[6:7], s[34:35], 1
	s_mov_b32 s18, s34
	s_add_u32 s6, s92, s6
	s_addc_u32 s7, s93, s7
	s_lshl_b64 s[18:19], s[18:19], 1
	v_mov_b32_e32 v0, 0x3e38aa3b
	s_add_u32 s18, s76, s18
	s_waitcnt vmcnt(3)
	v_cndmask_b32_e32 v146, 1.0, v0, vcc
	s_addc_u32 s19, s77, s19
	s_lshl_b32 s34, s38, 8
	v_mov_b32_e32 v147, v146
	s_sub_i32 s34, s34, s4
	s_mov_b32 s70, 0
	s_mov_b64 s[38:39], -1
	s_branch .LBB0_483

; DI void cfence() { asm volatile("" ::: "memory"); }
; DI void phase_scan(const Params& P, int l, char* smem) {
;     ...
;     for (int c = 0; c < nchunk; ++c) {
;       if (c + 1 < nchunk) scan_load(raw, R, E, Aa, b, dir, (c + 1) * 16 + st, k4);
;       cfence();
;       const float* cb = buf + (c & 1) * (16 * 384);
;       float ykeep = 0.f;
;     ...
;       {
;         float4 Ar[4], Aw[4], Ak[4], Aa[4], Ab[4], Br[4], Bw[4], Bk[4], Ba[4], Bb[4];
;         float Av[4], Bv[4];
;         SCAN_LOAD(A, 0);
;         SCAN_LOAD(B, 1);
;         SCAN_STEPS(A, 0);
;         SCAN_LOAD(A, 2);
;         SCAN_STEPS(B, 1);
;         SCAN_LOAD(B, 3);
;         SCAN_STEPS(A, 2);
;         SCAN_STEPS(B, 3);
;       }
.LBB0_513:
	s_add_i32 s8, s20, 1
	s_bitcmp1_b32 s20, 0
	s_cselect_b32 s9, 0x6000, 0
	v_lshl_or_b32 v219, v172, 2, s9
	s_lshl_b32 s10, s19, 2
	s_or_b32 s9, s9, s10
	v_lshl_add_u32 v218, v170, 2, s9
	ds_read_b128 v[40:43], v219 offset:512
	ds_read_b32 v60, v218 offset:1280
	ds_read_b128 v[44:47], v219 offset:768
	ds_read_b128 v[48:51], v219 offset:256
	ds_read_b128 v[52:55], v219 offset:1024
	ds_read_b128 v[56:59], v219
	ds_read_b128 v[64:67], v219 offset:2048
	ds_read_b32 v84, v218 offset:2816
	ds_read_b128 v[68:71], v219 offset:2304
	ds_read_b128 v[72:75], v219 offset:1792
	ds_read_b128 v[76:79], v219 offset:2560
	ds_read_b128 v[80:83], v219 offset:1536
	s_cmp_lt_u32 s20, 16
	s_movk_i32 s9, 0x41ff
	s_cselect_b32 s9, 0xff, s9
	s_andn2_b64 vcc, exec, s[16:17]
	s_mov_b32 s10, 0x10001
	s_mov_b32 s11, 0x10001
	s_waitcnt lgkmcnt(10)
	v_pk_mul_f32 v[156:157], v[60:61], v[40:41] op_sel_hi:[0,1]
	v_pk_mul_f32 v[158:159], v[60:61], v[42:43] op_sel_hi:[0,1]
	s_waitcnt lgkmcnt(6)
	ds_read_b128 v[88:91], v219 offset:3584
	ds_read_b32 v108, v218 offset:4352
	ds_read_b128 v[92:95], v219 offset:3840
	ds_read_b128 v[96:99], v219 offset:3328
	ds_read_b128 v[100:103], v219 offset:4096
	ds_read_b128 v[104:107], v219 offset:3072
	v_mul_f32_e32 v164, v126, v44
	v_fma_f32 v164, v127, v45, v164
	v_fma_f32 v164, v128, v46, v164
	v_fma_f32 v164, v129, v47, v164
	v_pk_fma_f32 v[156:157], v[126:127], v[48:49], v[156:157]
	v_pk_fma_f32 v[158:159], v[128:129], v[50:51], v[158:159]
	v_add_f32_dpp v164, v164, v164 quad_perm:[1,0,3,2] row_mask:0xf bank_mask:0xf bound_ctrl:1
	s_nop 0
	s_waitcnt lgkmcnt(10)
	v_pk_mul_f32 v[160:161], v[84:85], v[64:65] op_sel_hi:[0,1]
	v_add_f32_dpp v164, v164, v164 quad_perm:[2,3,0,1] row_mask:0xf bank_mask:0xf bound_ctrl:1
	s_nop 0
	v_pk_mul_f32 v[162:163], v[84:85], v[66:67] op_sel_hi:[0,1]
	v_add_f32_dpp v164, v164, v164 row_half_mirror row_mask:0xf bank_mask:0xf bound_ctrl:1
	s_nop 0
	s_nop 0
	v_add_f32_dpp v164, v164, v164 row_mirror row_mask:0xf bank_mask:0xf bound_ctrl:1
	s_nop 0
	v_pk_fma_f32 v[126:127], v[164:165], v[52:53], v[156:157] op_sel_hi:[0,1,1]
	v_pk_fma_f32 v[128:129], v[164:165], v[54:55], v[158:159] op_sel_hi:[0,1,1]
	s_waitcnt lgkmcnt(6)
	ds_read_b128 v[132:135], v219 offset:5120
	ds_read_b32 v152, v218 offset:5888
	ds_read_b128 v[136:139], v219 offset:5376
	ds_read_b128 v[140:143], v219 offset:4864
	ds_read_b128 v[144:147], v219 offset:5632
	ds_read_b128 v[148:151], v219 offset:4608
	v_mul_f32_e32 v164, v126, v68
	v_mul_f32_e32 v165, v126, v56
	v_fma_f32 v164, v127, v69, v164
	v_fma_f32 v165, v127, v57, v165
	v_fma_f32 v164, v128, v70, v164
	v_fma_f32 v165, v128, v58, v165
	v_fma_f32 v164, v129, v71, v164
	v_fma_f32 v165, v129, v59, v165
	v_pk_fma_f32 v[160:161], v[126:127], v[72:73], v[160:161]
	v_pk_fma_f32 v[162:163], v[128:129], v[74:75], v[162:163]
	v_add_f32_dpp v164, v164, v164 quad_perm:[1,0,3,2] row_mask:0xf bank_mask:0xf bound_ctrl:1
	v_add_f32_dpp v165, v165, v165 quad_perm:[1,0,3,2] row_mask:0xf bank_mask:0xf bound_ctrl:1
	s_waitcnt lgkmcnt(10)
	v_pk_mul_f32 v[156:157], v[108:109], v[88:89] op_sel_hi:[0,1]
	v_add_f32_dpp v164, v164, v164 quad_perm:[2,3,0,1] row_mask:0xf bank_mask:0xf bound_ctrl:1
	v_add_f32_dpp v165, v165, v165 quad_perm:[2,3,0,1] row_mask:0xf bank_mask:0xf bound_ctrl:1
	v_pk_mul_f32 v[158:159], v[108:109], v[90:91] op_sel_hi:[0,1]
	v_add_f32_dpp v164, v164, v164 row_half_mirror row_mask:0xf bank_mask:0xf bound_ctrl:1
	v_add_f32_dpp v165, v165, v165 row_half_mirror row_mask:0xf bank_mask:0xf bound_ctrl:1
	s_nop 0
	v_add_f32_dpp v164, v164, v164 row_mirror row_mask:0xf bank_mask:0xf bound_ctrl:1
	v_add_f32_dpp v165, v165, v165 row_mirror row_mask:0xf bank_mask:0xf bound_ctrl:1
	v_pk_fma_f32 v[126:127], v[164:165], v[76:77], v[160:161] op_sel_hi:[0,1,1]
	v_cndmask_b32_e64 v11, v1, v165, s[10:11]
	s_lshl_b64 s[10:11], s[10:11], 1
	v_pk_fma_f32 v[128:129], v[164:165], v[78:79], v[162:163] op_sel_hi:[0,1,1]
	s_waitcnt lgkmcnt(6)
	ds_read_b128 v[40:43], v219 offset:6656
	ds_read_b32 v60, v218 offset:7424
	ds_read_b128 v[44:47], v219 offset:6912
	ds_read_b128 v[48:51], v219 offset:6400
	ds_read_b128 v[52:55], v219 offset:7168
	ds_read_b128 v[56:59], v219 offset:6144
	v_mul_f32_e32 v164, v126, v92
	v_mul_f32_e32 v165, v126, v80
	v_fma_f32 v164, v127, v93, v164
	v_fma_f32 v165, v127, v81, v165
	v_fma_f32 v164, v128, v94, v164
	v_fma_f32 v165, v128, v82, v165
	v_fma_f32 v164, v129, v95, v164
	v_fma_f32 v165, v129, v83, v165
	v_pk_fma_f32 v[156:157], v[126:127], v[96:97], v[156:157]
	v_pk_fma_f32 v[158:159], v[128:129], v[98:99], v[158:159]
	v_add_f32_dpp v164, v164, v164 quad_perm:[1,0,3,2] row_mask:0xf bank_mask:0xf bound_ctrl:1
	v_add_f32_dpp v165, v165, v165 quad_perm:[1,0,3,2] row_mask:0xf bank_mask:0xf bound_ctrl:1
	s_waitcnt lgkmcnt(10)
	v_pk_mul_f32 v[160:161], v[152:153], v[132:133] op_sel_hi:[0,1]
	v_add_f32_dpp v164, v164, v164 quad_perm:[2,3,0,1] row_mask:0xf bank_mask:0xf bound_ctrl:1
	v_add_f32_dpp v165, v165, v165 quad_perm:[2,3,0,1] row_mask:0xf bank_mask:0xf bound_ctrl:1
	v_pk_mul_f32 v[162:163], v[152:153], v[134:135] op_sel_hi:[0,1]
	v_add_f32_dpp v164, v164, v164 row_half_mirror row_mask:0xf bank_mask:0xf bound_ctrl:1
	v_add_f32_dpp v165, v165, v165 row_half_mirror row_mask:0xf bank_mask:0xf bound_ctrl:1
	s_nop 0
	v_add_f32_dpp v164, v164, v164 row_mirror row_mask:0xf bank_mask:0xf bound_ctrl:1
	v_add_f32_dpp v165, v165, v165 row_mirror row_mask:0xf bank_mask:0xf bound_ctrl:1
	v_pk_fma_f32 v[126:127], v[164:165], v[100:101], v[156:157] op_sel_hi:[0,1,1]
	v_cndmask_b32_e64 v11, v11, v165, s[10:11]
	s_lshl_b64 s[10:11], s[10:11], 1
	v_pk_fma_f32 v[128:129], v[164:165], v[102:103], v[158:159] op_sel_hi:[0,1,1]
	s_waitcnt lgkmcnt(6)
	ds_read_b128 v[64:67], v219 offset:8192
	ds_read_b32 v84, v218 offset:8960
	ds_read_b128 v[68:71], v219 offset:8448
	ds_read_b128 v[72:75], v219 offset:7936
	ds_read_b128 v[76:79], v219 offset:8704
	ds_read_b128 v[80:83], v219 offset:7680
	v_mul_f32_e32 v164, v126, v136
	v_mul_f32_e32 v165, v126, v104
	v_fma_f32 v164, v127, v137, v164
	v_fma_f32 v165, v127, v105, v165
	v_fma_f32 v164, v128, v138, v164
	v_fma_f32 v165, v128, v106, v165
	v_fma_f32 v164, v129, v139, v164
	v_fma_f32 v165, v129, v107, v165
	v_pk_fma_f32 v[160:161], v[126:127], v[140:141], v[160:161]
	v_pk_fma_f32 v[162:163], v[128:129], v[142:143], v[162:163]
	v_add_f32_dpp v164, v164, v164 quad_perm:[1,0,3,2] row_mask:0xf bank_mask:0xf bound_ctrl:1
	v_add_f32_dpp v165, v165, v165 quad_perm:[1,0,3,2] row_mask:0xf bank_mask:0xf bound_ctrl:1
	s_waitcnt lgkmcnt(10)
	v_pk_mul_f32 v[156:157], v[60:61], v[40:41] op_sel_hi:[0,1]
	v_add_f32_dpp v164, v164, v164 quad_perm:[2,3,0,1] row_mask:0xf bank_mask:0xf bound_ctrl:1
	v_add_f32_dpp v165, v165, v165 quad_perm:[2,3,0,1] row_mask:0xf bank_mask:0xf bound_ctrl:1
	v_pk_mul_f32 v[158:159], v[60:61], v[42:43] op_sel_hi:[0,1]
	v_add_f32_dpp v164, v164, v164 row_half_mirror row_mask:0xf bank_mask:0xf bound_ctrl:1
	v_add_f32_dpp v165, v165, v165 row_half_mirror row_mask:0xf bank_mask:0xf bound_ctrl:1
	s_nop 0
	v_add_f32_dpp v164, v164, v164 row_mirror row_mask:0xf bank_mask:0xf bound_ctrl:1
	v_add_f32_dpp v165, v165, v165 row_mirror row_mask:0xf bank_mask:0xf bound_ctrl:1
	v_pk_fma_f32 v[126:127], v[164:165], v[144:145], v[160:161] op_sel_hi:[0,1,1]
	v_cndmask_b32_e64 v11, v11, v165, s[10:11]
	s_lshl_b64 s[10:11], s[10:11], 1
	v_pk_fma_f32 v[128:129], v[164:165], v[146:147], v[162:163] op_sel_hi:[0,1,1]
	s_waitcnt lgkmcnt(6)
	ds_read_b128 v[88:91], v219 offset:9728
	ds_read_b32 v108, v218 offset:10496
	ds_read_b128 v[92:95], v219 offset:9984
	ds_read_b128 v[96:99], v219 offset:9472
	ds_read_b128 v[100:103], v219 offset:10240
	ds_read_b128 v[104:107], v219 offset:9216
	v_mul_f32_e32 v164, v126, v44
	v_mul_f32_e32 v165, v126, v148
	v_fma_f32 v164, v127, v45, v164
	v_fma_f32 v165, v127, v149, v165
	v_fma_f32 v164, v128, v46, v164
	v_fma_f32 v165, v128, v150, v165
	v_fma_f32 v164, v129, v47, v164
	v_fma_f32 v165, v129, v151, v165
	v_pk_fma_f32 v[156:157], v[126:127], v[48:49], v[156:157]
	v_pk_fma_f32 v[158:159], v[128:129], v[50:51], v[158:159]
	v_add_f32_dpp v164, v164, v164 quad_perm:[1,0,3,2] row_mask:0xf bank_mask:0xf bound_ctrl:1
	v_add_f32_dpp v165, v165, v165 quad_perm:[1,0,3,2] row_mask:0xf bank_mask:0xf bound_ctrl:1
	s_waitcnt lgkmcnt(10)
	v_pk_mul_f32 v[160:161], v[84:85], v[64:65] op_sel_hi:[0,1]
	v_add_f32_dpp v164, v164, v164 quad_perm:[2,3,0,1] row_mask:0xf bank_mask:0xf bound_ctrl:1
	v_add_f32_dpp v165, v165, v165 quad_perm:[2,3,0,1] row_mask:0xf bank_mask:0xf bound_ctrl:1
	v_pk_mul_f32 v[162:163], v[84:85], v[66:67] op_sel_hi:[0,1]
	v_add_f32_dpp v164, v164, v164 row_half_mirror row_mask:0xf bank_mask:0xf bound_ctrl:1
	v_add_f32_dpp v165, v165, v165 row_half_mirror row_mask:0xf bank_mask:0xf bound_ctrl:1
	s_nop 0
	v_add_f32_dpp v164, v164, v164 row_mirror row_mask:0xf bank_mask:0xf bound_ctrl:1
	v_add_f32_dpp v165, v165, v165 row_mirror row_mask:0xf bank_mask:0xf bound_ctrl:1
	v_pk_fma_f32 v[126:127], v[164:165], v[52:53], v[156:157] op_sel_hi:[0,1,1]
	v_cndmask_b32_e64 v11, v11, v165, s[10:11]
	s_lshl_b64 s[10:11], s[10:11], 1
	v_pk_fma_f32 v[128:129], v[164:165], v[54:55], v[158:159] op_sel_hi:[0,1,1]
	s_waitcnt lgkmcnt(6)
	ds_read_b128 v[132:135], v219 offset:11264
	ds_read_b32 v152, v218 offset:12032
	ds_read_b128 v[136:139], v219 offset:11520
	ds_read_b128 v[140:143], v219 offset:11008
	ds_read_b128 v[144:147], v219 offset:11776
	ds_read_b128 v[148:151], v219 offset:10752
	v_mul_f32_e32 v164, v126, v68
	v_mul_f32_e32 v165, v126, v56
	v_fma_f32 v164, v127, v69, v164
	v_fma_f32 v165, v127, v57, v165
	v_fma_f32 v164, v128, v70, v164
	v_fma_f32 v165, v128, v58, v165
	v_fma_f32 v164, v129, v71, v164
	v_fma_f32 v165, v129, v59, v165
	v_pk_fma_f32 v[160:161], v[126:127], v[72:73], v[160:161]
	v_pk_fma_f32 v[162:163], v[128:129], v[74:75], v[162:163]
	v_add_f32_dpp v164, v164, v164 quad_perm:[1,0,3,2] row_mask:0xf bank_mask:0xf bound_ctrl:1
	v_add_f32_dpp v165, v165, v165 quad_perm:[1,0,3,2] row_mask:0xf bank_mask:0xf bound_ctrl:1
	s_waitcnt lgkmcnt(10)
	v_pk_mul_f32 v[156:157], v[108:109], v[88:89] op_sel_hi:[0,1]
	v_add_f32_dpp v164, v164, v164 quad_perm:[2,3,0,1] row_mask:0xf bank_mask:0xf bound_ctrl:1
	v_add_f32_dpp v165, v165, v165 quad_perm:[2,3,0,1] row_mask:0xf bank_mask:0xf bound_ctrl:1
	v_pk_mul_f32 v[158:159], v[108:109], v[90:91] op_sel_hi:[0,1]
	v_add_f32_dpp v164, v164, v164 row_half_mirror row_mask:0xf bank_mask:0xf bound_ctrl:1
	v_add_f32_dpp v165, v165, v165 row_half_mirror row_mask:0xf bank_mask:0xf bound_ctrl:1
	s_nop 0
	v_add_f32_dpp v164, v164, v164 row_mirror row_mask:0xf bank_mask:0xf bound_ctrl:1
	v_add_f32_dpp v165, v165, v165 row_mirror row_mask:0xf bank_mask:0xf bound_ctrl:1
	v_pk_fma_f32 v[126:127], v[164:165], v[76:77], v[160:161] op_sel_hi:[0,1,1]
	v_cndmask_b32_e64 v11, v11, v165, s[10:11]
	s_lshl_b64 s[10:11], s[10:11], 1
	v_pk_fma_f32 v[128:129], v[164:165], v[78:79], v[162:163] op_sel_hi:[0,1,1]
	s_waitcnt lgkmcnt(6)
	ds_read_b128 v[40:43], v219 offset:12800
	ds_read_b32 v60, v218 offset:13568
	ds_read_b128 v[44:47], v219 offset:13056
	ds_read_b128 v[48:51], v219 offset:12544
	ds_read_b128 v[52:55], v219 offset:13312
	ds_read_b128 v[56:59], v219 offset:12288
	v_mul_f32_e32 v164, v126, v92
	v_mul_f32_e32 v165, v126, v80
	v_fma_f32 v164, v127, v93, v164
	v_fma_f32 v165, v127, v81, v165
	v_fma_f32 v164, v128, v94, v164
	v_fma_f32 v165, v128, v82, v165
	v_fma_f32 v164, v129, v95, v164
	v_fma_f32 v165, v129, v83, v165
	v_pk_fma_f32 v[156:157], v[126:127], v[96:97], v[156:157]
	v_pk_fma_f32 v[158:159], v[128:129], v[98:99], v[158:159]
	v_add_f32_dpp v164, v164, v164 quad_perm:[1,0,3,2] row_mask:0xf bank_mask:0xf bound_ctrl:1
	v_add_f32_dpp v165, v165, v165 quad_perm:[1,0,3,2] row_mask:0xf bank_mask:0xf bound_ctrl:1
	s_waitcnt lgkmcnt(10)
	v_pk_mul_f32 v[160:161], v[152:153], v[132:133] op_sel_hi:[0,1]
	v_add_f32_dpp v164, v164, v164 quad_perm:[2,3,0,1] row_mask:0xf bank_mask:0xf bound_ctrl:1
	v_add_f32_dpp v165, v165, v165 quad_perm:[2,3,0,1] row_mask:0xf bank_mask:0xf bound_ctrl:1
	v_pk_mul_f32 v[162:163], v[152:153], v[134:135] op_sel_hi:[0,1]
	v_add_f32_dpp v164, v164, v164 row_half_mirror row_mask:0xf bank_mask:0xf bound_ctrl:1
	v_add_f32_dpp v165, v165, v165 row_half_mirror row_mask:0xf bank_mask:0xf bound_ctrl:1
	s_nop 0
	v_add_f32_dpp v164, v164, v164 row_mirror row_mask:0xf bank_mask:0xf bound_ctrl:1
	v_add_f32_dpp v165, v165, v165 row_mirror row_mask:0xf bank_mask:0xf bound_ctrl:1
	v_pk_fma_f32 v[126:127], v[164:165], v[100:101], v[156:157] op_sel_hi:[0,1,1]
	v_cndmask_b32_e64 v11, v11, v165, s[10:11]
	s_lshl_b64 s[10:11], s[10:11], 1
	v_pk_fma_f32 v[128:129], v[164:165], v[102:103], v[158:159] op_sel_hi:[0,1,1]
	s_waitcnt lgkmcnt(6)
	ds_read_b128 v[64:67], v219 offset:14336
	ds_read_b32 v84, v218 offset:15104
	ds_read_b128 v[68:71], v219 offset:14592
	ds_read_b128 v[72:75], v219 offset:14080
	ds_read_b128 v[76:79], v219 offset:14848
	ds_read_b128 v[80:83], v219 offset:13824
	v_mul_f32_e32 v164, v126, v136
	v_mul_f32_e32 v165, v126, v104
	v_fma_f32 v164, v127, v137, v164
	v_fma_f32 v165, v127, v105, v165
	v_fma_f32 v164, v128, v138, v164
	v_fma_f32 v165, v128, v106, v165
	v_fma_f32 v164, v129, v139, v164
	v_fma_f32 v165, v129, v107, v165
	v_pk_fma_f32 v[160:161], v[126:127], v[140:141], v[160:161]
	v_pk_fma_f32 v[162:163], v[128:129], v[142:143], v[162:163]
	v_add_f32_dpp v164, v164, v164 quad_perm:[1,0,3,2] row_mask:0xf bank_mask:0xf bound_ctrl:1
	v_add_f32_dpp v165, v165, v165 quad_perm:[1,0,3,2] row_mask:0xf bank_mask:0xf bound_ctrl:1
	s_waitcnt lgkmcnt(10)
	v_pk_mul_f32 v[156:157], v[60:61], v[40:41] op_sel_hi:[0,1]
	v_add_f32_dpp v164, v164, v164 quad_perm:[2,3,0,1] row_mask:0xf bank_mask:0xf bound_ctrl:1
	v_add_f32_dpp v165, v165, v165 quad_perm:[2,3,0,1] row_mask:0xf bank_mask:0xf bound_ctrl:1
	v_pk_mul_f32 v[158:159], v[60:61], v[42:43] op_sel_hi:[0,1]
	v_add_f32_dpp v164, v164, v164 row_half_mirror row_mask:0xf bank_mask:0xf bound_ctrl:1
	v_add_f32_dpp v165, v165, v165 row_half_mirror row_mask:0xf bank_mask:0xf bound_ctrl:1
	s_nop 0
	v_add_f32_dpp v164, v164, v164 row_mirror row_mask:0xf bank_mask:0xf bound_ctrl:1
	v_add_f32_dpp v165, v165, v165 row_mirror row_mask:0xf bank_mask:0xf bound_ctrl:1
	v_pk_fma_f32 v[126:127], v[164:165], v[144:145], v[160:161] op_sel_hi:[0,1,1]
	v_cndmask_b32_e64 v11, v11, v165, s[10:11]
	s_lshl_b64 s[10:11], s[10:11], 1
	v_pk_fma_f32 v[128:129], v[164:165], v[146:147], v[162:163] op_sel_hi:[0,1,1]
	s_waitcnt lgkmcnt(6)
	ds_read_b128 v[88:91], v219 offset:15872
	ds_read_b32 v108, v218 offset:16640
	ds_read_b128 v[92:95], v219 offset:16128
	ds_read_b128 v[96:99], v219 offset:15616
	ds_read_b128 v[100:103], v219 offset:16384
	ds_read_b128 v[104:107], v219 offset:15360
	v_mul_f32_e32 v164, v126, v44
	v_mul_f32_e32 v165, v126, v148
	v_fma_f32 v164, v127, v45, v164
	v_fma_f32 v165, v127, v149, v165
	v_fma_f32 v164, v128, v46, v164
	v_fma_f32 v165, v128, v150, v165
	v_fma_f32 v164, v129, v47, v164
	v_fma_f32 v165, v129, v151, v165
	v_pk_fma_f32 v[156:157], v[126:127], v[48:49], v[156:157]
	v_pk_fma_f32 v[158:159], v[128:129], v[50:51], v[158:159]
	v_add_f32_dpp v164, v164, v164 quad_perm:[1,0,3,2] row_mask:0xf bank_mask:0xf bound_ctrl:1
	v_add_f32_dpp v165, v165, v165 quad_perm:[1,0,3,2] row_mask:0xf bank_mask:0xf bound_ctrl:1
	s_waitcnt lgkmcnt(10)
	v_pk_mul_f32 v[160:161], v[84:85], v[64:65] op_sel_hi:[0,1]
	v_add_f32_dpp v164, v164, v164 quad_perm:[2,3,0,1] row_mask:0xf bank_mask:0xf bound_ctrl:1
	v_add_f32_dpp v165, v165, v165 quad_perm:[2,3,0,1] row_mask:0xf bank_mask:0xf bound_ctrl:1
	v_pk_mul_f32 v[162:163], v[84:85], v[66:67] op_sel_hi:[0,1]
	v_add_f32_dpp v164, v164, v164 row_half_mirror row_mask:0xf bank_mask:0xf bound_ctrl:1
	v_add_f32_dpp v165, v165, v165 row_half_mirror row_mask:0xf bank_mask:0xf bound_ctrl:1
	s_nop 0
	v_add_f32_dpp v164, v164, v164 row_mirror row_mask:0xf bank_mask:0xf bound_ctrl:1
	v_add_f32_dpp v165, v165, v165 row_mirror row_mask:0xf bank_mask:0xf bound_ctrl:1
	v_pk_fma_f32 v[126:127], v[164:165], v[52:53], v[156:157] op_sel_hi:[0,1,1]
	v_cndmask_b32_e64 v11, v11, v165, s[10:11]
	s_lshl_b64 s[10:11], s[10:11], 1
	v_pk_fma_f32 v[128:129], v[164:165], v[54:55], v[158:159] op_sel_hi:[0,1,1]
	s_waitcnt lgkmcnt(6)
	ds_read_b128 v[132:135], v219 offset:17408
	ds_read_b32 v152, v218 offset:18176
	ds_read_b128 v[136:139], v219 offset:17664
	ds_read_b128 v[140:143], v219 offset:17152
	ds_read_b128 v[144:147], v219 offset:17920
	ds_read_b128 v[148:151], v219 offset:16896
	v_mul_f32_e32 v164, v126, v68
	v_mul_f32_e32 v165, v126, v56
	v_fma_f32 v164, v127, v69, v164
	v_fma_f32 v165, v127, v57, v165
	v_fma_f32 v164, v128, v70, v164
	v_fma_f32 v165, v128, v58, v165
	v_fma_f32 v164, v129, v71, v164
	v_fma_f32 v165, v129, v59, v165
	v_pk_fma_f32 v[160:161], v[126:127], v[72:73], v[160:161]
	v_pk_fma_f32 v[162:163], v[128:129], v[74:75], v[162:163]
	v_add_f32_dpp v164, v164, v164 quad_perm:[1,0,3,2] row_mask:0xf bank_mask:0xf bound_ctrl:1
	v_add_f32_dpp v165, v165, v165 quad_perm:[1,0,3,2] row_mask:0xf bank_mask:0xf bound_ctrl:1
	s_waitcnt lgkmcnt(10)
	v_pk_mul_f32 v[156:157], v[108:109], v[88:89] op_sel_hi:[0,1]
	v_add_f32_dpp v164, v164, v164 quad_perm:[2,3,0,1] row_mask:0xf bank_mask:0xf bound_ctrl:1
	v_add_f32_dpp v165, v165, v165 quad_perm:[2,3,0,1] row_mask:0xf bank_mask:0xf bound_ctrl:1
	v_pk_mul_f32 v[158:159], v[108:109], v[90:91] op_sel_hi:[0,1]
	v_add_f32_dpp v164, v164, v164 row_half_mirror row_mask:0xf bank_mask:0xf bound_ctrl:1
	v_add_f32_dpp v165, v165, v165 row_half_mirror row_mask:0xf bank_mask:0xf bound_ctrl:1
	s_nop 0
	v_add_f32_dpp v164, v164, v164 row_mirror row_mask:0xf bank_mask:0xf bound_ctrl:1
	v_add_f32_dpp v165, v165, v165 row_mirror row_mask:0xf bank_mask:0xf bound_ctrl:1
	v_pk_fma_f32 v[126:127], v[164:165], v[76:77], v[160:161] op_sel_hi:[0,1,1]
	v_cndmask_b32_e64 v11, v11, v165, s[10:11]
	s_lshl_b64 s[10:11], s[10:11], 1
	v_pk_fma_f32 v[128:129], v[164:165], v[78:79], v[162:163] op_sel_hi:[0,1,1]
	s_waitcnt lgkmcnt(6)
	ds_read_b128 v[40:43], v219 offset:18944
	ds_read_b32 v60, v218 offset:19712
	ds_read_b128 v[44:47], v219 offset:19200
	ds_read_b128 v[48:51], v219 offset:18688
	ds_read_b128 v[52:55], v219 offset:19456
	ds_read_b128 v[56:59], v219 offset:18432
	v_mul_f32_e32 v164, v126, v92
	v_mul_f32_e32 v165, v126, v80
	v_fma_f32 v164, v127, v93, v164
	v_fma_f32 v165, v127, v81, v165
	v_fma_f32 v164, v128, v94, v164
	v_fma_f32 v165, v128, v82, v165
	v_fma_f32 v164, v129, v95, v164
	v_fma_f32 v165, v129, v83, v165
	v_pk_fma_f32 v[156:157], v[126:127], v[96:97], v[156:157]
	v_pk_fma_f32 v[158:159], v[128:129], v[98:99], v[158:159]
	v_add_f32_dpp v164, v164, v164 quad_perm:[1,0,3,2] row_mask:0xf bank_mask:0xf bound_ctrl:1
	v_add_f32_dpp v165, v165, v165 quad_perm:[1,0,3,2] row_mask:0xf bank_mask:0xf bound_ctrl:1
	s_waitcnt lgkmcnt(10)
	v_pk_mul_f32 v[160:161], v[152:153], v[132:133] op_sel_hi:[0,1]
	v_add_f32_dpp v164, v164, v164 quad_perm:[2,3,0,1] row_mask:0xf bank_mask:0xf bound_ctrl:1
	v_add_f32_dpp v165, v165, v165 quad_perm:[2,3,0,1] row_mask:0xf bank_mask:0xf bound_ctrl:1
	v_pk_mul_f32 v[162:163], v[152:153], v[134:135] op_sel_hi:[0,1]
	v_add_f32_dpp v164, v164, v164 row_half_mirror row_mask:0xf bank_mask:0xf bound_ctrl:1
	v_add_f32_dpp v165, v165, v165 row_half_mirror row_mask:0xf bank_mask:0xf bound_ctrl:1
	s_nop 0
	v_add_f32_dpp v164, v164, v164 row_mirror row_mask:0xf bank_mask:0xf bound_ctrl:1
	v_add_f32_dpp v165, v165, v165 row_mirror row_mask:0xf bank_mask:0xf bound_ctrl:1
	v_pk_fma_f32 v[126:127], v[164:165], v[100:101], v[156:157] op_sel_hi:[0,1,1]
	v_cndmask_b32_e64 v11, v11, v165, s[10:11]
	s_lshl_b64 s[10:11], s[10:11], 1
	v_pk_fma_f32 v[128:129], v[164:165], v[102:103], v[158:159] op_sel_hi:[0,1,1]
	s_waitcnt lgkmcnt(6)
	ds_read_b128 v[64:67], v219 offset:20480
	ds_read_b32 v84, v218 offset:21248
	ds_read_b128 v[68:71], v219 offset:20736
	ds_read_b128 v[72:75], v219 offset:20224
	ds_read_b128 v[76:79], v219 offset:20992
	ds_read_b128 v[80:83], v219 offset:19968
	v_mul_f32_e32 v164, v126, v136
	v_mul_f32_e32 v165, v126, v104
	v_fma_f32 v164, v127, v137, v164
	v_fma_f32 v165, v127, v105, v165
	v_fma_f32 v164, v128, v138, v164
	v_fma_f32 v165, v128, v106, v165
	v_fma_f32 v164, v129, v139, v164
	v_fma_f32 v165, v129, v107, v165
	v_pk_fma_f32 v[160:161], v[126:127], v[140:141], v[160:161]
	v_pk_fma_f32 v[162:163], v[128:129], v[142:143], v[162:163]
	v_add_f32_dpp v164, v164, v164 quad_perm:[1,0,3,2] row_mask:0xf bank_mask:0xf bound_ctrl:1
	v_add_f32_dpp v165, v165, v165 quad_perm:[1,0,3,2] row_mask:0xf bank_mask:0xf bound_ctrl:1
	s_waitcnt lgkmcnt(10)
	v_pk_mul_f32 v[156:157], v[60:61], v[40:41] op_sel_hi:[0,1]
	v_add_f32_dpp v164, v164, v164 quad_perm:[2,3,0,1] row_mask:0xf bank_mask:0xf bound_ctrl:1
	v_add_f32_dpp v165, v165, v165 quad_perm:[2,3,0,1] row_mask:0xf bank_mask:0xf bound_ctrl:1
	v_pk_mul_f32 v[158:159], v[60:61], v[42:43] op_sel_hi:[0,1]
	v_add_f32_dpp v164, v164, v164 row_half_mirror row_mask:0xf bank_mask:0xf bound_ctrl:1
	v_add_f32_dpp v165, v165, v165 row_half_mirror row_mask:0xf bank_mask:0xf bound_ctrl:1
	s_nop 0
	v_add_f32_dpp v164, v164, v164 row_mirror row_mask:0xf bank_mask:0xf bound_ctrl:1
	v_add_f32_dpp v165, v165, v165 row_mirror row_mask:0xf bank_mask:0xf bound_ctrl:1
	v_pk_fma_f32 v[126:127], v[164:165], v[144:145], v[160:161] op_sel_hi:[0,1,1]
	v_cndmask_b32_e64 v11, v11, v165, s[10:11]
	s_lshl_b64 s[10:11], s[10:11], 1
	v_pk_fma_f32 v[128:129], v[164:165], v[146:147], v[162:163] op_sel_hi:[0,1,1]
	s_waitcnt lgkmcnt(6)
	ds_read_b128 v[88:91], v219 offset:22016
	ds_read_b32 v108, v218 offset:22784
	ds_read_b128 v[92:95], v219 offset:22272
	ds_read_b128 v[96:99], v219 offset:21760
	ds_read_b128 v[100:103], v219 offset:22528
	ds_read_b128 v[104:107], v219 offset:21504
	v_mul_f32_e32 v164, v126, v44
	v_mul_f32_e32 v165, v126, v148
	v_fma_f32 v164, v127, v45, v164
	v_fma_f32 v165, v127, v149, v165
	v_fma_f32 v164, v128, v46, v164
	v_fma_f32 v165, v128, v150, v165
	v_fma_f32 v164, v129, v47, v164
	v_fma_f32 v165, v129, v151, v165
	v_pk_fma_f32 v[156:157], v[126:127], v[48:49], v[156:157]
	v_pk_fma_f32 v[158:159], v[128:129], v[50:51], v[158:159]
	v_add_f32_dpp v164, v164, v164 quad_perm:[1,0,3,2] row_mask:0xf bank_mask:0xf bound_ctrl:1
	v_add_f32_dpp v165, v165, v165 quad_perm:[1,0,3,2] row_mask:0xf bank_mask:0xf bound_ctrl:1
	s_waitcnt lgkmcnt(10)
	v_pk_mul_f32 v[160:161], v[84:85], v[64:65] op_sel_hi:[0,1]
	v_add_f32_dpp v164, v164, v164 quad_perm:[2,3,0,1] row_mask:0xf bank_mask:0xf bound_ctrl:1
	v_add_f32_dpp v165, v165, v165 quad_perm:[2,3,0,1] row_mask:0xf bank_mask:0xf bound_ctrl:1
	v_pk_mul_f32 v[162:163], v[84:85], v[66:67] op_sel_hi:[0,1]
	v_add_f32_dpp v164, v164, v164 row_half_mirror row_mask:0xf bank_mask:0xf bound_ctrl:1
	v_add_f32_dpp v165, v165, v165 row_half_mirror row_mask:0xf bank_mask:0xf bound_ctrl:1
	s_nop 0
	v_add_f32_dpp v164, v164, v164 row_mirror row_mask:0xf bank_mask:0xf bound_ctrl:1
	v_add_f32_dpp v165, v165, v165 row_mirror row_mask:0xf bank_mask:0xf bound_ctrl:1
	v_pk_fma_f32 v[126:127], v[164:165], v[52:53], v[156:157] op_sel_hi:[0,1,1]
	v_cndmask_b32_e64 v11, v11, v165, s[10:11]
	s_lshl_b64 s[10:11], s[10:11], 1
	v_pk_fma_f32 v[128:129], v[164:165], v[54:55], v[158:159] op_sel_hi:[0,1,1]
	s_waitcnt lgkmcnt(6)
	ds_read_b128 v[132:135], v219 offset:23552
	ds_read_b32 v152, v218 offset:24320
	ds_read_b128 v[136:139], v219 offset:23808
	ds_read_b128 v[140:143], v219 offset:23296
	ds_read_b128 v[144:147], v219 offset:24064
	ds_read_b128 v[148:151], v219 offset:23040
	v_mul_f32_e32 v164, v126, v68
	v_mul_f32_e32 v165, v126, v56
	v_fma_f32 v164, v127, v69, v164
	v_fma_f32 v165, v127, v57, v165
	v_fma_f32 v164, v128, v70, v164
	v_fma_f32 v165, v128, v58, v165
	v_fma_f32 v164, v129, v71, v164
	v_fma_f32 v165, v129, v59, v165
	v_pk_fma_f32 v[160:161], v[126:127], v[72:73], v[160:161]
	v_pk_fma_f32 v[162:163], v[128:129], v[74:75], v[162:163]
	v_add_f32_dpp v164, v164, v164 quad_perm:[1,0,3,2] row_mask:0xf bank_mask:0xf bound_ctrl:1
	v_add_f32_dpp v165, v165, v165 quad_perm:[1,0,3,2] row_mask:0xf bank_mask:0xf bound_ctrl:1
	s_waitcnt lgkmcnt(10)
	v_pk_mul_f32 v[156:157], v[108:109], v[88:89] op_sel_hi:[0,1]
	v_add_f32_dpp v164, v164, v164 quad_perm:[2,3,0,1] row_mask:0xf bank_mask:0xf bound_ctrl:1
	v_add_f32_dpp v165, v165, v165 quad_perm:[2,3,0,1] row_mask:0xf bank_mask:0xf bound_ctrl:1
	v_pk_mul_f32 v[158:159], v[108:109], v[90:91] op_sel_hi:[0,1]
	v_add_f32_dpp v164, v164, v164 row_half_mirror row_mask:0xf bank_mask:0xf bound_ctrl:1
	v_add_f32_dpp v165, v165, v165 row_half_mirror row_mask:0xf bank_mask:0xf bound_ctrl:1
	s_nop 0
	v_add_f32_dpp v164, v164, v164 row_mirror row_mask:0xf bank_mask:0xf bound_ctrl:1
	v_add_f32_dpp v165, v165, v165 row_mirror row_mask:0xf bank_mask:0xf bound_ctrl:1
	v_pk_fma_f32 v[126:127], v[164:165], v[76:77], v[160:161] op_sel_hi:[0,1,1]
	v_cndmask_b32_e64 v11, v11, v165, s[10:11]
	s_lshl_b64 s[10:11], s[10:11], 1
	v_pk_fma_f32 v[128:129], v[164:165], v[78:79], v[162:163] op_sel_hi:[0,1,1]
	s_waitcnt lgkmcnt(6)
	v_mul_f32_e32 v164, v126, v92
	v_mul_f32_e32 v165, v126, v80
	v_fma_f32 v164, v127, v93, v164
	v_fma_f32 v165, v127, v81, v165
	v_fma_f32 v164, v128, v94, v164
	v_fma_f32 v165, v128, v82, v165
	v_fma_f32 v164, v129, v95, v164
	v_fma_f32 v165, v129, v83, v165
	v_pk_fma_f32 v[156:157], v[126:127], v[96:97], v[156:157]
	v_pk_fma_f32 v[158:159], v[128:129], v[98:99], v[158:159]
	v_add_f32_dpp v164, v164, v164 quad_perm:[1,0,3,2] row_mask:0xf bank_mask:0xf bound_ctrl:1
	v_add_f32_dpp v165, v165, v165 quad_perm:[1,0,3,2] row_mask:0xf bank_mask:0xf bound_ctrl:1
	s_waitcnt lgkmcnt(4)
	v_pk_mul_f32 v[160:161], v[152:153], v[132:133] op_sel_hi:[0,1]
	v_add_f32_dpp v164, v164, v164 quad_perm:[2,3,0,1] row_mask:0xf bank_mask:0xf bound_ctrl:1
	v_add_f32_dpp v165, v165, v165 quad_perm:[2,3,0,1] row_mask:0xf bank_mask:0xf bound_ctrl:1
	v_pk_mul_f32 v[162:163], v[152:153], v[134:135] op_sel_hi:[0,1]
	v_add_f32_dpp v164, v164, v164 row_half_mirror row_mask:0xf bank_mask:0xf bound_ctrl:1
	v_add_f32_dpp v165, v165, v165 row_half_mirror row_mask:0xf bank_mask:0xf bound_ctrl:1
	s_nop 0
	v_add_f32_dpp v164, v164, v164 row_mirror row_mask:0xf bank_mask:0xf bound_ctrl:1
	v_add_f32_dpp v165, v165, v165 row_mirror row_mask:0xf bank_mask:0xf bound_ctrl:1
	v_pk_fma_f32 v[126:127], v[164:165], v[100:101], v[156:157] op_sel_hi:[0,1,1]
	v_cndmask_b32_e64 v11, v11, v165, s[10:11]
	s_lshl_b64 s[10:11], s[10:11], 1
	v_pk_fma_f32 v[128:129], v[164:165], v[102:103], v[158:159] op_sel_hi:[0,1,1]
	s_waitcnt lgkmcnt(0)
; DI unsigned short f2bf(float x) { return (unsigned short)(pack2(x, 0.f) & 0xffffu); }
; DI float bflo(unsigned u) { return __uint_as_float(u << 16); }
; DI float bfhi(unsigned u) { return __uint_as_float(u & 0xffff0000u); }
; DI void scan_prep(u32x2 (&raw)[5], const float (&kkw)[4], const float (&kaw)[4], float* dst  ) {
;     ...
;   float r[4] = {bflo(raw[0].x), bfhi(raw[0].x), bflo(raw[0].y), bfhi(raw[0].y)};
;   float k[4] = {bflo(raw[1].x), bfhi(raw[1].x), bflo(raw[1].y), bfhi(raw[1].y)};
;   float v[4] = {bflo(raw[2].x), bfhi(raw[2].x), bflo(raw[2].y), bfhi(raw[2].y)};
;   float e[4] = {bflo(raw[3].x), bfhi(raw[3].x), bflo(raw[3].y), bfhi(raw[3].y)};
;   float a[4] = {bflo(raw[4].x), bfhi(raw[4].x), bflo(raw[4].y), bfhi(raw[4].y)};
;   float kr[4], ss = 0.f;
; #pragma unroll
;   for (int i = 0; i < 4; ++i) { kr[i] = mul_(k[i], kkw[i]); ss = (i < 3) ? fma_(kr[i], kr[i], ss) : fma_n_(kr[i], kr[i], ss); }
;   ss = reduce16(ss);
;   const float inv = __builtin_amdgcn_rcpf(fmaxf(__builtin_amdgcn_sqrtf(ss), 1e-12f));
;   float w4[4], kd4[4], a4[4], b4[4];
; #pragma unroll
;   for (int i = 0; i < 4; ++i) {
;     float kn = kr[i] * inv;
;     w4[i] = __builtin_amdgcn_exp2f(mul_(e[i], -LOG2E));
;     kd4[i] = mul_(k[i], fma_(add_(a[i], -1.f), kaw[i], 1.f));
;     a4[i] = -kn;
;     b4[i] = mul_(kn, a[i]);
;   }
;   *(float4*)(dst) = float4{r[0], r[1], r[2], r[3]};
;   *(float4*)(dst + 64) = float4{w4[0], w4[1], w4[2], w4[3]};
;   *(float4*)(dst + 128) = float4{kd4[0], kd4[1], kd4[2], kd4[3]};
;   *(float4*)(dst + 192) = float4{a4[0], a4[1], a4[2], a4[3]};
;   *(float4*)(dst + 256) = float4{b4[0], b4[1], b4[2], b4[3]};
;   *(float4*)(dst + 320) = float4{v[0], v[1], v[2], v[3]};
; DI void phase_scan(const Params& P, int l, char* smem) {
;     ...
;       {
;         float4 Ar[4], Aw[4], Ak[4], Aa[4], Ab[4], Br[4], Bw[4], Bk[4], Ba[4], Bb[4];
;         float Av[4], Bv[4];
;         SCAN_LOAD(A, 0);
;         SCAN_LOAD(B, 1);
;         SCAN_STEPS(A, 0);
;         SCAN_LOAD(A, 2);
;         SCAN_STEPS(B, 1);
;         SCAN_LOAD(B, 3);
;         SCAN_STEPS(A, 2);
;         SCAN_STEPS(B, 3);
;       }
;     ...
;       {
;         int i = c * 16 + kl;
;         int s = dir == 0 ? i : (i < 256 ? 255 - i : 16895 - i);
;         Y[((size_t)b * SB + s) * 1024 + st] = f2bf(ykeep);
;       }
	v_mul_f32_e32 v164, v126, v136
	v_mul_f32_e32 v165, v126, v104
	v_fma_f32 v164, v127, v137, v164
	v_fma_f32 v165, v127, v105, v165
	v_fma_f32 v164, v128, v138, v164
	v_fma_f32 v165, v128, v106, v165
	v_fma_f32 v164, v129, v139, v164
	v_fma_f32 v165, v129, v107, v165
	v_pk_fma_f32 v[160:161], v[126:127], v[140:141], v[160:161]
	v_pk_fma_f32 v[162:163], v[128:129], v[142:143], v[162:163]
	v_add_f32_dpp v164, v164, v164 quad_perm:[1,0,3,2] row_mask:0xf bank_mask:0xf bound_ctrl:1
	v_add_f32_dpp v165, v165, v165 quad_perm:[1,0,3,2] row_mask:0xf bank_mask:0xf bound_ctrl:1
	s_nop 0
	v_add_f32_dpp v164, v164, v164 quad_perm:[2,3,0,1] row_mask:0xf bank_mask:0xf bound_ctrl:1
	v_add_f32_dpp v165, v165, v165 quad_perm:[2,3,0,1] row_mask:0xf bank_mask:0xf bound_ctrl:1
	s_nop 0
	v_add_f32_dpp v164, v164, v164 row_half_mirror row_mask:0xf bank_mask:0xf bound_ctrl:1
	v_add_f32_dpp v165, v165, v165 row_half_mirror row_mask:0xf bank_mask:0xf bound_ctrl:1
	s_nop 0
	v_add_f32_dpp v164, v164, v164 row_mirror row_mask:0xf bank_mask:0xf bound_ctrl:1
	v_add_f32_dpp v165, v165, v165 row_mirror row_mask:0xf bank_mask:0xf bound_ctrl:1
	v_pk_fma_f32 v[126:127], v[164:165], v[144:145], v[160:161] op_sel_hi:[0,1,1]
	v_cndmask_b32_e64 v11, v11, v165, s[10:11]
	s_lshl_b64 s[10:11], s[10:11], 1
	v_pk_fma_f32 v[128:129], v[164:165], v[146:147], v[162:163] op_sel_hi:[0,1,1]
	v_mul_f32_e32 v165, v126, v148
	v_fma_f32 v165, v127, v149, v165
	v_fma_f32 v165, v128, v150, v165
	v_fma_f32 v165, v129, v151, v165
	s_nop 1
	v_add_f32_dpp v165, v165, v165 quad_perm:[1,0,3,2] row_mask:0xf bank_mask:0xf bound_ctrl:1
	s_nop 1
	v_add_f32_dpp v165, v165, v165 quad_perm:[2,3,0,1] row_mask:0xf bank_mask:0xf bound_ctrl:1
	s_nop 1
	v_add_f32_dpp v165, v165, v165 row_half_mirror row_mask:0xf bank_mask:0xf bound_ctrl:1
	s_nop 1
	v_add_f32_dpp v165, v165, v165 row_mirror row_mask:0xf bank_mask:0xf bound_ctrl:1
	v_cndmask_b32_e64 v11, v11, v165, s[10:11]
	v_add_u32_e32 v10, s9, v216
	v_cndmask_b32_e64 v10, v10, v217, s[4:5]
	v_cvt_pk_bf16_f32 v12, v11, s0
	v_ashrrev_i32_e32 v11, 31, v10
	v_lshl_add_u64 v[10:11], s[6:7], 0, v[10:11]
	v_lshlrev_b64 v[10:11], 11, v[10:11]
	v_lshl_add_u64 v[10:11], v[188:189], 0, v[10:11]
	global_store_short v[10:11], v12, off
	s_cbranch_vccnz .LBB0_510
	s_waitcnt vmcnt(4)
	v_lshlrev_b32_e32 v11, 16, v176
	v_mul_f32 v12, v11, v2
	v_and_b32_e32 v15, 0xffff0000, v176
	v_fma_f32 v10, v12, v12, v1
	v_mul_f32 v13, v15, v3
	v_lshlrev_b32_e32 v16, 16, v177
	v_fma_f32 v10, v13, v13, v10
	v_mul_f32 v28, v16, v4
	v_and_b32_e32 v17, 0xffff0000, v177
	v_fma_f32 v10, v28, v28, v10
	v_mul_f32 v29, v17, v5
	s_waitcnt vmcnt(2)
	v_lshlrev_b32_e32 v14, 16, v178
	v_fma_f32 v10, v29, v29, v10
	s_nop 1
	s_waitcnt vmcnt(1)
	v_lshlrev_b32_e32 v26, 16, v182
	v_lshlrev_b32_e32 v33, 16, v179
	v_add_f32_dpp v10, v10, v10 quad_perm:[1,0,3,2] row_mask:0xf bank_mask:0xf bound_ctrl:1
	v_and_b32_e32 v27, 0xffff0000, v182
	v_and_b32_e32 v30, 0xffff0000, v178
	v_add_f32_dpp v10, v10, v10 quad_perm:[2,3,0,1] row_mask:0xf bank_mask:0xf bound_ctrl:1
	v_lshlrev_b32_e32 v35, 16, v183
	v_and_b32_e32 v37, 0xffff0000, v179
	v_add_f32_dpp v10, v10, v10 row_half_mirror row_mask:0xf bank_mask:0xf bound_ctrl:1
	s_bitcmp1_b32 s8, 0
	s_cselect_b32 s9, 0x6000, 0
	v_add_f32_dpp v10, v10, v10 row_mirror row_mask:0xf bank_mask:0xf bound_ctrl:1
	v_sqrt_f32_e32 v10, v10
	v_add_u32_e32 v34, s9, v192
	v_and_b32_e32 v36, 0xffff0000, v183
	v_and_b32_e32 v25, 0xffff0000, v175
	v_max_f32_e32 v10, 0x2b8cbccc, v10
	v_rcp_f32_e32 v32, v10
	v_mul_f32 v10, v14, v196
	v_add_f32 v14, v26, v197
	v_lshlrev_b32_e32 v24, 16, v175
	v_fma_f32 v14, v14, v6, v198
	v_pk_mul_f32 v[12:13], v[12:13], v[32:33] op_sel_hi:[1,0]
	v_mul_f32 v14, v11, v14
	v_mul_f32 v11, v30, v196
	v_add_f32 v30, v27, v197
	v_exp_f32_e32 v10, v10
	v_xor_b32_e32 v31, 0x80000000, v13
	v_mul_f32 v27, v13, v27
	v_add_f32 v13, v35, v197
	v_fma_f32 v30, v30, v7, v198
	v_mul_f32 v26, v12, v26
	v_exp_f32_e32 v11, v11
	v_fma_f32 v13, v13, v8, v198
	v_mul_f32 v15, v15, v30
	v_xor_b32_e32 v30, 0x80000000, v12
	v_mul_f32 v12, v33, v196
	v_mul_f32 v16, v16, v13
	v_mul_f32 v13, v37, v196
	v_pk_mul_f32 v[28:29], v[28:29], v[32:33] op_sel_hi:[1,0]
	v_exp_f32_e32 v12, v12
	v_exp_f32_e32 v13, v13
	v_and_b32_e32 v23, 0xffff0000, v174
	v_lshlrev_b32_e32 v22, 16, v174
	v_xor_b32_e32 v32, 0x80000000, v28
	v_mul_f32 v28, v28, v35
	v_add_f32 v35, v36, v197
	v_and_b32_e32 v21, 0xffff0000, v181
	v_lshlrev_b32_e32 v20, 16, v181
	v_and_b32_e32 v19, 0xffff0000, v180
	v_lshlrev_b32_e32 v18, 16, v180
	v_xor_b32_e32 v33, 0x80000000, v29
	v_fma_f32 v35, v35, v9, v198
	v_mul_f32 v29, v29, v36
	s_nop 0
	v_mul_f32 v17, v17, v35
	ds_write_b128 v34, v[22:25]
	ds_write_b128 v34, v[10:13] offset:256
	ds_write_b128 v34, v[14:17] offset:512
	ds_write_b128 v34, v[30:33] offset:768
	ds_write_b128 v34, v[26:29] offset:1024
	ds_write_b128 v34, v[18:21] offset:1280
	s_branch .LBB0_510

; DI void cfence() { asm volatile("" ::: "memory"); }
; DI int swz4(int row) { const int g = (row >> 2) & 3; return ((g << 1) ^ ((g >> 1) * 3)) & 3; }
; #define LSTORE2(RA, RB, P)                                       \
;   {                                                              \
;     char* dA_ = smem + (P) * 24576 + wofs;                       \
;     _Pragma("unroll") for (int j = 0; j < 4; ++j) *(u32x4*)(dA_ + j * 4096) = RA[j]; \
;     _Pragma("unroll") for (int j = 0; j < 2; ++j) *(u32x4*)(dA_ + 16384 + j * 4096) = RB[j]; \
;   }
; DI void gemm256_kloop(f32x4 (&acc)[8][4], const bf16_t* __restrict__ A, int lda, const bf16_t* __restrict__ Bt, int ldb,
;                       int K, int b, int s0, int col0, char* smem) {
;     ...
;   GLOAD2(xa, xb, 0);
;   GLOAD2(ya, yb, 1);
;   cfence();
;   LSTORE2(xa, xb, 0);
;   __syncthreads();
;   const int co = ((fq ^ swz4(fr)) << 4);
;   const int aofs = (wr * 128 + fr) * 64 + co, bofs = (wc * 64 + fr) * 64 + co;
;   for (int kt = 0; kt < nk; kt += 2) {
;     GLOAD2(xa, xb, kt + 2);
;     cfence();
;     COMPUTE2(0);
;     LSTORE2(ya, yb, 1);
;     __syncthreads();
;     if (kt + 1 < nk) {
;       GLOAD2(ya, yb, kt + 3);
;       cfence();
;       COMPUTE2(1);
;       LSTORE2(xa, xb, 0);
;       __syncthreads();
;     }
;   }
.LBB0_578:
	s_add_i32 s7, s6, 2
	s_cmp_lt_u32 s6, 62
	s_cselect_b64 s[8:9], -1, 0
	s_and_b64 vcc, s[8:9], exec
	s_cselect_b32 s8, s3, 0xfc0
	buffer_load_dwordx4 v[162:165], v0, s[20:23], s8 offen
	buffer_load_dwordx4 v[166:169], v154, s[20:23], s8 offen
	buffer_load_dwordx4 v[170:173], v155, s[20:23], s8 offen
	buffer_load_dwordx4 v[174:177], v156, s[20:23], s8 offen
	buffer_load_dwordx4 v[178:181], v157, s[12:15], s8 offen
	buffer_load_dwordx4 v[182:185], v158, s[12:15], s8 offen
	ds_read_b128 v[236:239], v160 offset:16384
	ds_read_b128 v[240:243], v160 offset:17408
	ds_read_b128 v[244:247], v160 offset:18432
	ds_read_b128 v[248:251], v160 offset:19456
	ds_read_b128 v[186:189], v161
	ds_read_b128 v[190:193], v161 offset:1024
	ds_read_b128 v[212:215], v161 offset:2048
	ds_read_b128 v[216:219], v161 offset:3072
	ds_read_b128 v[220:223], v161 offset:4096
	ds_read_b128 v[224:227], v161 offset:5120
	ds_read_b128 v[228:231], v161 offset:6144
	ds_read_b128 v[232:235], v161 offset:7168
	s_setprio 1
	s_waitcnt lgkmcnt(7)
	v_mfma_f32_16x16x32_bf16 v[126:129], v[186:189], v[236:239], v[126:129]
	v_mfma_f32_16x16x32_bf16 v[122:125], v[186:189], v[240:243], v[122:125]
	v_mfma_f32_16x16x32_bf16 v[118:121], v[186:189], v[244:247], v[118:121]
	v_mfma_f32_16x16x32_bf16 v[114:117], v[186:189], v[248:251], v[114:117]
	s_waitcnt lgkmcnt(6)
	v_mfma_f32_16x16x32_bf16 v[110:113], v[190:193], v[236:239], v[110:113]
	v_mfma_f32_16x16x32_bf16 v[106:109], v[190:193], v[240:243], v[106:109]
	v_mfma_f32_16x16x32_bf16 v[102:105], v[190:193], v[244:247], v[102:105]
	v_mfma_f32_16x16x32_bf16 v[98:101], v[190:193], v[248:251], v[98:101]
	s_waitcnt lgkmcnt(5)
	v_mfma_f32_16x16x32_bf16 v[94:97], v[212:215], v[236:239], v[94:97]
	v_mfma_f32_16x16x32_bf16 v[90:93], v[212:215], v[240:243], v[90:93]
	v_mfma_f32_16x16x32_bf16 v[86:89], v[212:215], v[244:247], v[86:89]
	v_mfma_f32_16x16x32_bf16 v[82:85], v[212:215], v[248:251], v[82:85]
	s_waitcnt lgkmcnt(4)
	v_mfma_f32_16x16x32_bf16 v[78:81], v[216:219], v[236:239], v[78:81]
	v_mfma_f32_16x16x32_bf16 v[74:77], v[216:219], v[240:243], v[74:77]
	v_mfma_f32_16x16x32_bf16 v[70:73], v[216:219], v[244:247], v[70:73]
	v_mfma_f32_16x16x32_bf16 v[66:69], v[216:219], v[248:251], v[66:69]
	s_waitcnt lgkmcnt(3)
	v_mfma_f32_16x16x32_bf16 v[62:65], v[220:223], v[236:239], v[62:65]
	v_mfma_f32_16x16x32_bf16 v[58:61], v[220:223], v[240:243], v[58:61]
	s_waitcnt vmcnt(9)
	ds_write_b128 v159, v[138:141] offset:24576
	v_mfma_f32_16x16x32_bf16 v[54:57], v[220:223], v[244:247], v[54:57]
	v_mfma_f32_16x16x32_bf16 v[50:53], v[220:223], v[248:251], v[50:53]
	s_waitcnt vmcnt(8)
	ds_write_b128 v159, v[142:145] offset:28672
	s_waitcnt lgkmcnt(4)
	v_mfma_f32_16x16x32_bf16 v[46:49], v[224:227], v[236:239], v[46:49]
	v_mfma_f32_16x16x32_bf16 v[42:45], v[224:227], v[240:243], v[42:45]
	s_waitcnt vmcnt(7)
	ds_write_b128 v159, v[146:149] offset:32768
	v_mfma_f32_16x16x32_bf16 v[38:41], v[224:227], v[244:247], v[38:41]
	v_mfma_f32_16x16x32_bf16 v[34:37], v[224:227], v[248:251], v[34:37]
	s_waitcnt vmcnt(6)
	ds_write_b128 v159, v[150:153] offset:36864
	s_waitcnt lgkmcnt(5)
	v_mfma_f32_16x16x32_bf16 v[30:33], v[228:231], v[236:239], v[30:33]
	v_mfma_f32_16x16x32_bf16 v[26:29], v[228:231], v[240:243], v[26:29]
	ds_write_b128 v159, v[130:133] offset:40960
	v_mfma_f32_16x16x32_bf16 v[22:25], v[228:231], v[244:247], v[22:25]
	v_mfma_f32_16x16x32_bf16 v[18:21], v[228:231], v[248:251], v[18:21]
	ds_write_b128 v159, v[134:137] offset:45056
	s_waitcnt lgkmcnt(6)
	v_mfma_f32_16x16x32_bf16 v[14:17], v[232:235], v[236:239], v[14:17]
	v_mfma_f32_16x16x32_bf16 v[10:13], v[232:235], v[240:243], v[10:13]
	v_mfma_f32_16x16x32_bf16 v[6:9], v[232:235], v[244:247], v[6:9]
	v_mfma_f32_16x16x32_bf16 v[2:5], v[232:235], v[248:251], v[2:5]
	s_setprio 0
	s_min_u32 s6, s6, 60
	s_lshl_b32 s6, s6, 6
	s_addk_i32 s6, 0xc0
	s_waitcnt lgkmcnt(0)
	s_barrier
; DI void cfence() { asm volatile("" ::: "memory"); }
; DI int swz4(int row) { const int g = (row >> 2) & 3; return ((g << 1) ^ ((g >> 1) * 3)) & 3; }
; #define LSTORE2(RA, RB, P)                                       \
;   {                                                              \
;     char* dA_ = smem + (P) * 24576 + wofs;                       \
;     _Pragma("unroll") for (int j = 0; j < 4; ++j) *(u32x4*)(dA_ + j * 4096) = RA[j]; \
;     _Pragma("unroll") for (int j = 0; j < 2; ++j) *(u32x4*)(dA_ + 16384 + j * 4096) = RB[j]; \
;   }
; DI void gemm256_kloop(f32x4 (&acc)[8][4], const bf16_t* __restrict__ A, int lda, const bf16_t* __restrict__ Bt, int ldb,
;                       int K, int b, int s0, int col0, char* smem) {
;     ...
;   GLOAD2(xa, xb, 0);
;   GLOAD2(ya, yb, 1);
;   cfence();
;   LSTORE2(xa, xb, 0);
;   __syncthreads();
;   const int co = ((fq ^ swz4(fr)) << 4);
;   const int aofs = (wr * 128 + fr) * 64 + co, bofs = (wc * 64 + fr) * 64 + co;
;   for (int kt = 0; kt < nk; kt += 2) {
;     GLOAD2(xa, xb, kt + 2);
;     cfence();
;     COMPUTE2(0);
;     LSTORE2(ya, yb, 1);
;     __syncthreads();
;     if (kt + 1 < nk) {
;       GLOAD2(ya, yb, kt + 3);
;       cfence();
;       COMPUTE2(1);
;       LSTORE2(xa, xb, 0);
;       __syncthreads();
;     }
;   }
	buffer_load_dwordx4 v[138:141], v0, s[20:23], s6 offen
	buffer_load_dwordx4 v[142:145], v154, s[20:23], s6 offen
	buffer_load_dwordx4 v[146:149], v155, s[20:23], s6 offen
	buffer_load_dwordx4 v[150:153], v156, s[20:23], s6 offen
	buffer_load_dwordx4 v[130:133], v157, s[12:15], s6 offen
	buffer_load_dwordx4 v[134:137], v158, s[12:15], s6 offen
	ds_read_b128 v[236:239], v160 offset:40960
	ds_read_b128 v[240:243], v160 offset:41984
	ds_read_b128 v[244:247], v160 offset:43008
	ds_read_b128 v[248:251], v160 offset:44032
	ds_read_b128 v[186:189], v161 offset:24576
	ds_read_b128 v[190:193], v161 offset:25600
	ds_read_b128 v[212:215], v161 offset:26624
	ds_read_b128 v[216:219], v161 offset:27648
	ds_read_b128 v[220:223], v161 offset:28672
	ds_read_b128 v[224:227], v161 offset:29696
	ds_read_b128 v[228:231], v161 offset:30720
	ds_read_b128 v[232:235], v161 offset:31744
	s_setprio 1
	s_waitcnt lgkmcnt(7)
	v_mfma_f32_16x16x32_bf16 v[126:129], v[186:189], v[236:239], v[126:129]
	v_mfma_f32_16x16x32_bf16 v[122:125], v[186:189], v[240:243], v[122:125]
	v_mfma_f32_16x16x32_bf16 v[118:121], v[186:189], v[244:247], v[118:121]
	v_mfma_f32_16x16x32_bf16 v[114:117], v[186:189], v[248:251], v[114:117]
	s_waitcnt lgkmcnt(6)
	v_mfma_f32_16x16x32_bf16 v[110:113], v[190:193], v[236:239], v[110:113]
	v_mfma_f32_16x16x32_bf16 v[106:109], v[190:193], v[240:243], v[106:109]
	v_mfma_f32_16x16x32_bf16 v[102:105], v[190:193], v[244:247], v[102:105]
	v_mfma_f32_16x16x32_bf16 v[98:101], v[190:193], v[248:251], v[98:101]
	s_waitcnt lgkmcnt(5)
	v_mfma_f32_16x16x32_bf16 v[94:97], v[212:215], v[236:239], v[94:97]
	v_mfma_f32_16x16x32_bf16 v[90:93], v[212:215], v[240:243], v[90:93]
	v_mfma_f32_16x16x32_bf16 v[86:89], v[212:215], v[244:247], v[86:89]
	v_mfma_f32_16x16x32_bf16 v[82:85], v[212:215], v[248:251], v[82:85]
	s_waitcnt lgkmcnt(4)
	v_mfma_f32_16x16x32_bf16 v[78:81], v[216:219], v[236:239], v[78:81]
	v_mfma_f32_16x16x32_bf16 v[74:77], v[216:219], v[240:243], v[74:77]
	v_mfma_f32_16x16x32_bf16 v[70:73], v[216:219], v[244:247], v[70:73]
	v_mfma_f32_16x16x32_bf16 v[66:69], v[216:219], v[248:251], v[66:69]
	s_waitcnt lgkmcnt(3)
	v_mfma_f32_16x16x32_bf16 v[62:65], v[220:223], v[236:239], v[62:65]
	v_mfma_f32_16x16x32_bf16 v[58:61], v[220:223], v[240:243], v[58:61]
	s_waitcnt vmcnt(11)
	ds_write_b128 v159, v[162:165]
	v_mfma_f32_16x16x32_bf16 v[54:57], v[220:223], v[244:247], v[54:57]
	v_mfma_f32_16x16x32_bf16 v[50:53], v[220:223], v[248:251], v[50:53]
	s_waitcnt vmcnt(10)
	ds_write_b128 v159, v[166:169] offset:4096
	s_waitcnt lgkmcnt(4)
	v_mfma_f32_16x16x32_bf16 v[46:49], v[224:227], v[236:239], v[46:49]
	v_mfma_f32_16x16x32_bf16 v[42:45], v[224:227], v[240:243], v[42:45]
	s_waitcnt vmcnt(9)
	ds_write_b128 v159, v[170:173] offset:8192
	v_mfma_f32_16x16x32_bf16 v[38:41], v[224:227], v[244:247], v[38:41]
	v_mfma_f32_16x16x32_bf16 v[34:37], v[224:227], v[248:251], v[34:37]
	s_waitcnt vmcnt(8)
	ds_write_b128 v159, v[174:177] offset:12288
	s_waitcnt lgkmcnt(5)
	v_mfma_f32_16x16x32_bf16 v[30:33], v[228:231], v[236:239], v[30:33]
	v_mfma_f32_16x16x32_bf16 v[26:29], v[228:231], v[240:243], v[26:29]
	s_waitcnt vmcnt(7)
	ds_write_b128 v159, v[178:181] offset:16384
	v_mfma_f32_16x16x32_bf16 v[22:25], v[228:231], v[244:247], v[22:25]
	v_mfma_f32_16x16x32_bf16 v[18:21], v[228:231], v[248:251], v[18:21]
	s_waitcnt vmcnt(6)
	ds_write_b128 v159, v[182:185] offset:20480
	s_waitcnt lgkmcnt(6)
	v_mfma_f32_16x16x32_bf16 v[14:17], v[232:235], v[236:239], v[14:17]
	v_mfma_f32_16x16x32_bf16 v[10:13], v[232:235], v[240:243], v[10:13]
	v_mfma_f32_16x16x32_bf16 v[6:9], v[232:235], v[244:247], v[6:9]
	v_mfma_f32_16x16x32_bf16 v[2:5], v[232:235], v[248:251], v[2:5]
	s_setprio 0
	s_addk_i32 s3, 0x80
	s_mov_b32 s6, s7
	s_waitcnt lgkmcnt(0)
	s_barrier
	s_cbranch_vccnz .LBB0_578
	s_cmp_gt_i32 s2, 23
	s_cselect_b64 s[2:3], -1, 0
	s_cmpk_gt_u32 s71, 0xd7f
	s_mulk_i32 s5, 0xfc
	s_mul_i32 s6, s4, 0x41f4
	s_cselect_b64 s[8:9], -1, 0
	s_sub_i32 s72, s5, s6
	s_mul_i32 s6, s4, 0x1248000
	s_mul_hi_i32 s5, s4, 0x1248000
	s_add_u32 s14, s48, s6
	s_addc_u32 s15, s49, s5
	s_add_u32 s16, s50, s6
	s_addc_u32 s17, s51, s5
	s_mul_i32 s6, s4, 0x2080000
	s_mul_hi_i32 s5, s4, 0x2080000
	s_add_u32 s18, s52, s6
	s_addc_u32 s19, s53, s5
	s_mul_hi_i32 s5, s4, 0x6180000
	s_mul_i32 s4, s4, 0x6180000
	s_add_u32 s24, s69, s4
	s_addc_u32 s25, s70, s5
	s_mov_b32 s73, 0
	s_mov_b64 s[26:27], -1
	s_branch .LBB0_582

; __global__ void __launch_bounds__(256, 2) mega(Params P) {
;   __shared__ __attribute__((aligned(16))) char smem[69632];
;   const int p0 = P.p0, p1 = P.p1;
	.amdhsa_kernel _Z4mega6Params
		.amdhsa_group_segment_fixed_size 69632
		.amdhsa_private_segment_fixed_size 0
		.amdhsa_kernarg_size 560
		.amdhsa_user_sgpr_count 2
		.amdhsa_user_sgpr_dispatch_ptr 0
		.amdhsa_user_sgpr_queue_ptr 0
		.amdhsa_user_sgpr_kernarg_segment_ptr 1
		.amdhsa_user_sgpr_dispatch_id 0
		.amdhsa_user_sgpr_kernarg_preload_length 0
		.amdhsa_user_sgpr_kernarg_preload_offset 0
		.amdhsa_user_sgpr_private_segment_size 0
		.amdhsa_uses_dynamic_stack 0
		.amdhsa_enable_private_segment 0
		.amdhsa_system_sgpr_workgroup_id_x 1
		.amdhsa_system_sgpr_workgroup_id_y 0
		.amdhsa_system_sgpr_workgroup_id_z 0
		.amdhsa_system_sgpr_workgroup_info 0
		.amdhsa_system_vgpr_workitem_id 2
		.amdhsa_next_free_vgpr 254
		.amdhsa_next_free_sgpr 99
		.amdhsa_accum_offset 256
		.amdhsa_reserve_vcc 1
		.amdhsa_float_round_mode_32 0
		.amdhsa_float_round_mode_16_64 0
		.amdhsa_float_denorm_mode_32 3
		.amdhsa_float_denorm_mode_16_64 3
		.amdhsa_dx10_clamp 1
		.amdhsa_ieee_mode 1
		.amdhsa_fp16_overflow 0
		.amdhsa_tg_split 0
		.amdhsa_exception_fp_ieee_invalid_op 0
		.amdhsa_exception_fp_denorm_src 0
		.amdhsa_exception_fp_ieee_div_zero 0
		.amdhsa_exception_fp_ieee_overflow 0
		.amdhsa_exception_fp_ieee_underflow 0
		.amdhsa_exception_fp_ieee_inexact 0
		.amdhsa_exception_int_div_zero 0
	.end_amdhsa_kernel

; __global__ void __launch_bounds__(256, 2) mega(Params P) {
;   __shared__ __attribute__((aligned(16))) char smem[69632];
;   const int p0 = P.p0, p1 = P.p1;
amdhsa.kernels:
  - .agpr_count:     0
    .args:
      - .offset:         0
        .size:           304
        .value_kind:     by_value
      - .offset:         304
        .size:           4
        .value_kind:     hidden_block_count_x
      - .offset:         308
        .size:           4
        .value_kind:     hidden_block_count_y
      - .offset:         312
        .size:           4
        .value_kind:     hidden_block_count_z
      - .offset:         316
        .size:           2
        .value_kind:     hidden_group_size_x
      - .offset:         318
        .size:           2
        .value_kind:     hidden_group_size_y
      - .offset:         320
        .size:           2
        .value_kind:     hidden_group_size_z
      - .offset:         322
        .size:           2
        .value_kind:     hidden_remainder_x
      - .offset:         324
        .size:           2
        .value_kind:     hidden_remainder_y
      - .offset:         326
        .size:           2
        .value_kind:     hidden_remainder_z
      - .offset:         344
        .size:           8
        .value_kind:     hidden_global_offset_x
      - .offset:         352
        .size:           8
        .value_kind:     hidden_global_offset_y
      - .offset:         360
        .size:           8
        .value_kind:     hidden_global_offset_z
      - .offset:         368
        .size:           2
        .value_kind:     hidden_grid_dims
      - .offset:         392
        .size:           8
        .value_kind:     hidden_multigrid_sync_arg
    .group_segment_fixed_size: 69632
    .kernarg_segment_align: 8
    .kernarg_segment_size: 560
    .language:       OpenCL C
    .language_version:
      - 2
      - 0
    .max_flat_workgroup_size: 256
    .name:           _Z4mega6Params
    .private_segment_fixed_size: 0
    .sgpr_count:     105
    .sgpr_spill_count: 70
    .symbol:         _Z4mega6Params.kd
    .uniform_work_group_size: 1
    .uses_dynamic_stack: false
    .vgpr_count:     254
    .vgpr_spill_count: 0
    .wavefront_size: 64
